# scan sqrt peephole: dropped the placeholder s_nops outside MFMA hazard windows (hazard-checked), trans-consumer nops re-inserted
# speedup vs baseline: 1.0785x; 1.0000x over previous
; __device__ __forceinline__ void scan_phase(KP p, int l, LAS unsigned char* lds) {
;     ...
;     for (int task = gw; task < NTASK; task += NGW) {
;         const int head = task & 15, ck = task >> 4, hc0 = head * 64;
;         LDS_WAIT();
;         {
;             const int ch = hc0 + lane;
; #pragma unroll
;             for (int k = 0; k < 4; ++k) CST[k * 64 + lane] = p->in[14][(size_t)(l * 4 + k) * D + ch];
;             CST[4 * 64 + lane] = p->in[15][l * D + ch]; CST[5 * 64 + lane] = p->in[17][l * D + ch]; CST[6 * 64 + lane] = p->in[19][l * D + ch]; CST[7 * 64 + lane] = SP[ch];
;         }
;         bf16x8 Wa[4][2], Wx[4][2];
; #pragma unroll
;         for (int n = 0; n < 4; ++n)
; #pragma unroll
;             for (int s = 0; s < 2; ++s) { const size_t o = (size_t)head * 4096 + (16 * n + fr) * 64 + 32 * s + 8 * fq;
;                 Wa[n][s] = *(const bf16x8*)((const bf16_t*)(p->ws + WS_RGA) + o); Wx[n][s] = *(const bf16x8*)((const bf16_t*)(p->ws + WS_RGX) + o); }
;         if (ck < 128) {
;             const int b = ck >> 4, q = ck & 15, tile0 = b * 129 + 8 * q;
;             float Hc[4], Pc[4];
; #pragma unroll
;             for (int n = 0; n < 4; ++n) { Hc[n] = 0.f; Pc[n] = 1.f; }
;             for (int tt = 0; tt < 8; tt += 2) scan_tiles<2>(p, l, P, HLOC, PCUM, XC, CST, Wa, Wx, b, hc0, (tile0 + tt) * 16, lane, fr, fq, Hc, Pc);
;             if (q == 15) scan_tiles<1>(p, l, P, HLOC, PCUM, XC, CST, Wa, Wx, b, hc0, (tile0 + 8) * 16, lane, fr, fq, Hc, Pc);
;             if (fq == 0) {
; #pragma unroll
;                 for (int n = 0; n < 4; ++n) { const int ch = hc0 + 16 * n + fr; SUMM[(size_t)ck * 2 * D + ch] = Pc[n]; SUMM[(size_t)ck * 2 * D + D + ch] = Hc[n]; } }
;         } else {
;             const int m0 = (1032 + (ck - 128)) * 16;
;             LDS_WAIT();
;             {   const int rr = lane >> 2, cb = lane & 3, cl = cb * 16, m = m0 + rr, sb = m - MP;
;                 float xv[4][16];
;                 const float* st = p->in[3] + ((size_t)(l * MS + sb) * 3) * D + hc0 + cl;
; #pragma unroll
;                 for (int k = 0; k < 3; ++k)
; #pragma unroll
;                     for (int e = 0; e < 16; e += 4) { const f32x4 v = *(const f32x4*)(st + (size_t)k * D + e); xv[k][e] = v[0]; xv[k][e + 1] = v[1]; xv[k][e + 2] = v[2]; xv[k][e + 3] = v[3]; }
;                 const bf16_t* src = P + (size_t)m * DP + C_XR + hc0 + cl;
.LBB0_331:
	s_and_b32 s16, s54, 15
	s_waitcnt lgkmcnt(0)
	s_lshl_b32 s75, s16, 6
	s_load_dwordx4 s[12:15], s[58:59], 0x70
	s_load_dwordx2 s[10:11], s[58:59], 0x88
	s_load_dwordx2 s[18:19], s[58:59], 0x98
	s_waitcnt vmcnt(1)
	v_or_b32_e32 v6, s75, v205
	v_lshlrev_b32_e32 v0, 2, v6
	s_waitcnt vmcnt(0) lgkmcnt(0)
	v_lshl_add_u64 v[2:3], s[12:13], 0, v[0:1]
	v_lshl_add_u64 v[2:3], v[2:3], 0, s[68:69]
	v_add_co_u32_e32 v4, vcc, s43, v2
	global_load_dword v7, v[2:3], off
	s_nop 0
	v_addc_co_u32_e32 v5, vcc, 0, v3, vcc
	global_load_dword v8, v[4:5], off offset:-4096
	v_add_co_u32_e32 v2, vcc, s23, v2
	global_load_dword v4, v[4:5], off
	s_nop 0
	v_addc_co_u32_e32 v3, vcc, 0, v3, vcc
	global_load_dword v2, v[2:3], off
	v_mov_b32_e32 v3, v1
	s_ashr_i32 s74, s54, 4
	s_cmpk_gt_i32 s74, 0x7f
	v_add_u32_e32 v241, v232, v231
	s_waitcnt vmcnt(2)
	ds_write2st64_b32 v225, v7, v8 offset0:34 offset1:35
	s_waitcnt vmcnt(0)
	ds_write2st64_b32 v225, v4, v2 offset0:36 offset1:37
	v_or_b32_e32 v2, s77, v6
	v_lshlrev_b64 v[2:3], 2, v[2:3]
	v_lshl_add_u64 v[4:5], s[14:15], 0, v[2:3]
	global_load_dword v6, v[4:5], off
	v_lshl_add_u64 v[4:5], s[10:11], 0, v[2:3]
	global_load_dword v4, v[4:5], off
	v_lshl_add_u64 v[2:3], s[18:19], 0, v[2:3]
	s_mov_b64 s[10:11], -1
	s_waitcnt vmcnt(0)
	ds_write2st64_b32 v225, v6, v4 offset0:38 offset1:39
	global_load_dword v2, v[2:3], off
	s_nop 0
	global_load_dword v0, v0, s[66:67]
	s_waitcnt vmcnt(0)
	ds_write2st64_b32 v225, v2, v0 offset0:40 offset1:41
	v_lshl_or_b32 v0, s16, 13, v238
	v_or_b32_e32 v2, 64, v0
	global_load_dwordx4 v[34:37], v0, s[70:71]
	global_load_dwordx4 v[38:41], v0, s[72:73]
	global_load_dwordx4 v[10:13], v2, s[70:71]
	global_load_dwordx4 v[14:17], v2, s[72:73]
	v_or_b32_e32 v2, 0x800, v0
	global_load_dwordx4 v[42:45], v2, s[70:71]
	global_load_dwordx4 v[46:49], v2, s[72:73]
	v_or_b32_e32 v2, 0x840, v0
	global_load_dwordx4 v[22:25], v2, s[70:71]
	global_load_dwordx4 v[26:29], v2, s[72:73]
	v_or_b32_e32 v2, 0x1000, v0
	global_load_dwordx4 v[50:53], v2, s[70:71]
	global_load_dwordx4 v[54:57], v2, s[72:73]
	v_or_b32_e32 v2, 0x1040, v0
	global_load_dwordx4 v[30:33], v2, s[70:71]
	global_load_dwordx4 v[18:21], v2, s[72:73]
	v_or_b32_e32 v2, 0x1800, v0
	v_or_b32_e32 v0, 0x1840, v0
	global_load_dwordx4 v[62:65], v2, s[70:71]
	global_load_dwordx4 v[58:61], v2, s[72:73]
	global_load_dwordx4 v[6:9], v0, s[70:71]
	s_nop 0
	global_load_dwordx4 v[2:5], v0, s[72:73]
	v_lshlrev_b32_e32 v0, 1, v206
	s_cbranch_scc0 .LBB0_333
	s_waitcnt lgkmcnt(0)
	s_load_dwordx4 s[12:15], s[58:59], 0x18
	s_and_b32 s10, s54, -16
	s_add_i32 s11, s10, 0x3880
	v_or_b32_e32 v106, s11, v226
	v_add_u32_e32 v126, s78, v106
	s_waitcnt lgkmcnt(0)
	v_mov_b64_e32 v[66:67], s[12:13]
	v_mad_i64_i32 v[66:67], s[12:13], v126, s23, v[66:67]
	s_lshl_b32 s16, s75, 2
	v_lshl_add_u64 v[66:67], v[66:67], 0, s[16:17]
	v_lshlrev_b32_e32 v122, 2, v206
	v_mov_b32_e32 v123, v1
	v_lshl_add_u64 v[70:71], v[66:67], 0, v[122:123]
	v_add_co_u32_e32 v78, vcc, s43, v70
	v_lshl_add_u64 v[72:73], v[70:71], 0, s[28:29]
	s_nop 0
	v_addc_co_u32_e32 v79, vcc, 0, v71, vcc
	global_load_dwordx4 v[66:69], v[70:71], off offset:48
	global_load_dwordx4 v[82:85], v[70:71], off offset:32
	global_load_dwordx4 v[94:97], v[70:71], off offset:16
	global_load_dwordx4 v[110:113], v[70:71], off
	global_load_dwordx4 v[114:117], v[78:79], off offset:-4096
	global_load_dwordx4 v[74:77], v[72:73], off offset:48
	global_load_dwordx4 v[90:93], v[72:73], off offset:32
	global_load_dwordx4 v[102:105], v[72:73], off offset:16
	v_lshl_add_u64 v[80:81], v[70:71], 0, s[30:31]
	global_load_dwordx4 v[118:121], v[78:79], off
	global_load_dwordx4 v[70:73], v[80:81], off offset:48
	global_load_dwordx4 v[86:89], v[80:81], off offset:32
	global_load_dwordx4 v[98:101], v[80:81], off offset:16
	v_mov_b64_e32 v[78:79], s[60:61]
	v_mad_u64_u32 v[78:79], s[12:13], v106, s33, v[78:79]
	s_lshl_b32 s12, s75, 1
	s_mov_b32 s13, s17
	v_lshl_add_u64 v[78:79], v[78:79], 0, s[12:13]
	v_lshl_add_u64 v[78:79], v[78:79], 0, v[0:1]
	v_lshl_add_u64 v[80:81], v[78:79], 0, s[28:29]
	v_add_co_u32_e32 v78, vcc, s38, v78
	s_nop 1
	v_addc_co_u32_e32 v79, vcc, 0, v79, vcc
	global_load_dwordx4 v[106:109], v[78:79], off
	s_nop 0
	global_load_dwordx4 v[78:81], v[80:81], off offset:16
	s_load_dwordx2 s[12:13], s[58:59], 0xe0
	s_waitcnt lgkmcnt(0)
	v_mov_b64_e32 v[124:125], s[12:13]
	v_mad_i64_i32 v[124:125], s[18:19], v126, s23, v[124:125]
	v_lshl_add_u64 v[124:125], v[124:125], 0, s[16:17]
	v_lshl_add_u64 v[146:147], v[124:125], 0, v[122:123]
	s_mov_b32 s16, 0x45f1000
	v_add_co_u32_e32 v124, vcc, s16, v146
	s_mov_b64 s[18:19], 0x45f0000
	s_nop 0
	v_addc_co_u32_e32 v125, vcc, 0, v147, vcc
	v_lshl_add_u64 v[122:123], v[146:147], 0, s[18:19]
	s_mov_b32 s16, 0x45f2000
	s_mov_b64 s[18:19], 0x4bf0000
	s_waitcnt vmcnt(9)
	global_store_dwordx4 v[124:125], v[114:117], off offset:-4096
	s_waitcnt vmcnt(7)
	global_store_dwordx4 v[122:123], v[102:105], off offset:16
	global_store_dwordx4 v[122:123], v[90:93], off offset:32
	global_store_dwordx4 v[122:123], v[74:77], off offset:48
	s_waitcnt vmcnt(9)
	global_store_dwordx4 v[124:125], v[118:121], off
	s_waitcnt vmcnt(7)
	global_store_dwordx4 v[124:125], v[98:101], off offset:16
	global_store_dwordx4 v[124:125], v[86:89], off offset:32
	global_store_dwordx4 v[124:125], v[70:73], off offset:48
	ds_read_b128 v[122:125], v227 offset:8704
	ds_read_b128 v[126:129], v227 offset:8960
	ds_read_b128 v[130:133], v227 offset:9216
	ds_read_b128 v[134:137], v227 offset:9472
	ds_read_b128 v[138:141], v227 offset:9728
	s_waitcnt lgkmcnt(3)
; #define LAS __attribute__((address_space(3)))
; __device__ __forceinline__ unsigned cvt_pk_bf16(float lo, float hi) { unsigned r; asm volatile("v_cvt_pk_bf16_f32 %0, %1, %2" : "=v"(r) : "v"(lo), "v"(hi)); return r; }
; #define LDS_WAIT() asm volatile("s_waitcnt lgkmcnt(0)" ::: "memory")
; __device__ __forceinline__ void scan_phase(KP p, int l, LAS unsigned char* lds) {
;     ...
;                 for (int e = 0; e < 8; ++e) { xv[3][e] = f0[e]; xv[3][8 + e] = f1[e]; }
;                 float* o = p->out + O_SCB + ((size_t)(l * MS + sb) * 3) * D + hc0 + cl;
; #pragma unroll
;                 for (int k = 0; k < 3; ++k)
; #pragma unroll
;                     for (int e = 0; e < 16; e += 4) *(f32x4*)(o + (size_t)k * D + e) = (f32x4){xv[k + 1][e], xv[k + 1][e + 1], xv[k + 1][e + 2], xv[k + 1][e + 3]};
; #pragma unroll
;                 for (int e = 0; e < 16; e += 4) {
;                     const f32x4 w0 = *(const LAS f32x4*)(CST + 0 * 64 + cl + e), w1 = *(const LAS f32x4*)(CST + 1 * 64 + cl + e), w2 = *(const LAS f32x4*)(CST + 2 * 64 + cl + e),
;                                 w3 = *(const LAS f32x4*)(CST + 3 * 64 + cl + e), bb = *(const LAS f32x4*)(CST + 4 * 64 + cl + e);
;                     f32x4 r;
; #pragma unroll
;                     for (int q = 0; q < 4; ++q) r[q] = w0[q] * xv[0][e + q] + w1[q] * xv[1][e + q] + w2[q] * xv[2][e + q] + w3[q] * xv[3][e + q] + bb[q];
;                     *(LAS f32x4*)(XC + rr * 68 + cl + e) = r;
;                 }
;             }
;             LDS_WAIT();
;             f32x4 ar[4], ai[4];
; #pragma unroll
;             for (int n = 0; n < 4; ++n) { ar[n] = (f32x4){0.f, 0.f, 0.f, 0.f}; ai[n] = (f32x4){0.f, 0.f, 0.f, 0.f}; }
; #pragma unroll
;             for (int s = 0; s < 2; ++s) {
;                 const f32x4 x0 = *(const LAS f32x4*)(XC + fr * 68 + 32 * s + 8 * fq), x1 = *(const LAS f32x4*)(XC + fr * 68 + 32 * s + 8 * fq + 4);
;                 u32x4 aw; aw.x = cvt_pk_bf16(x0[0], x0[1]); aw.y = cvt_pk_bf16(x0[2], x0[3]); aw.z = cvt_pk_bf16(x1[0], x1[1]); aw.w = cvt_pk_bf16(x1[2], x1[3]);
;                 const bf16x8 af = __builtin_bit_cast(bf16x8, aw);
; #pragma unroll
;                 for (int n = 0; n < 4; ++n) { ar[n] = __builtin_amdgcn_mfma_f32_16x16x32_bf16(af, Wa[n][s], ar[n], 0, 0, 0); ai[n] = __builtin_amdgcn_mfma_f32_16x16x32_bf16(af, Wx[n][s], ai[n], 0, 0, 0); }
	v_pk_mul_f32 v[116:117], v[116:117], v[128:129]
	v_pk_mul_f32 v[114:115], v[114:115], v[126:127]
	v_pk_fma_f32 v[112:113], v[112:113], v[124:125], v[116:117]
	v_pk_fma_f32 v[110:111], v[110:111], v[122:123], v[114:115]
	s_waitcnt lgkmcnt(2)
	v_pk_fma_f32 v[112:113], v[120:121], v[132:133], v[112:113]
	v_pk_fma_f32 v[110:111], v[118:119], v[130:131], v[110:111]
	s_waitcnt vmcnt(9)
	v_lshlrev_b32_e32 v142, 16, v106
	v_and_b32_e32 v143, 0xffff0000, v106
	v_lshlrev_b32_e32 v144, 16, v107
	v_and_b32_e32 v145, 0xffff0000, v107
	v_add_co_u32_e32 v106, vcc, s16, v146
	s_waitcnt lgkmcnt(1)
	v_pk_fma_f32 v[112:113], v[136:137], v[144:145], v[112:113]
	v_pk_fma_f32 v[110:111], v[134:135], v[142:143], v[110:111]
	v_addc_co_u32_e32 v107, vcc, 0, v147, vcc
	s_waitcnt lgkmcnt(0)
	v_pk_add_f32 v[112:113], v[140:141], v[112:113]
	v_pk_add_f32 v[110:111], v[138:139], v[110:111]
	global_store_dwordx4 v[106:107], v[142:145], off
	ds_write_b128 v228, v[110:113]
	ds_read_b128 v[110:113], v227 offset:8720
	ds_read_b128 v[114:117], v227 offset:8976
	ds_read_b128 v[118:121], v227 offset:9232
	ds_read_b128 v[122:125], v227 offset:9488
	ds_read_b128 v[126:129], v227 offset:9744
	v_lshlrev_b32_e32 v130, 16, v108
	s_waitcnt lgkmcnt(3)
	v_pk_mul_f32 v[104:105], v[104:105], v[116:117]
	v_pk_mul_f32 v[102:103], v[102:103], v[114:115]
	v_pk_fma_f32 v[96:97], v[96:97], v[112:113], v[104:105]
	v_pk_fma_f32 v[94:95], v[94:95], v[110:111], v[102:103]
	v_and_b32_e32 v131, 0xffff0000, v108
	v_lshlrev_b32_e32 v132, 16, v109
	v_and_b32_e32 v133, 0xffff0000, v109
	s_waitcnt lgkmcnt(2)
	v_pk_fma_f32 v[96:97], v[100:101], v[120:121], v[96:97]
	v_pk_fma_f32 v[94:95], v[98:99], v[118:119], v[94:95]
	s_waitcnt lgkmcnt(1)
	v_pk_fma_f32 v[96:97], v[124:125], v[132:133], v[96:97]
	v_pk_fma_f32 v[94:95], v[122:123], v[130:131], v[94:95]
	s_waitcnt lgkmcnt(0)
	v_pk_add_f32 v[96:97], v[128:129], v[96:97]
	v_pk_add_f32 v[94:95], v[126:127], v[94:95]
	global_store_dwordx4 v[106:107], v[130:133], off offset:16
	ds_write_b128 v228, v[94:97] offset:16
	ds_read_b128 v[94:97], v227 offset:8736
	ds_read_b128 v[98:101], v227 offset:8992
	ds_read_b128 v[102:105], v227 offset:9248
	ds_read_b128 v[108:111], v227 offset:9504
	ds_read_b128 v[112:115], v227 offset:9760
	s_waitcnt vmcnt(10)
	v_lshlrev_b32_e32 v116, 16, v78
	v_and_b32_e32 v117, 0xffff0000, v78
	v_lshlrev_b32_e32 v118, 16, v79
	v_and_b32_e32 v119, 0xffff0000, v79
	s_waitcnt lgkmcnt(3)
	v_pk_mul_f32 v[78:79], v[92:93], v[100:101]
	v_pk_mul_f32 v[90:91], v[90:91], v[98:99]
	v_pk_fma_f32 v[78:79], v[84:85], v[96:97], v[78:79]
	v_pk_fma_f32 v[82:83], v[82:83], v[94:95], v[90:91]
	s_waitcnt lgkmcnt(2)
	v_pk_fma_f32 v[78:79], v[88:89], v[104:105], v[78:79]
	v_pk_fma_f32 v[82:83], v[86:87], v[102:103], v[82:83]
	s_waitcnt lgkmcnt(1)
	v_pk_fma_f32 v[78:79], v[110:111], v[118:119], v[78:79]
	v_pk_fma_f32 v[82:83], v[108:109], v[116:117], v[82:83]
	s_waitcnt lgkmcnt(0)
	v_pk_add_f32 v[84:85], v[114:115], v[78:79]
	v_pk_add_f32 v[82:83], v[112:113], v[82:83]
	global_store_dwordx4 v[106:107], v[116:119], off offset:32
	ds_write_b128 v228, v[82:85] offset:32
	ds_read_b128 v[82:85], v227 offset:8752
	ds_read_b128 v[86:89], v227 offset:9008
	ds_read_b128 v[90:93], v227 offset:9264
	ds_read_b128 v[94:97], v227 offset:9520
	ds_read_b128 v[98:101], v227 offset:9776
	v_lshlrev_b32_e32 v78, 16, v80
	s_waitcnt lgkmcnt(3)
	v_pk_mul_f32 v[76:77], v[76:77], v[88:89]
	v_pk_mul_f32 v[74:75], v[74:75], v[86:87]
	v_pk_fma_f32 v[68:69], v[68:69], v[84:85], v[76:77]
	v_pk_fma_f32 v[66:67], v[66:67], v[82:83], v[74:75]
	v_and_b32_e32 v79, 0xffff0000, v80
	v_lshlrev_b32_e32 v80, 16, v81
	v_and_b32_e32 v81, 0xffff0000, v81
	s_waitcnt lgkmcnt(2)
	v_pk_fma_f32 v[68:69], v[72:73], v[92:93], v[68:69]
	v_pk_fma_f32 v[66:67], v[70:71], v[90:91], v[66:67]
	s_waitcnt lgkmcnt(1)
	v_pk_fma_f32 v[68:69], v[96:97], v[80:81], v[68:69]
	v_pk_fma_f32 v[66:67], v[94:95], v[78:79], v[66:67]
	s_waitcnt lgkmcnt(0)
	v_pk_add_f32 v[68:69], v[100:101], v[68:69]
	v_pk_add_f32 v[66:67], v[98:99], v[66:67]
	global_store_dwordx4 v[106:107], v[78:81], off offset:48
	ds_write_b128 v228, v[66:69] offset:48
	s_waitcnt lgkmcnt(0)
	ds_read_b128 v[66:69], v239
	ds_read_b128 v[70:73], v239 offset:16
	s_waitcnt lgkmcnt(1)
	v_cvt_pk_bf16_f32 v66, v66, v67
	v_cvt_pk_bf16_f32 v67, v68, v69
	s_waitcnt lgkmcnt(0)
	v_cvt_pk_bf16_f32 v68, v70, v71
	v_cvt_pk_bf16_f32 v69, v72, v73
	ds_read_b128 v[86:89], v239 offset:128
	ds_read_b128 v[90:93], v239 offset:144
	v_mfma_f32_16x16x32_bf16 v[70:73], v[66:69], v[34:37], 0
	s_waitcnt lgkmcnt(1)
	v_cvt_pk_bf16_f32 v110, v86, v87
	v_cvt_pk_bf16_f32 v111, v88, v89
	s_waitcnt lgkmcnt(0)
	v_cvt_pk_bf16_f32 v112, v90, v91
	v_cvt_pk_bf16_f32 v113, v92, v93
	ds_read2st64_b32 v[120:121], v232 offset0:39 offset1:40
	ds_read_b32 v123, v232 offset:10496
	v_mfma_f32_16x16x32_bf16 v[94:97], v[110:113], v[10:13], v[70:73]
	v_or_b32_e32 v114, s11, v229
	v_or_b32_e32 v122, s75, v223
	v_lshlrev_b32_e32 v116, 2, v122
	v_mfma_f32_16x16x32_bf16 v[78:81], v[66:69], v[42:45], 0
	v_mov_b32_e32 v117, v1
	s_waitcnt lgkmcnt(1)
	s_nop 1
	v_add_f32_e32 v94, v94, v120
	v_mul_f32_e32 v94, 0xbfb8aa3b, v94
	v_exp_f32_e32 v94, v94
	v_mfma_f32_16x16x32_bf16 v[98:101], v[66:69], v[50:53], 0
	v_lshl_add_u64 v[118:119], s[14:15], 0, v[116:117]
	v_ashrrev_i32_e32 v115, 31, v114
	v_add_f32_e32 v94, 1.0, v94
	v_rcp_f32_e32 v94, v94
	v_mfma_f32_16x16x32_bf16 v[86:89], v[110:113], v[22:25], v[78:81]
	v_mul_f32_e32 v94, 0xc1000000, v94
	s_waitcnt lgkmcnt(0)
; __device__ __forceinline__ unsigned cvt_pk_bf16(float lo, float hi) { unsigned r; asm volatile("v_cvt_pk_bf16_f32 %0, %1, %2" : "=v"(r) : "v"(lo), "v"(hi)); return r; }
; __device__ __forceinline__ float sigmoidf_(float x) { return __builtin_amdgcn_rcpf(1.0f + __expf(-x)); }
; __device__ __forceinline__ void scan_phase(KP p, int l, LAS unsigned char* lds) {
;     ...
;                 for (int n = 0; n < 4; ++n) { ar[n] = __builtin_amdgcn_mfma_f32_16x16x32_bf16(af, Wa[n][s], ar[n], 0, 0, 0); ai[n] = __builtin_amdgcn_mfma_f32_16x16x32_bf16(af, Wx[n][s], ai[n], 0, 0, 0); }
;             }
; #pragma unroll
;             for (int n = 0; n < 4; ++n) {
;                 const int cc = 16 * n + fr, ch = hc0 + cc;
;                 const float ba = CST[5 * 64 + cc], bx = CST[6 * 64 + cc], sp = CST[7 * 64 + cc];
; #pragma unroll
;                 for (int j = 0; j < 4; ++j) {
;                     const float xc = XC[(4 * fq + j) * 68 + cc];
;                     const float r = sigmoidf_(ar[n][j] + ba), ig = sigmoidf_(ai[n][j] + bx);
;                     const float a = __expf(-8.0f * r * sp);
;                     const float mult = sqrtf(fmaxf(1.0f - a * a, 0.f));
;                     const int sb = m0 - MP + 4 * fq + j;
;                     const float h0 = p->in[4][(size_t)(l * MS + sb) * D + ch];
;                     const float h = a * h0 + mult * ig * xc;
;                     const size_t o = (size_t)(m0 + 4 * fq + j) * D + ch; HLOC[o] = (bf16_t)(cvt_pk_bf16(h, 0.f) & 0xffffu); PCUM[o] = 0;
;                     p->out[O_SRG + (size_t)(l * MS + sb) * D + ch] = h; }
	v_mul_f32_e32 v94, v123, v94
	v_mul_f32_e32 v94, 0x3fb8aa3b, v94
	v_exp_f32_e32 v94, v94
	v_mfma_f32_16x16x32_bf16 v[78:81], v[110:113], v[30:33], v[98:101]
	s_nop 2
	v_fma_f32 v98, -v94, v94, 1.0
	v_max_f32_e32 v98, 0, v98
	s_nop 0
	s_nop 0
	v_mfma_f32_16x16x32_bf16 v[74:77], v[66:69], v[38:41], 0
	ds_read_b32 v100, v241
	v_mfma_f32_16x16x32_bf16 v[102:105], v[66:69], v[54:57], 0
	s_nop 0
	v_mfma_f32_16x16x32_bf16 v[82:85], v[66:69], v[46:49], 0
	v_mfma_f32_16x16x32_bf16 v[106:109], v[66:69], v[62:65], 0
	v_mfma_f32_16x16x32_bf16 v[66:69], v[66:69], v[58:61], 0
	v_mfma_f32_16x16x32_bf16 v[90:93], v[110:113], v[14:17], v[74:77]
	v_mfma_f32_16x16x32_bf16 v[74:77], v[110:113], v[18:21], v[102:105]
	s_nop 2
	s_nop 0
	v_mfma_f32_16x16x32_bf16 v[82:85], v[110:113], v[26:29], v[82:85]
	s_nop 1
	v_add_f32_e32 v90, v90, v121
	v_mul_f32_e32 v90, 0xbfb8aa3b, v90
	v_exp_f32_e32 v90, v90
	v_mfma_f32_16x16x32_bf16 v[70:73], v[110:113], v[6:9], v[106:109]
	v_add_f32_e32 v91, v91, v121
	v_mul_f32_e32 v91, 0xbfb8aa3b, v91
	v_add_f32_e32 v90, 1.0, v90
	v_mfma_f32_16x16x32_bf16 v[66:69], v[110:113], v[2:5], v[66:69]
	v_add_u32_e32 v110, s10, v230
	v_ashrrev_i32_e32 v111, 31, v110
	v_lshlrev_b64 v[106:107], 12, v[110:111]
	v_rcp_f32_e32 v90, v90
	v_lshlrev_b64 v[102:103], 10, v[114:115]
	v_exp_f32_e32 v91, v91
	v_sqrt_f32_e32 v101, v98
	s_nop 0
	v_lshl_add_u64 v[98:99], v[118:119], 0, v[106:107]
	global_load_dword v98, v[98:99], off
	v_mul_f32_e32 v90, v90, v101
	s_waitcnt lgkmcnt(0)
	v_mul_f32_e32 v90, v100, v90
	v_mov_b32_e32 v99, v103
	v_add_f32_e32 v91, 1.0, v91
	v_add_f32_e32 v92, v92, v121
	v_mul_f32_e32 v92, 0xbfb8aa3b, v92
	v_exp_f32_e32 v92, v92
	v_add_f32_e32 v93, v93, v121
	v_mul_f32_e32 v93, 0xbfb8aa3b, v93
	v_exp_f32_e32 v93, v93
	v_add_f32_e32 v92, 1.0, v92
	v_rcp_f32_e32 v92, v92
	v_add_f32_e32 v93, 1.0, v93
	s_waitcnt vmcnt(0)
	v_fmac_f32_e32 v90, v98, v94
	v_or_b32_e32 v98, v102, v122
	v_lshlrev_b64 v[98:99], 1, v[98:99]
	v_lshl_add_u64 v[100:101], s[62:63], 0, v[98:99]
	v_lshl_add_u64 v[98:99], s[64:65], 0, v[98:99]
	v_cvt_pk_bf16_f32 v94, v90, v1
	global_store_short v[98:99], v1, off
	v_lshl_add_u64 v[98:99], s[12:13], 0, v[106:107]
	v_lshl_add_u64 v[98:99], v[98:99], 0, s[18:19]
	global_store_short v[100:101], v94, off
	v_lshl_add_u64 v[100:101], v[98:99], 0, v[116:117]
	global_store_dword v[100:101], v90, off
	v_add_f32_e32 v90, v95, v120
	v_mul_f32_e32 v90, 0xbfb8aa3b, v90
	v_exp_f32_e32 v90, v90
	v_rcp_f32_e32 v95, v91
	ds_read_b32 v94, v241 offset:272
	v_add_f32_e32 v90, 1.0, v90
	v_rcp_f32_e32 v90, v90
	s_nop 0
	v_mul_f32_e32 v90, 0xc1000000, v90
	v_mul_f32_e32 v90, v123, v90
	v_mul_f32_e32 v90, 0x3fb8aa3b, v90
	v_exp_f32_e32 v100, v90
	s_nop 0
	v_fma_f32 v90, -v100, v100, 1.0
	v_max_f32_e32 v90, 0, v90
	s_nop 0
	s_nop 0
	s_nop 0
	s_nop 1
	s_nop 1
	v_sqrt_f32_e32 v101, v90
	s_nop 0
	v_or_b32_e32 v90, 1, v110
	v_ashrrev_i32_e32 v91, 31, v90
	v_lshlrev_b64 v[112:113], 12, v[90:91]
	v_lshl_add_u64 v[90:91], v[118:119], 0, v[112:113]
	global_load_dword v90, v[90:91], off
	v_mul_f32_e32 v91, v95, v101
	s_waitcnt lgkmcnt(0)
	v_mul_f32_e32 v104, v94, v91
	s_waitcnt vmcnt(0)
	v_fmac_f32_e32 v104, v100, v90
	v_or_b32_e32 v90, 1, v114
	v_ashrrev_i32_e32 v91, 31, v90
	v_lshlrev_b64 v[100:101], 10, v[90:91]
	v_or_b32_e32 v90, v100, v122
	v_mov_b32_e32 v91, v101
	v_lshlrev_b64 v[90:91], 1, v[90:91]
	v_lshl_add_u64 v[94:95], s[62:63], 0, v[90:91]
	v_lshl_add_u64 v[90:91], s[64:65], 0, v[90:91]
	v_cvt_pk_bf16_f32 v105, v104, v1
	global_store_short v[90:91], v1, off
	v_lshl_add_u64 v[90:91], s[12:13], 0, v[112:113]
	v_lshl_add_u64 v[90:91], v[90:91], 0, s[18:19]
	global_store_short v[94:95], v105, off
	v_lshl_add_u64 v[94:95], v[90:91], 0, v[116:117]
	global_store_dword v[94:95], v104, off
	v_add_f32_e32 v94, v96, v120
	v_mul_f32_e32 v94, 0xbfb8aa3b, v94
	v_exp_f32_e32 v94, v94
	ds_read_b32 v104, v241 offset:544
	v_add_f32_e32 v94, 1.0, v94
	v_rcp_f32_e32 v94, v94
	s_nop 0
	v_mul_f32_e32 v94, 0xc1000000, v94
	v_mul_f32_e32 v94, v123, v94
	v_mul_f32_e32 v94, 0x3fb8aa3b, v94
	v_exp_f32_e32 v96, v94
	s_nop 0
	v_fma_f32 v94, -v96, v96, 1.0
	v_max_f32_e32 v94, 0, v94
	s_nop 0
	s_nop 0
	s_nop 0
	s_nop 1
	s_nop 1
	v_sqrt_f32_e32 v105, v94
	s_nop 0
	v_or_b32_e32 v94, 2, v110
	v_ashrrev_i32_e32 v95, 31, v94
	v_lshlrev_b64 v[108:109], 12, v[94:95]
	v_lshl_add_u64 v[94:95], v[118:119], 0, v[108:109]
	global_load_dword v94, v[94:95], off
	v_mul_f32_e32 v92, v92, v105
	s_waitcnt vmcnt(0)
	v_mul_f32_e32 v96, v96, v94
	v_or_b32_e32 v94, 2, v114
	v_ashrrev_i32_e32 v95, 31, v94
	s_waitcnt lgkmcnt(0)
	v_fmac_f32_e32 v96, v92, v104
	v_lshlrev_b64 v[104:105], 10, v[94:95]
	v_or_b32_e32 v94, v104, v122
	v_mov_b32_e32 v95, v105
	v_lshlrev_b64 v[94:95], 1, v[94:95]
	v_cvt_pk_bf16_f32 v92, v96, v1
	v_lshl_add_u64 v[124:125], s[62:63], 0, v[94:95]
	global_store_short v[124:125], v92, off
	v_add_f32_e32 v92, v97, v120
	v_mul_f32_e32 v92, 0xbfb8aa3b, v92
	v_exp_f32_e32 v92, v92
	v_rcp_f32_e32 v97, v93
	v_lshl_add_u64 v[94:95], s[64:65], 0, v[94:95]
	global_store_short v[94:95], v1, off
	v_add_f32_e32 v92, 1.0, v92
	v_rcp_f32_e32 v92, v92
	v_lshl_add_u64 v[94:95], s[12:13], 0, v[108:109]
	v_lshl_add_u64 v[94:95], v[94:95], 0, s[18:19]
	v_lshl_add_u64 v[124:125], v[94:95], 0, v[116:117]
	v_mul_f32_e32 v92, 0xc1000000, v92
	v_mul_f32_e32 v92, v123, v92
	v_mul_f32_e32 v92, 0x3fb8aa3b, v92
	v_exp_f32_e32 v115, v92
	global_store_dword v[124:125], v96, off
	ds_read_b32 v96, v241 offset:816
	v_fma_f32 v92, -v115, v115, 1.0
	v_max_f32_e32 v92, 0, v92
	s_nop 0
	s_nop 0
	s_nop 0
	s_nop 1
	s_nop 1
	v_sqrt_f32_e32 v120, v92
	s_nop 0
	v_or_b32_e32 v92, 3, v110
	v_ashrrev_i32_e32 v93, 31, v92
	v_lshlrev_b64 v[110:111], 12, v[92:93]
	v_lshl_add_u64 v[92:93], v[118:119], 0, v[110:111]
	global_load_dword v92, v[92:93], off
	s_waitcnt vmcnt(0)
; __device__ __forceinline__ unsigned cvt_pk_bf16(float lo, float hi) { unsigned r; asm volatile("v_cvt_pk_bf16_f32 %0, %1, %2" : "=v"(r) : "v"(lo), "v"(hi)); return r; }
; __device__ __forceinline__ float sigmoidf_(float x) { return __builtin_amdgcn_rcpf(1.0f + __expf(-x)); }
; __device__ __forceinline__ void scan_phase(KP p, int l, LAS unsigned char* lds) {
;     ...
;             for (int n = 0; n < 4; ++n) {
;                 const int cc = 16 * n + fr, ch = hc0 + cc;
;                 const float ba = CST[5 * 64 + cc], bx = CST[6 * 64 + cc], sp = CST[7 * 64 + cc];
; #pragma unroll
;                 for (int j = 0; j < 4; ++j) {
;                     const float xc = XC[(4 * fq + j) * 68 + cc];
;                     const float r = sigmoidf_(ar[n][j] + ba), ig = sigmoidf_(ai[n][j] + bx);
;                     const float a = __expf(-8.0f * r * sp);
;                     const float mult = sqrtf(fmaxf(1.0f - a * a, 0.f));
;                     const int sb = m0 - MP + 4 * fq + j;
;                     const float h0 = p->in[4][(size_t)(l * MS + sb) * D + ch];
;                     const float h = a * h0 + mult * ig * xc;
;                     const size_t o = (size_t)(m0 + 4 * fq + j) * D + ch; HLOC[o] = (bf16_t)(cvt_pk_bf16(h, 0.f) & 0xffffu); PCUM[o] = 0;
;                     p->out[O_SRG + (size_t)(l * MS + sb) * D + ch] = h; }
	v_mul_f32_e32 v118, v115, v92
	v_mul_f32_e32 v92, v97, v120
	s_waitcnt lgkmcnt(0)
	v_fmac_f32_e32 v118, v92, v96
	v_or_b32_e32 v92, 3, v114
	v_ashrrev_i32_e32 v93, 31, v92
	v_lshlrev_b64 v[96:97], 10, v[92:93]
	v_or_b32_e32 v92, v96, v122
	v_mov_b32_e32 v93, v97
	v_lshlrev_b64 v[92:93], 1, v[92:93]
	v_lshl_add_u64 v[114:115], s[62:63], 0, v[92:93]
	v_lshl_add_u64 v[92:93], s[64:65], 0, v[92:93]
	v_cvt_pk_bf16_f32 v119, v118, v1
	global_store_short v[92:93], v1, off
	v_lshl_add_u64 v[92:93], s[12:13], 0, v[110:111]
	v_lshl_add_u64 v[92:93], v[92:93], 0, s[18:19]
	global_store_short v[114:115], v119, off
	v_lshl_add_u64 v[114:115], v[92:93], 0, v[116:117]
	global_store_dword v[114:115], v118, off
	v_add_u32_e32 v114, 64, v232
	ds_read2st64_b32 v[118:119], v114 offset0:39 offset1:40
	ds_read_b32 v121, v232 offset:10560
	v_add_lshl_u32 v114, s75, v223, 2
	v_mov_b32_e32 v115, v1
	v_lshl_add_u64 v[114:115], s[14:15], 0, v[114:115]
	s_waitcnt lgkmcnt(1)
	v_add_f32_e32 v86, v86, v118
	v_mul_f32_e32 v86, 0xbfb8aa3b, v86
	v_exp_f32_e32 v86, v86
	v_lshl_add_u64 v[106:107], v[114:115], 0, v[106:107]
	v_add_f32_e32 v82, v82, v119
	v_mul_f32_e32 v82, 0xbfb8aa3b, v82
	v_add_f32_e32 v86, 1.0, v86
	v_rcp_f32_e32 v86, v86
	v_exp_f32_e32 v82, v82
	ds_read_b32 v116, v241 offset:64
	v_or_b32_e32 v120, s75, v233
	v_mul_f32_e32 v86, 0xc1000000, v86
	s_waitcnt lgkmcnt(1)
	v_mul_f32_e32 v86, v121, v86
	v_mul_f32_e32 v86, 0x3fb8aa3b, v86
	v_exp_f32_e32 v86, v86
	v_add_f32_e32 v82, 1.0, v82
	v_rcp_f32_e32 v82, v82
	v_add_f32_e32 v83, v83, v119
	v_fma_f32 v117, -v86, v86, 1.0
	v_max_f32_e32 v117, 0, v117
	v_mul_f32_e32 v83, 0xbfb8aa3b, v83
	v_exp_f32_e32 v83, v83
	v_add_f32_e32 v84, v84, v119
	v_mul_f32_e32 v84, 0xbfb8aa3b, v84
	v_add_f32_e32 v83, 1.0, v83
	v_exp_f32_e32 v84, v84
	v_add_f32_e32 v85, v85, v119
	v_add_f32_e32 v84, 1.0, v84
	v_rcp_f32_e32 v84, v84
	v_sqrt_f32_e32 v117, v117
	s_nop 0
	global_load_dword v122, v[106:107], off offset:64
	v_mul_f32_e32 v82, v82, v117
	s_waitcnt lgkmcnt(0)
	v_mul_f32_e32 v82, v116, v82
	v_or_b32_e32 v116, v102, v120
	v_mov_b32_e32 v117, v103
	v_lshlrev_b64 v[116:117], 1, v[116:117]
	v_mul_f32_e32 v85, 0xbfb8aa3b, v85
	v_exp_f32_e32 v85, v85
	s_waitcnt vmcnt(0)
	v_fmac_f32_e32 v82, v122, v86
	v_lshl_add_u64 v[122:123], s[62:63], 0, v[116:117]
	v_lshl_add_u64 v[116:117], s[64:65], 0, v[116:117]
	v_cvt_pk_bf16_f32 v86, v82, v1
	global_store_short v[116:117], v1, off
	v_lshlrev_b32_e32 v116, 2, v120
	v_mov_b32_e32 v117, v1
	global_store_short v[122:123], v86, off
	v_lshl_add_u64 v[122:123], v[98:99], 0, v[116:117]
	global_store_dword v[122:123], v82, off
	v_add_f32_e32 v82, v87, v118
	v_mul_f32_e32 v82, 0xbfb8aa3b, v82
	v_exp_f32_e32 v82, v82
	v_rcp_f32_e32 v87, v83
	ds_read_b32 v86, v241 offset:336
	v_add_f32_e32 v85, 1.0, v85
	v_add_f32_e32 v82, 1.0, v82
	v_rcp_f32_e32 v82, v82
	s_nop 0
	v_mul_f32_e32 v82, 0xc1000000, v82
	v_mul_f32_e32 v82, v121, v82
	v_mul_f32_e32 v82, 0x3fb8aa3b, v82
	v_exp_f32_e32 v122, v82
	s_nop 0
	v_fma_f32 v82, -v122, v122, 1.0
	v_max_f32_e32 v82, 0, v82
	s_nop 0
	s_nop 0
	s_nop 0
	s_nop 1
	s_nop 1
	v_sqrt_f32_e32 v123, v82
	s_nop 0
	v_lshl_add_u64 v[82:83], v[114:115], 0, v[112:113]
	global_load_dword v112, v[82:83], off offset:64
	v_mul_f32_e32 v87, v87, v123
	s_waitcnt lgkmcnt(0)
	v_mul_f32_e32 v123, v86, v87
	v_or_b32_e32 v86, v100, v120
	v_mov_b32_e32 v87, v101
	v_lshlrev_b64 v[86:87], 1, v[86:87]
	s_waitcnt vmcnt(0)
	v_fmac_f32_e32 v123, v122, v112
	v_lshl_add_u64 v[112:113], s[62:63], 0, v[86:87]
	v_lshl_add_u64 v[86:87], s[64:65], 0, v[86:87]
	v_cvt_pk_bf16_f32 v122, v123, v1
	global_store_short v[86:87], v1, off
	v_lshl_add_u64 v[86:87], v[90:91], 0, v[116:117]
	global_store_dword v[86:87], v123, off
	v_add_f32_e32 v86, v88, v118
	v_mul_f32_e32 v86, 0xbfb8aa3b, v86
	v_exp_f32_e32 v86, v86
	global_store_short v[112:113], v122, off
	ds_read_b32 v112, v241 offset:608
	v_add_f32_e32 v86, 1.0, v86
	v_rcp_f32_e32 v86, v86
	s_nop 0
	v_mul_f32_e32 v86, 0xc1000000, v86
	v_mul_f32_e32 v86, v121, v86
	v_mul_f32_e32 v86, 0x3fb8aa3b, v86
	v_exp_f32_e32 v88, v86
	s_nop 0
	v_fma_f32 v86, -v88, v88, 1.0
	v_max_f32_e32 v86, 0, v86
	s_nop 0
	s_nop 0
	s_nop 0
	s_nop 1
	s_nop 1
	v_sqrt_f32_e32 v113, v86
	s_nop 0
	v_lshl_add_u64 v[86:87], v[114:115], 0, v[108:109]
	global_load_dword v108, v[86:87], off offset:64
	v_mov_b32_e32 v109, v105
	v_mul_f32_e32 v84, v84, v113
	s_waitcnt vmcnt(0)
	v_mul_f32_e32 v88, v88, v108
	v_or_b32_e32 v108, v104, v120
	v_lshlrev_b64 v[108:109], 1, v[108:109]
	s_waitcnt lgkmcnt(0)
	v_fmac_f32_e32 v88, v84, v112
	v_cvt_pk_bf16_f32 v84, v88, v1
	v_lshl_add_u64 v[112:113], s[62:63], 0, v[108:109]
	global_store_short v[112:113], v84, off
	v_add_f32_e32 v84, v89, v118
	v_mul_f32_e32 v84, 0xbfb8aa3b, v84
	v_exp_f32_e32 v84, v84
	v_lshl_add_u64 v[108:109], s[64:65], 0, v[108:109]
	global_store_short v[108:109], v1, off
	v_lshl_add_u64 v[108:109], v[94:95], 0, v[116:117]
	v_add_f32_e32 v84, 1.0, v84
	v_rcp_f32_e32 v84, v84
	global_store_dword v[108:109], v88, off
	v_rcp_f32_e32 v89, v85
	ds_read_b32 v88, v241 offset:880
	v_mul_f32_e32 v84, 0xc1000000, v84
	v_mul_f32_e32 v84, v121, v84
	v_mul_f32_e32 v84, 0x3fb8aa3b, v84
	v_exp_f32_e32 v108, v84
	s_nop 0
	v_fma_f32 v84, -v108, v108, 1.0
	v_max_f32_e32 v84, 0, v84
	s_nop 0
	s_nop 0
	s_nop 0
	s_nop 1
	s_nop 1
	v_sqrt_f32_e32 v109, v84
	s_nop 0
	v_lshl_add_u64 v[84:85], v[114:115], 0, v[110:111]
	global_load_dword v110, v[84:85], off offset:64
	v_mul_f32_e32 v89, v89, v109
	s_waitcnt vmcnt(0)
	v_mul_f32_e32 v110, v108, v110
	s_waitcnt lgkmcnt(0)
; __device__ __forceinline__ unsigned cvt_pk_bf16(float lo, float hi) { unsigned r; asm volatile("v_cvt_pk_bf16_f32 %0, %1, %2" : "=v"(r) : "v"(lo), "v"(hi)); return r; }
; __device__ __forceinline__ float sigmoidf_(float x) { return __builtin_amdgcn_rcpf(1.0f + __expf(-x)); }
; __device__ __forceinline__ void scan_phase(KP p, int l, LAS unsigned char* lds) {
;     ...
;             for (int n = 0; n < 4; ++n) {
;                 const int cc = 16 * n + fr, ch = hc0 + cc;
;                 const float ba = CST[5 * 64 + cc], bx = CST[6 * 64 + cc], sp = CST[7 * 64 + cc];
; #pragma unroll
;                 for (int j = 0; j < 4; ++j) {
;                     const float xc = XC[(4 * fq + j) * 68 + cc];
;                     const float r = sigmoidf_(ar[n][j] + ba), ig = sigmoidf_(ai[n][j] + bx);
;                     const float a = __expf(-8.0f * r * sp);
;                     const float mult = sqrtf(fmaxf(1.0f - a * a, 0.f));
;                     const int sb = m0 - MP + 4 * fq + j;
;                     const float h0 = p->in[4][(size_t)(l * MS + sb) * D + ch];
;                     const float h = a * h0 + mult * ig * xc;
;                     const size_t o = (size_t)(m0 + 4 * fq + j) * D + ch; HLOC[o] = (bf16_t)(cvt_pk_bf16(h, 0.f) & 0xffffu); PCUM[o] = 0;
;                     p->out[O_SRG + (size_t)(l * MS + sb) * D + ch] = h; }
	v_fmac_f32_e32 v110, v89, v88
	v_or_b32_e32 v88, v96, v120
	v_mov_b32_e32 v89, v97
	v_lshlrev_b64 v[88:89], 1, v[88:89]
	v_lshl_add_u64 v[108:109], s[62:63], 0, v[88:89]
	v_lshl_add_u64 v[88:89], s[64:65], 0, v[88:89]
	v_cvt_pk_bf16_f32 v111, v110, v1
	global_store_short v[88:89], v1, off
	v_lshl_add_u64 v[88:89], v[92:93], 0, v[116:117]
	global_store_short v[108:109], v111, off
	global_store_dword v[88:89], v110, off
	v_add_u32_e32 v88, 0x80, v232
	ds_read2st64_b32 v[108:109], v88 offset0:39 offset1:40
	ds_read_b32 v111, v232 offset:10624
	ds_read_b32 v88, v241 offset:128
	v_or_b32_e32 v110, s75, v234
	s_waitcnt lgkmcnt(2)
	v_add_f32_e32 v78, v78, v108
	v_mul_f32_e32 v78, 0xbfb8aa3b, v78
	v_exp_f32_e32 v78, v78
	v_add_f32_e32 v74, v74, v109
	v_mul_f32_e32 v74, 0xbfb8aa3b, v74
	v_exp_f32_e32 v74, v74
	v_add_f32_e32 v78, 1.0, v78
	v_rcp_f32_e32 v78, v78
	v_add_f32_e32 v75, v75, v109
	v_add_f32_e32 v74, 1.0, v74
	v_rcp_f32_e32 v74, v74
	v_mul_f32_e32 v78, 0xc1000000, v78
	s_waitcnt lgkmcnt(1)
	v_mul_f32_e32 v78, v111, v78
	v_mul_f32_e32 v78, 0x3fb8aa3b, v78
	v_exp_f32_e32 v78, v78
	v_mul_f32_e32 v75, 0xbfb8aa3b, v75
	v_exp_f32_e32 v75, v75
	v_add_f32_e32 v76, v76, v109
	v_fma_f32 v89, -v78, v78, 1.0
	v_max_f32_e32 v89, 0, v89
	v_add_f32_e32 v75, 1.0, v75
	v_rcp_f32_e32 v75, v75
	v_mul_f32_e32 v76, 0xbfb8aa3b, v76
	v_exp_f32_e32 v76, v76
	s_nop 0
	v_add_f32_e32 v76, 1.0, v76
	v_rcp_f32_e32 v76, v76
	s_nop 0
	s_nop 1
	v_sqrt_f32_e32 v89, v89
	s_nop 0
	global_load_dword v112, v[106:107], off offset:128
	v_mul_f32_e32 v74, v74, v89
	s_waitcnt lgkmcnt(0)
	v_mul_f32_e32 v74, v88, v74
	v_or_b32_e32 v88, v102, v110
	v_mov_b32_e32 v89, v103
	v_lshlrev_b64 v[88:89], 1, v[88:89]
	s_waitcnt vmcnt(0)
	v_fmac_f32_e32 v74, v112, v78
	v_cvt_pk_bf16_f32 v78, v74, v1
	v_lshl_add_u64 v[112:113], s[62:63], 0, v[88:89]
	global_store_short v[112:113], v78, off
	v_add_f32_e32 v78, v79, v108
	v_mul_f32_e32 v78, 0xbfb8aa3b, v78
	v_exp_f32_e32 v78, v78
	v_lshl_add_u64 v[88:89], s[64:65], 0, v[88:89]
	global_store_short v[88:89], v1, off
	v_lshlrev_b32_e32 v88, 2, v110
	v_add_f32_e32 v78, 1.0, v78
	v_rcp_f32_e32 v78, v78
	v_mov_b32_e32 v89, v1
	v_lshl_add_u64 v[112:113], v[98:99], 0, v[88:89]
	global_store_dword v[112:113], v74, off
	v_mul_f32_e32 v78, 0xc1000000, v78
	v_mul_f32_e32 v78, v111, v78
	v_mul_f32_e32 v78, 0x3fb8aa3b, v78
	v_exp_f32_e32 v78, v78
	ds_read_b32 v74, v241 offset:400
	v_fma_f32 v79, -v78, v78, 1.0
	v_max_f32_e32 v79, 0, v79
	s_nop 0
	s_nop 0
	s_nop 0
	s_nop 1
	s_nop 1
	v_sqrt_f32_e32 v79, v79
	s_nop 0
	global_load_dword v112, v[82:83], off offset:128
	v_mul_f32_e32 v75, v75, v79
	s_waitcnt lgkmcnt(0)
	v_mul_f32_e32 v113, v74, v75
	v_or_b32_e32 v74, v100, v110
	v_mov_b32_e32 v75, v101
	v_lshlrev_b64 v[74:75], 1, v[74:75]
	s_waitcnt vmcnt(0)
	v_fmac_f32_e32 v113, v78, v112
	v_lshl_add_u64 v[78:79], s[62:63], 0, v[74:75]
	v_lshl_add_u64 v[74:75], s[64:65], 0, v[74:75]
	v_cvt_pk_bf16_f32 v112, v113, v1
	global_store_short v[74:75], v1, off
	v_lshl_add_u64 v[74:75], v[90:91], 0, v[88:89]
	global_store_dword v[74:75], v113, off
	v_add_f32_e32 v75, v80, v108
	v_mul_f32_e32 v75, 0xbfb8aa3b, v75
	v_exp_f32_e32 v75, v75
	global_store_short v[78:79], v112, off
	ds_read_b32 v74, v241 offset:672
	v_add_f32_e32 v75, 1.0, v75
	v_rcp_f32_e32 v75, v75
	s_nop 0
	v_mul_f32_e32 v75, 0xc1000000, v75
	v_mul_f32_e32 v75, v111, v75
	v_mul_f32_e32 v75, 0x3fb8aa3b, v75
	v_exp_f32_e32 v75, v75
	s_nop 0
	v_fma_f32 v78, -v75, v75, 1.0
	v_max_f32_e32 v78, 0, v78
	s_nop 0
	s_nop 0
	s_nop 0
	s_nop 1
	s_nop 1
	v_sqrt_f32_e32 v78, v78
	s_nop 0
	global_load_dword v79, v[86:87], off offset:128
	s_waitcnt vmcnt(0)
	v_mul_f32_e32 v80, v75, v79
	v_mul_f32_e32 v75, v76, v78
	s_waitcnt lgkmcnt(0)
	v_fmac_f32_e32 v80, v75, v74
	v_or_b32_e32 v74, v104, v110
	v_mov_b32_e32 v75, v105
	v_lshlrev_b64 v[74:75], 1, v[74:75]
	v_lshl_add_u64 v[78:79], s[62:63], 0, v[74:75]
	v_lshl_add_u64 v[74:75], s[64:65], 0, v[74:75]
	v_cvt_pk_bf16_f32 v76, v80, v1
	global_store_short v[74:75], v1, off
	v_lshl_add_u64 v[74:75], v[94:95], 0, v[88:89]
	global_store_dword v[74:75], v80, off
	v_add_f32_e32 v75, v81, v108
	v_mul_f32_e32 v75, 0xbfb8aa3b, v75
	v_exp_f32_e32 v75, v75
	global_store_short v[78:79], v76, off
	v_add_f32_e32 v76, v77, v109
	v_mul_f32_e32 v76, 0xbfb8aa3b, v76
	v_add_f32_e32 v75, 1.0, v75
	v_rcp_f32_e32 v75, v75
	v_exp_f32_e32 v76, v76
	ds_read_b32 v74, v241 offset:944
	v_mul_f32_e32 v75, 0xc1000000, v75
	v_mul_f32_e32 v75, v111, v75
	v_mul_f32_e32 v75, 0x3fb8aa3b, v75
	v_exp_f32_e32 v75, v75
	v_add_f32_e32 v76, 1.0, v76
	v_rcp_f32_e32 v76, v76
	v_fma_f32 v77, -v75, v75, 1.0
	v_max_f32_e32 v77, 0, v77
	s_nop 0
	s_nop 0
	s_nop 0
	s_nop 1
	s_nop 1
	v_sqrt_f32_e32 v77, v77
	s_nop 0
	global_load_dword v78, v[84:85], off offset:128
	s_waitcnt vmcnt(0)
	v_mul_f32_e32 v78, v75, v78
	v_mul_f32_e32 v75, v76, v77
	s_waitcnt lgkmcnt(0)
; __device__ __forceinline__ unsigned cvt_pk_bf16(float lo, float hi) { unsigned r; asm volatile("v_cvt_pk_bf16_f32 %0, %1, %2" : "=v"(r) : "v"(lo), "v"(hi)); return r; }
; __device__ __forceinline__ float sigmoidf_(float x) { return __builtin_amdgcn_rcpf(1.0f + __expf(-x)); }
; __device__ __forceinline__ void scan_phase(KP p, int l, LAS unsigned char* lds) {
;     ...
;             for (int n = 0; n < 4; ++n) {
;                 const int cc = 16 * n + fr, ch = hc0 + cc;
;                 const float ba = CST[5 * 64 + cc], bx = CST[6 * 64 + cc], sp = CST[7 * 64 + cc];
; #pragma unroll
;                 for (int j = 0; j < 4; ++j) {
;                     const float xc = XC[(4 * fq + j) * 68 + cc];
;                     const float r = sigmoidf_(ar[n][j] + ba), ig = sigmoidf_(ai[n][j] + bx);
;                     const float a = __expf(-8.0f * r * sp);
;                     const float mult = sqrtf(fmaxf(1.0f - a * a, 0.f));
;                     const int sb = m0 - MP + 4 * fq + j;
;                     const float h0 = p->in[4][(size_t)(l * MS + sb) * D + ch];
;                     const float h = a * h0 + mult * ig * xc;
;                     const size_t o = (size_t)(m0 + 4 * fq + j) * D + ch; HLOC[o] = (bf16_t)(cvt_pk_bf16(h, 0.f) & 0xffffu); PCUM[o] = 0;
;                     p->out[O_SRG + (size_t)(l * MS + sb) * D + ch] = h; }
	v_fmac_f32_e32 v78, v75, v74
	v_or_b32_e32 v74, v96, v110
	v_mov_b32_e32 v75, v97
	v_lshlrev_b64 v[74:75], 1, v[74:75]
	v_lshl_add_u64 v[76:77], s[62:63], 0, v[74:75]
	v_lshl_add_u64 v[74:75], s[64:65], 0, v[74:75]
	v_cvt_pk_bf16_f32 v79, v78, v1
	global_store_short v[74:75], v1, off
	v_lshl_add_u64 v[74:75], v[92:93], 0, v[88:89]
	global_store_short v[76:77], v79, off
	global_store_dword v[74:75], v78, off
	v_add_u32_e32 v74, 0xc0, v232
	ds_read2st64_b32 v[76:77], v74 offset0:39 offset1:40
	ds_read_b32 v79, v232 offset:10688
	ds_read_b32 v74, v241 offset:192
	v_or_b32_e32 v78, s75, v235
	v_or_b32_e32 v102, v102, v78
	s_waitcnt lgkmcnt(2)
	v_add_f32_e32 v70, v70, v76
	v_mul_f32_e32 v70, 0xbfb8aa3b, v70
	v_exp_f32_e32 v70, v70
	v_add_f32_e32 v66, v66, v77
	v_mul_f32_e32 v66, 0xbfb8aa3b, v66
	v_exp_f32_e32 v66, v66
	v_add_f32_e32 v70, 1.0, v70
	v_rcp_f32_e32 v70, v70
	v_add_f32_e32 v67, v67, v77
	v_add_f32_e32 v66, 1.0, v66
	v_rcp_f32_e32 v66, v66
	v_mul_f32_e32 v70, 0xc1000000, v70
	s_waitcnt lgkmcnt(1)
	v_mul_f32_e32 v70, v79, v70
	v_mul_f32_e32 v70, 0x3fb8aa3b, v70
	v_exp_f32_e32 v70, v70
	v_mul_f32_e32 v67, 0xbfb8aa3b, v67
	v_exp_f32_e32 v67, v67
	v_or_b32_e32 v100, v100, v78
	v_fma_f32 v75, -v70, v70, 1.0
	v_max_f32_e32 v75, 0, v75
	v_add_f32_e32 v67, 1.0, v67
	v_rcp_f32_e32 v67, v67
	v_add_f32_e32 v68, v68, v77
	v_mul_f32_e32 v68, 0xbfb8aa3b, v68
	v_exp_f32_e32 v68, v68
	s_nop 0
	v_add_f32_e32 v68, 1.0, v68
	v_rcp_f32_e32 v68, v68
	v_or_b32_e32 v104, v104, v78
	v_or_b32_e32 v96, v96, v78
	v_sqrt_f32_e32 v75, v75
	s_nop 0
	global_load_dword v80, v[106:107], off offset:192
	v_mul_f32_e32 v66, v66, v75
	s_waitcnt lgkmcnt(0)
	v_mul_f32_e32 v66, v74, v66
	v_lshlrev_b64 v[74:75], 1, v[102:103]
	s_waitcnt vmcnt(0)
	v_fmac_f32_e32 v66, v80, v70
	v_cvt_pk_bf16_f32 v70, v66, v1
	v_lshl_add_u64 v[80:81], s[62:63], 0, v[74:75]
	global_store_short v[80:81], v70, off
	v_add_f32_e32 v70, v71, v76
	v_mul_f32_e32 v70, 0xbfb8aa3b, v70
	v_exp_f32_e32 v70, v70
	v_lshl_add_u64 v[74:75], s[64:65], 0, v[74:75]
	global_store_short v[74:75], v1, off
	v_lshlrev_b32_e32 v74, 2, v78
	v_add_f32_e32 v70, 1.0, v70
	v_rcp_f32_e32 v70, v70
	v_mov_b32_e32 v75, v1
	v_lshl_add_u64 v[80:81], v[98:99], 0, v[74:75]
	global_store_dword v[80:81], v66, off
	v_mul_f32_e32 v70, 0xc1000000, v70
	v_mul_f32_e32 v70, v79, v70
	v_mul_f32_e32 v70, 0x3fb8aa3b, v70
	v_exp_f32_e32 v70, v70
	ds_read_b32 v66, v241 offset:464
	v_fma_f32 v71, -v70, v70, 1.0
	v_max_f32_e32 v71, 0, v71
	s_nop 0
	s_nop 0
	s_nop 0
	s_nop 1
	s_nop 1
	v_sqrt_f32_e32 v71, v71
	s_nop 0
	global_load_dword v80, v[82:83], off offset:192
	v_mul_f32_e32 v67, v67, v71
	s_waitcnt lgkmcnt(0)
	v_mul_f32_e32 v81, v66, v67
	v_lshlrev_b64 v[66:67], 1, v[100:101]
	s_waitcnt vmcnt(0)
	v_fmac_f32_e32 v81, v70, v80
	v_lshl_add_u64 v[70:71], s[62:63], 0, v[66:67]
	v_lshl_add_u64 v[66:67], s[64:65], 0, v[66:67]
	v_cvt_pk_bf16_f32 v80, v81, v1
	global_store_short v[66:67], v1, off
	v_lshl_add_u64 v[66:67], v[90:91], 0, v[74:75]
	global_store_dword v[66:67], v81, off
	v_add_f32_e32 v67, v72, v76
	v_mul_f32_e32 v67, 0xbfb8aa3b, v67
	v_exp_f32_e32 v67, v67
	global_store_short v[70:71], v80, off
	ds_read_b32 v66, v241 offset:736
	v_add_f32_e32 v67, 1.0, v67
	v_rcp_f32_e32 v67, v67
	s_nop 0
	v_mul_f32_e32 v67, 0xc1000000, v67
	v_mul_f32_e32 v67, v79, v67
	v_mul_f32_e32 v67, 0x3fb8aa3b, v67
	v_exp_f32_e32 v67, v67
	s_nop 0
	v_fma_f32 v70, -v67, v67, 1.0
	v_max_f32_e32 v70, 0, v70
	s_nop 0
	s_nop 0
	s_nop 0
	s_nop 1
	s_nop 1
	v_sqrt_f32_e32 v70, v70
	s_nop 0
	global_load_dword v71, v[86:87], off offset:192
	s_waitcnt vmcnt(0)
	v_mul_f32_e32 v72, v67, v71
	v_mul_f32_e32 v67, v68, v70
	s_waitcnt lgkmcnt(0)
	v_fmac_f32_e32 v72, v67, v66
	v_lshlrev_b64 v[66:67], 1, v[104:105]
	v_lshl_add_u64 v[70:71], s[62:63], 0, v[66:67]
	v_lshl_add_u64 v[66:67], s[64:65], 0, v[66:67]
	v_cvt_pk_bf16_f32 v68, v72, v1
	global_store_short v[66:67], v1, off
	v_lshl_add_u64 v[66:67], v[94:95], 0, v[74:75]
	global_store_dword v[66:67], v72, off
	v_add_f32_e32 v67, v73, v76
	v_mul_f32_e32 v67, 0xbfb8aa3b, v67
	v_exp_f32_e32 v67, v67
	global_store_short v[70:71], v68, off
	v_add_f32_e32 v68, v69, v77
	v_mul_f32_e32 v68, 0xbfb8aa3b, v68
	v_add_f32_e32 v67, 1.0, v67
	v_rcp_f32_e32 v67, v67
	v_exp_f32_e32 v68, v68
	ds_read_b32 v66, v241 offset:1008
	v_mul_f32_e32 v67, 0xc1000000, v67
	v_mul_f32_e32 v67, v79, v67
	v_mul_f32_e32 v67, 0x3fb8aa3b, v67
	v_exp_f32_e32 v67, v67
	v_add_f32_e32 v68, 1.0, v68
	v_rcp_f32_e32 v68, v68
	v_fma_f32 v69, -v67, v67, 1.0
	v_max_f32_e32 v69, 0, v69
	s_nop 0
	s_nop 0
	s_nop 0
	s_nop 1
	s_nop 1
	v_sqrt_f32_e32 v69, v69
	s_nop 0
	global_load_dword v70, v[84:85], off offset:192
	s_waitcnt vmcnt(0)
	v_mul_f32_e32 v70, v67, v70
	v_mul_f32_e32 v67, v68, v69
	s_waitcnt lgkmcnt(0)
	v_fmac_f32_e32 v70, v67, v66
	v_lshlrev_b64 v[66:67], 1, v[96:97]
	v_lshl_add_u64 v[68:69], s[62:63], 0, v[66:67]
	v_lshl_add_u64 v[66:67], s[64:65], 0, v[66:67]
	v_cvt_pk_bf16_f32 v71, v70, v1
	global_store_short v[66:67], v1, off
	v_lshl_add_u64 v[66:67], v[92:93], 0, v[74:75]
	global_store_short v[68:69], v71, off
	global_store_dword v[66:67], v70, off
	s_cbranch_execnz .LBB0_330
	s_branch .LBB0_334

; #define LAS __attribute__((address_space(3)))
; #define LDS_WAIT() asm volatile("s_waitcnt lgkmcnt(0)" ::: "memory")
; template <int NT> ...
;     ...
;     for (int u = 0; u < NT; ++u) { const int m = m0 + 16 * u + rr, t = m - b * TP;
; #pragma unroll
;         for (int k = 0; k < 4; ++k) {
;             if (t - 3 + k >= 0) { const bf16_t* src = P + (size_t)(m - 3 + k) * DP + C_XR + hc0 + cl; raw[u][k][0] = *(const u32x4*)src; raw[u][k][1] = *(const u32x4*)(src + 8); }
;             else { raw[u][k][0] = (u32x4){0u, 0u, 0u, 0u}; raw[u][k][1] = (u32x4){0u, 0u, 0u, 0u}; } } }
;     LDS_WAIT();
; #pragma unroll
;     for (int u = 0; u < NT; ++u) { const int m = m0 + 16 * u + rr, t = m - b * TP; LAS float* XC = XCb + u * (16 * 68);
;         float xv[4][16];
; #pragma unroll
;         for (int k = 0; k < 4; ++k) { float f0[8], f1[8]; unpack8(raw[u][k][0], f0); unpack8(raw[u][k][1], f1);
; #pragma unroll
;             for (int e = 0; e < 8; ++e) { xv[k][e] = f0[e]; xv[k][8 + e] = f1[e]; } }
;         if (t >= TP - 3) { float* o = p->out + O_PCB + ((size_t)(l * NB + b) * 3 + (t - (TP - 3))) * D + hc0 + cl;
; #pragma unroll
;             for (int e = 0; e < 16; e += 4) *(f32x4*)(o + e) = (f32x4){xv[3][e], xv[3][e + 1], xv[3][e + 2], xv[3][e + 3]}; }
; #pragma unroll
;         for (int e = 0; e < 16; e += 4) {
;             const f32x4 w0 = *(const LAS f32x4*)(CST + 0 * 64 + cl + e), w1 = *(const LAS f32x4*)(CST + 1 * 64 + cl + e), w2 = *(const LAS f32x4*)(CST + 2 * 64 + cl + e),
;                         w3 = *(const LAS f32x4*)(CST + 3 * 64 + cl + e), bb = *(const LAS f32x4*)(CST + 4 * 64 + cl + e);
;             f32x4 r;
; #pragma unroll
;             for (int q = 0; q < 4; ++q) r[q] = w0[q] * xv[0][e + q] + w1[q] * xv[1][e + q] + w2[q] * xv[2][e + q] + w3[q] * xv[3][e + q] + bb[q];
;             *(LAS f32x4*)(XC + rr * 68 + cl + e) = r;
;         } }
.LBB0_335:
	s_or_b64 exec, exec, s[10:11]
	v_mov_b64_e32 v[84:85], s[60:61]
	v_mad_i64_i32 v[86:87], s[10:11], v82, s33, v[84:85]
	s_lshl_b32 s16, s75, 1
	v_lshl_add_u64 v[86:87], v[86:87], 0, s[16:17]
	v_lshl_add_u64 v[86:87], v[86:87], 0, v[0:1]
	v_add_co_u32_e32 v88, vcc, s38, v86
	v_add_u32_e32 v83, 13, v82
	s_nop 0
	v_addc_co_u32_e32 v89, vcc, 0, v87, vcc
	global_load_dwordx4 v[170:173], v[88:89], off
	v_lshl_add_u64 v[86:87], v[86:87], 0, s[28:29]
	global_load_dwordx4 v[136:139], v[86:87], off offset:16
	v_add_u32_e32 v92, 16, v82
	v_add_u32_e32 v88, 14, v82
	v_add_u32_e32 v90, 15, v82
	v_mad_i64_i32 v[82:83], s[10:11], v83, s33, v[84:85]
	v_lshl_add_u64 v[82:83], v[82:83], 0, s[16:17]
	v_mad_i64_i32 v[88:89], s[10:11], v88, s33, v[84:85]
	v_lshl_add_u64 v[82:83], v[82:83], 0, v[0:1]
	v_mad_i64_i32 v[90:91], s[10:11], v90, s33, v[84:85]
	v_mad_i64_i32 v[84:85], s[10:11], v92, s33, v[84:85]
	v_lshl_add_u64 v[88:89], v[88:89], 0, s[16:17]
	v_lshl_add_u64 v[92:93], v[82:83], 0, s[28:29]
	v_add_co_u32_e32 v82, vcc, s38, v82
	v_lshl_add_u64 v[88:89], v[88:89], 0, v[0:1]
	s_nop 0
	v_addc_co_u32_e32 v83, vcc, 0, v83, vcc
	v_lshl_add_u64 v[90:91], v[90:91], 0, s[16:17]
	v_add_co_u32_e32 v86, vcc, s38, v88
	v_lshl_add_u64 v[90:91], v[90:91], 0, v[0:1]
	s_nop 0
	v_addc_co_u32_e32 v87, vcc, 0, v89, vcc
	v_lshl_add_u64 v[84:85], v[84:85], 0, s[16:17]
	v_lshl_add_u64 v[96:97], v[90:91], 0, s[28:29]
	v_add_co_u32_e32 v90, vcc, s38, v90
	v_lshl_add_u64 v[84:85], v[84:85], 0, v[0:1]
	s_nop 0
	v_addc_co_u32_e32 v91, vcc, 0, v91, vcc
	v_add_co_u32_e32 v118, vcc, s38, v84
	v_lshl_add_u64 v[94:95], v[88:89], 0, s[28:29]
	s_nop 0
	v_addc_co_u32_e32 v119, vcc, 0, v85, vcc
	s_waitcnt vmcnt(3)
	v_lshlrev_b32_e32 v154, 16, v120
	v_and_b32_e32 v155, 0xffff0000, v120
	v_lshlrev_b32_e32 v158, 16, v121
	v_and_b32_e32 v159, 0xffff0000, v121
	v_lshl_add_u64 v[128:129], v[84:85], 0, s[28:29]
	global_load_dwordx4 v[106:109], v[82:83], off
	s_nop 0
	global_load_dwordx4 v[82:85], v[92:93], off offset:16
	global_load_dwordx4 v[110:113], v[86:87], off
	s_nop 0
	global_load_dwordx4 v[86:89], v[94:95], off offset:16
	global_load_dwordx4 v[114:117], v[90:91], off
	s_nop 0
	global_load_dwordx4 v[90:93], v[96:97], off offset:16
	s_nop 0
	global_load_dwordx4 v[118:121], v[118:119], off
	s_nop 0
	global_load_dwordx4 v[94:97], v[128:129], off offset:16
	s_waitcnt lgkmcnt(0)
	ds_read_b128 v[128:131], v227 offset:8704
	ds_read_b128 v[132:135], v227 offset:8960
	ds_read_b128 v[140:143], v227 offset:9216
	ds_read_b128 v[144:147], v227 offset:9472
	ds_read_b128 v[148:151], v227 offset:9728
	v_lshlrev_b32_e32 v156, 16, v102
	v_and_b32_e32 v157, 0xffff0000, v102
	v_lshlrev_b32_e32 v152, 16, v124
	s_waitcnt lgkmcnt(3)
	v_pk_mul_f32 v[154:155], v[132:133], v[154:155]
	v_and_b32_e32 v153, 0xffff0000, v124
	v_pk_fma_f32 v[154:155], v[128:129], v[156:157], v[154:155]
	v_lshlrev_b32_e32 v102, 16, v103
	s_waitcnt lgkmcnt(2)
	v_pk_fma_f32 v[152:153], v[140:141], v[152:153], v[154:155]
	v_and_b32_e32 v103, 0xffff0000, v103
	v_lshlrev_b32_e32 v124, 16, v125
	v_and_b32_e32 v125, 0xffff0000, v125
	v_lshlrev_b32_e32 v174, 16, v122
	v_and_b32_e32 v175, 0xffff0000, v122
	v_lshlrev_b32_e32 v176, 16, v104
	v_and_b32_e32 v177, 0xffff0000, v104
	v_lshlrev_b32_e32 v122, 16, v123
	v_and_b32_e32 v123, 0xffff0000, v123
	v_lshlrev_b32_e32 v104, 16, v105
	v_and_b32_e32 v105, 0xffff0000, v105
	s_waitcnt vmcnt(10)
	v_lshlrev_b32_e32 v186, 16, v78
	v_and_b32_e32 v187, 0xffff0000, v78
	v_lshlrev_b32_e32 v188, 16, v74
	v_and_b32_e32 v189, 0xffff0000, v74
	v_lshlrev_b32_e32 v184, 16, v98
	v_and_b32_e32 v185, 0xffff0000, v98
	v_lshlrev_b32_e32 v78, 16, v79
	v_and_b32_e32 v79, 0xffff0000, v79
	v_lshlrev_b32_e32 v74, 16, v75
	v_and_b32_e32 v75, 0xffff0000, v75
	v_lshlrev_b32_e32 v98, 16, v99
	s_waitcnt vmcnt(9)
	v_lshlrev_b32_e32 v154, 16, v170
	v_and_b32_e32 v155, 0xffff0000, v170
	s_waitcnt lgkmcnt(1)
	v_pk_fma_f32 v[152:153], v[144:145], v[154:155], v[152:153]
	v_pk_mul_f32 v[154:155], v[134:135], v[158:159]
	v_lshlrev_b32_e32 v156, 16, v171
	v_pk_fma_f32 v[102:103], v[130:131], v[102:103], v[154:155]
	v_and_b32_e32 v157, 0xffff0000, v171
	v_pk_fma_f32 v[102:103], v[142:143], v[124:125], v[102:103]
	s_waitcnt lgkmcnt(0)
	v_pk_add_f32 v[152:153], v[148:149], v[152:153]
	v_pk_fma_f32 v[102:103], v[146:147], v[156:157], v[102:103]
	v_lshlrev_b32_e32 v124, 16, v126
	v_pk_add_f32 v[154:155], v[150:151], v[102:103]
	ds_write_b128 v240, v[152:155]
	ds_read_b128 v[152:155], v227 offset:8720
	ds_read_b128 v[168:171], v227 offset:8976
	ds_read_b128 v[156:159], v227 offset:9232
	ds_read_b128 v[160:163], v227 offset:9488
	ds_read_b128 v[164:167], v227 offset:9744
	v_and_b32_e32 v125, 0xffff0000, v126
	s_waitcnt lgkmcnt(3)
	v_pk_mul_f32 v[174:175], v[168:169], v[174:175]
	v_pk_mul_f32 v[122:123], v[170:171], v[122:123]
	v_pk_fma_f32 v[174:175], v[152:153], v[176:177], v[174:175]
	v_lshlrev_b32_e32 v102, 16, v172
	v_and_b32_e32 v103, 0xffff0000, v172
	s_waitcnt lgkmcnt(2)
	v_pk_fma_f32 v[124:125], v[156:157], v[124:125], v[174:175]
	v_lshlrev_b32_e32 v126, 16, v127
	v_and_b32_e32 v127, 0xffff0000, v127
	v_pk_fma_f32 v[104:105], v[154:155], v[104:105], v[122:123]
	s_waitcnt lgkmcnt(1)
	v_pk_fma_f32 v[102:103], v[160:161], v[102:103], v[124:125]
	v_lshlrev_b32_e32 v124, 16, v173
	v_and_b32_e32 v125, 0xffff0000, v173
	v_pk_fma_f32 v[104:105], v[158:159], v[126:127], v[104:105]
	s_waitcnt lgkmcnt(0)
	v_pk_add_f32 v[102:103], v[164:165], v[102:103]
	v_pk_fma_f32 v[104:105], v[162:163], v[124:125], v[104:105]
	s_waitcnt vmcnt(8)
; #define LAS __attribute__((address_space(3)))
; template <int NT> ...
;     ...
;     for (int u = 0; u < NT; ++u) { const int m = m0 + 16 * u + rr, t = m - b * TP; LAS float* XC = XCb + u * (16 * 68);
;         float xv[4][16];
; #pragma unroll
;         for (int k = 0; k < 4; ++k) { float f0[8], f1[8]; unpack8(raw[u][k][0], f0); unpack8(raw[u][k][1], f1);
; #pragma unroll
;             for (int e = 0; e < 8; ++e) { xv[k][e] = f0[e]; xv[k][8 + e] = f1[e]; } }
;         if (t >= TP - 3) { float* o = p->out + O_PCB + ((size_t)(l * NB + b) * 3 + (t - (TP - 3))) * D + hc0 + cl;
; #pragma unroll
;             for (int e = 0; e < 16; e += 4) *(f32x4*)(o + e) = (f32x4){xv[3][e], xv[3][e + 1], xv[3][e + 2], xv[3][e + 3]}; }
; #pragma unroll
;         for (int e = 0; e < 16; e += 4) {
;             const f32x4 w0 = *(const LAS f32x4*)(CST + 0 * 64 + cl + e), w1 = *(const LAS f32x4*)(CST + 1 * 64 + cl + e), w2 = *(const LAS f32x4*)(CST + 2 * 64 + cl + e),
;                         w3 = *(const LAS f32x4*)(CST + 3 * 64 + cl + e), bb = *(const LAS f32x4*)(CST + 4 * 64 + cl + e);
;             f32x4 r;
; #pragma unroll
;             for (int q = 0; q < 4; ++q) r[q] = w0[q] * xv[0][e + q] + w1[q] * xv[1][e + q] + w2[q] * xv[2][e + q] + w3[q] * xv[3][e + q] + bb[q];
;             *(LAS f32x4*)(XC + rr * 68 + cl + e) = r;
;         } }
	v_lshlrev_b32_e32 v126, 16, v136
	v_pk_add_f32 v[104:105], v[166:167], v[104:105]
	ds_write_b128 v240, v[102:105] offset:16
	ds_read_b128 v[102:105], v227 offset:8736
	ds_read_b128 v[180:183], v227 offset:8992
	ds_read_b128 v[122:125], v227 offset:9248
	ds_read_b128 v[172:175], v227 offset:9504
	ds_read_b128 v[176:179], v227 offset:9760
	v_and_b32_e32 v127, 0xffff0000, v136
	s_waitcnt lgkmcnt(3)
	v_pk_mul_f32 v[186:187], v[180:181], v[186:187]
	v_pk_mul_f32 v[78:79], v[182:183], v[78:79]
	v_pk_fma_f32 v[186:187], v[102:103], v[188:189], v[186:187]
	v_and_b32_e32 v99, 0xffff0000, v99
	s_waitcnt lgkmcnt(2)
	v_pk_fma_f32 v[184:185], v[122:123], v[184:185], v[186:187]
	v_pk_fma_f32 v[74:75], v[104:105], v[74:75], v[78:79]
	s_waitcnt lgkmcnt(1)
	v_pk_fma_f32 v[126:127], v[172:173], v[126:127], v[184:185]
	v_pk_fma_f32 v[74:75], v[124:125], v[98:99], v[74:75]
	s_waitcnt lgkmcnt(0)
	v_pk_add_f32 v[184:185], v[176:177], v[126:127]
	v_lshlrev_b32_e32 v126, 16, v137
	v_and_b32_e32 v127, 0xffff0000, v137
	v_pk_fma_f32 v[74:75], v[174:175], v[126:127], v[74:75]
	v_lshlrev_b32_e32 v78, 16, v76
	v_pk_add_f32 v[186:187], v[178:179], v[74:75]
	ds_write_b128 v240, v[184:187] offset:32
	ds_read_b128 v[184:187], v227 offset:8752
	ds_read_b128 v[200:203], v227 offset:9008
	ds_read_b128 v[188:191], v227 offset:9264
	ds_read_b128 v[192:195], v227 offset:9520
	ds_read_b128 v[196:199], v227 offset:9776
	v_lshlrev_b32_e32 v74, 16, v80
	v_and_b32_e32 v75, 0xffff0000, v80
	v_and_b32_e32 v79, 0xffff0000, v76
	s_waitcnt lgkmcnt(3)
	v_pk_mul_f32 v[74:75], v[200:201], v[74:75]
	v_lshlrev_b32_e32 v80, 16, v81
	v_and_b32_e32 v81, 0xffff0000, v81
	v_pk_fma_f32 v[74:75], v[184:185], v[78:79], v[74:75]
	v_lshlrev_b32_e32 v78, 16, v100
	v_and_b32_e32 v79, 0xffff0000, v100
	v_lshlrev_b32_e32 v76, 16, v77
	v_and_b32_e32 v77, 0xffff0000, v77
	v_pk_mul_f32 v[80:81], v[202:203], v[80:81]
	s_waitcnt lgkmcnt(2)
	v_pk_fma_f32 v[74:75], v[188:189], v[78:79], v[74:75]
	v_lshlrev_b32_e32 v78, 16, v138
	v_and_b32_e32 v79, 0xffff0000, v138
	v_lshlrev_b32_e32 v98, 16, v101
	v_and_b32_e32 v99, 0xffff0000, v101
	v_pk_fma_f32 v[76:77], v[186:187], v[76:77], v[80:81]
	s_waitcnt lgkmcnt(1)
	v_pk_fma_f32 v[74:75], v[192:193], v[78:79], v[74:75]
	v_lshlrev_b32_e32 v78, 16, v139
	v_and_b32_e32 v79, 0xffff0000, v139
	v_pk_fma_f32 v[76:77], v[190:191], v[98:99], v[76:77]
	s_waitcnt vmcnt(7)
	v_lshlrev_b32_e32 v80, 16, v106
	v_pk_fma_f32 v[76:77], v[194:195], v[78:79], v[76:77]
	s_waitcnt vmcnt(5)
	v_lshlrev_b32_e32 v78, 16, v110
	v_and_b32_e32 v79, 0xffff0000, v110
	v_and_b32_e32 v81, 0xffff0000, v106
	v_pk_mul_f32 v[78:79], v[132:133], v[78:79]
	s_waitcnt lgkmcnt(0)
	v_pk_add_f32 v[74:75], v[196:197], v[74:75]
	v_pk_add_f32 v[76:77], v[198:199], v[76:77]
	v_pk_fma_f32 v[78:79], v[128:129], v[80:81], v[78:79]
	v_lshlrev_b32_e32 v80, 16, v111
	v_and_b32_e32 v81, 0xffff0000, v111
	ds_write_b128 v240, v[74:77] offset:48
	s_waitcnt vmcnt(3)
	v_lshlrev_b32_e32 v76, 16, v114
	v_and_b32_e32 v77, 0xffff0000, v114
	v_lshlrev_b32_e32 v98, 16, v107
	v_and_b32_e32 v99, 0xffff0000, v107
	v_pk_mul_f32 v[80:81], v[134:135], v[80:81]
	s_waitcnt vmcnt(1)
	v_lshlrev_b32_e32 v74, 16, v118
	v_and_b32_e32 v75, 0xffff0000, v118
	v_pk_fma_f32 v[76:77], v[140:141], v[76:77], v[78:79]
	v_lshlrev_b32_e32 v78, 16, v115
	v_and_b32_e32 v79, 0xffff0000, v115
	v_pk_fma_f32 v[80:81], v[130:131], v[98:99], v[80:81]
	v_pk_fma_f32 v[74:75], v[144:145], v[74:75], v[76:77]
	v_lshlrev_b32_e32 v76, 16, v119
	v_and_b32_e32 v77, 0xffff0000, v119
	v_pk_fma_f32 v[78:79], v[142:143], v[78:79], v[80:81]
	v_lshlrev_b32_e32 v80, 16, v108
	v_pk_fma_f32 v[76:77], v[146:147], v[76:77], v[78:79]
	v_lshlrev_b32_e32 v78, 16, v112
	v_and_b32_e32 v79, 0xffff0000, v112
	v_and_b32_e32 v81, 0xffff0000, v108
	v_pk_mul_f32 v[78:79], v[168:169], v[78:79]
	v_pk_add_f32 v[74:75], v[148:149], v[74:75]
	v_pk_add_f32 v[76:77], v[150:151], v[76:77]
	v_pk_fma_f32 v[78:79], v[152:153], v[80:81], v[78:79]
	v_lshlrev_b32_e32 v80, 16, v113
	v_and_b32_e32 v81, 0xffff0000, v113
	ds_write_b128 v240, v[74:77] offset:4352
	v_lshlrev_b32_e32 v76, 16, v116
	v_and_b32_e32 v77, 0xffff0000, v116
	v_lshlrev_b32_e32 v98, 16, v109
	v_and_b32_e32 v99, 0xffff0000, v109
	v_pk_mul_f32 v[80:81], v[170:171], v[80:81]
	v_lshlrev_b32_e32 v74, 16, v120
	v_and_b32_e32 v75, 0xffff0000, v120
	v_pk_fma_f32 v[76:77], v[156:157], v[76:77], v[78:79]
	v_lshlrev_b32_e32 v78, 16, v117
	v_and_b32_e32 v79, 0xffff0000, v117
	v_pk_fma_f32 v[80:81], v[154:155], v[98:99], v[80:81]
	v_pk_fma_f32 v[74:75], v[160:161], v[74:75], v[76:77]
	v_lshlrev_b32_e32 v76, 16, v121
	v_and_b32_e32 v77, 0xffff0000, v121
	v_pk_fma_f32 v[78:79], v[158:159], v[78:79], v[80:81]
	v_lshlrev_b32_e32 v80, 16, v82
	v_pk_fma_f32 v[76:77], v[162:163], v[76:77], v[78:79]
	v_lshlrev_b32_e32 v78, 16, v86
	v_and_b32_e32 v79, 0xffff0000, v86
	v_and_b32_e32 v81, 0xffff0000, v82
	v_pk_mul_f32 v[78:79], v[180:181], v[78:79]
	v_pk_add_f32 v[74:75], v[164:165], v[74:75]
	v_pk_add_f32 v[76:77], v[166:167], v[76:77]
	v_pk_fma_f32 v[78:79], v[102:103], v[80:81], v[78:79]
	v_lshlrev_b32_e32 v80, 16, v87
	v_and_b32_e32 v81, 0xffff0000, v87
	ds_write_b128 v240, v[74:77] offset:4368
	v_lshlrev_b32_e32 v76, 16, v90
	v_and_b32_e32 v77, 0xffff0000, v90
	v_lshlrev_b32_e32 v82, 16, v83
	v_and_b32_e32 v83, 0xffff0000, v83
	v_pk_mul_f32 v[80:81], v[182:183], v[80:81]
	s_waitcnt vmcnt(0)
; #define LAS __attribute__((address_space(3)))
; __device__ __forceinline__ float sigmoidf_(float x) { return __builtin_amdgcn_rcpf(1.0f + __expf(-x)); }
; template <int NT> ...
;     ...
;         for (int e = 0; e < 16; e += 4) {
;             const f32x4 w0 = *(const LAS f32x4*)(CST + 0 * 64 + cl + e), w1 = *(const LAS f32x4*)(CST + 1 * 64 + cl + e), w2 = *(const LAS f32x4*)(CST + 2 * 64 + cl + e),
;                         w3 = *(const LAS f32x4*)(CST + 3 * 64 + cl + e), bb = *(const LAS f32x4*)(CST + 4 * 64 + cl + e);
;             f32x4 r;
; #pragma unroll
;             for (int q = 0; q < 4; ++q) r[q] = w0[q] * xv[0][e + q] + w1[q] * xv[1][e + q] + w2[q] * xv[2][e + q] + w3[q] * xv[3][e + q] + bb[q];
;             *(LAS f32x4*)(XC + rr * 68 + cl + e) = r;
;         } }
;     LDS_WAIT();
;     f32x4 ar[NT][4], ai[NT][4];
; #pragma unroll
;     for (int u = 0; u < NT; ++u) { const LAS float* XC = XCb + u * (16 * 68);
; #pragma unroll
;         for (int n = 0; n < 4; ++n) { ar[u][n] = (f32x4){0.f, 0.f, 0.f, 0.f}; ai[u][n] = (f32x4){0.f, 0.f, 0.f, 0.f}; }
; #pragma unroll
;         for (int s = 0; s < 2; ++s) {
;             const f32x4 x0 = *(const LAS f32x4*)(XC + fr * 68 + 32 * s + 8 * fq), x1 = *(const LAS f32x4*)(XC + fr * 68 + 32 * s + 8 * fq + 4);
;             u32x4 aw; aw.x = cvt_pk_bf16(x0[0], x0[1]); aw.y = cvt_pk_bf16(x0[2], x0[3]); aw.z = cvt_pk_bf16(x1[0], x1[1]); aw.w = cvt_pk_bf16(x1[2], x1[3]);
;             const bf16x8 af = __builtin_bit_cast(bf16x8, aw);
; #pragma unroll
;             for (int n = 0; n < 4; ++n) { ar[u][n] = __builtin_amdgcn_mfma_f32_16x16x32_bf16(af, Wa[n][s], ar[u][n], 0, 0, 0); ai[u][n] = __builtin_amdgcn_mfma_f32_16x16x32_bf16(af, Wx[n][s], ai[u][n], 0, 0, 0); }
;         } }
;     float av[NT][4][4], bv[NT][4][4];
; #pragma unroll
;     for (int u = 0; u < NT; ++u) { const LAS float* XC = XCb + u * (16 * 68); const int t0 = m0 + 16 * u - b * TP;
; #pragma unroll
;         for (int n = 0; n < 4; ++n) { const int cc = 16 * n + fr;
;             const float ba = CST[5 * 64 + cc], bx = CST[6 * 64 + cc], sp = CST[7 * 64 + cc];
; #pragma unroll
;             for (int j = 0; j < 4; ++j) {
;                 const float xc = XC[(4 * fq + j) * 68 + cc];
;                 const float r = sigmoidf_(ar[u][n][j] + ba), ig = sigmoidf_(ai[u][n][j] + bx);
;                 const float a = __expf(-8.0f * r * sp);
	v_lshlrev_b32_e32 v74, 16, v94
	v_and_b32_e32 v75, 0xffff0000, v94
	v_pk_fma_f32 v[76:77], v[122:123], v[76:77], v[78:79]
	v_lshlrev_b32_e32 v78, 16, v91
	v_and_b32_e32 v79, 0xffff0000, v91
	v_pk_fma_f32 v[80:81], v[104:105], v[82:83], v[80:81]
	v_pk_fma_f32 v[74:75], v[172:173], v[74:75], v[76:77]
	v_lshlrev_b32_e32 v76, 16, v95
	v_and_b32_e32 v77, 0xffff0000, v95
	v_pk_fma_f32 v[78:79], v[124:125], v[78:79], v[80:81]
	v_lshlrev_b32_e32 v80, 16, v84
	v_pk_fma_f32 v[76:77], v[174:175], v[76:77], v[78:79]
	v_lshlrev_b32_e32 v78, 16, v88
	v_and_b32_e32 v79, 0xffff0000, v88
	v_and_b32_e32 v81, 0xffff0000, v84
	v_pk_mul_f32 v[78:79], v[200:201], v[78:79]
	v_pk_add_f32 v[74:75], v[176:177], v[74:75]
	v_pk_add_f32 v[76:77], v[178:179], v[76:77]
	v_pk_fma_f32 v[78:79], v[184:185], v[80:81], v[78:79]
	v_lshlrev_b32_e32 v80, 16, v89
	v_and_b32_e32 v81, 0xffff0000, v89
	ds_write_b128 v240, v[74:77] offset:4384
	v_lshlrev_b32_e32 v76, 16, v92
	v_and_b32_e32 v77, 0xffff0000, v92
	v_lshlrev_b32_e32 v82, 16, v85
	v_and_b32_e32 v83, 0xffff0000, v85
	v_pk_mul_f32 v[80:81], v[202:203], v[80:81]
	v_lshlrev_b32_e32 v74, 16, v96
	v_and_b32_e32 v75, 0xffff0000, v96
	v_pk_fma_f32 v[76:77], v[188:189], v[76:77], v[78:79]
	v_lshlrev_b32_e32 v78, 16, v93
	v_and_b32_e32 v79, 0xffff0000, v93
	v_pk_fma_f32 v[80:81], v[186:187], v[82:83], v[80:81]
	v_pk_fma_f32 v[74:75], v[192:193], v[74:75], v[76:77]
	v_lshlrev_b32_e32 v76, 16, v97
	v_and_b32_e32 v77, 0xffff0000, v97
	v_pk_fma_f32 v[78:79], v[190:191], v[78:79], v[80:81]
	v_pk_add_f32 v[74:75], v[196:197], v[74:75]
	v_pk_fma_f32 v[76:77], v[194:195], v[76:77], v[78:79]
	v_add_u32_e32 v177, 0x2400, v232
	v_pk_add_f32 v[76:77], v[198:199], v[76:77]
	ds_write_b128 v240, v[74:77] offset:4400
	s_waitcnt lgkmcnt(0)
	ds_read_b128 v[74:77], v239
	ds_read_b128 v[78:81], v239 offset:16
	s_waitcnt lgkmcnt(1)
	v_cvt_pk_bf16_f32 v74, v74, v75
	v_cvt_pk_bf16_f32 v75, v76, v77
	s_waitcnt lgkmcnt(0)
	v_cvt_pk_bf16_f32 v76, v78, v79
	v_cvt_pk_bf16_f32 v77, v80, v81
	ds_read_b128 v[106:109], v239 offset:128
	ds_read_b128 v[110:113], v239 offset:144
	v_mfma_f32_16x16x32_bf16 v[78:81], v[74:77], v[34:37], 0
	s_waitcnt lgkmcnt(1)
	v_cvt_pk_bf16_f32 v106, v106, v107
	v_mfma_f32_16x16x32_bf16 v[82:85], v[74:77], v[38:41], 0
	v_cvt_pk_bf16_f32 v107, v108, v109
	s_waitcnt lgkmcnt(0)
	v_cvt_pk_bf16_f32 v108, v110, v111
	v_cvt_pk_bf16_f32 v109, v112, v113
	v_mfma_f32_16x16x32_bf16 v[86:89], v[74:77], v[42:45], 0
	v_add_u32_e32 v176, 0x2800, v232
	s_add_i32 s21, s21, 2
	v_add_u32_e32 v243, 32, v243
	v_mfma_f32_16x16x32_bf16 v[132:135], v[106:109], v[10:13], v[78:81]
	s_cmp_gt_u32 s21, 5
	v_subrev_u32_e32 v244, 32, v244
	v_mfma_f32_16x16x32_bf16 v[140:143], v[106:109], v[14:17], v[82:85]
	ds_read_b128 v[78:81], v239 offset:4352
	s_nop 1
	ds_read_b128 v[82:85], v239 offset:4368
	v_mfma_f32_16x16x32_bf16 v[90:93], v[74:77], v[46:49], 0
	v_mfma_f32_16x16x32_bf16 v[94:97], v[74:77], v[50:53], 0
	v_mfma_f32_16x16x32_bf16 v[98:101], v[74:77], v[54:57], 0
	v_mfma_f32_16x16x32_bf16 v[102:105], v[74:77], v[62:65], 0
	v_mfma_f32_16x16x32_bf16 v[74:77], v[74:77], v[58:61], 0
	v_mfma_f32_16x16x32_bf16 v[126:129], v[106:109], v[22:25], v[86:89]
	v_mfma_f32_16x16x32_bf16 v[122:125], v[106:109], v[26:29], v[90:93]
	v_mfma_f32_16x16x32_bf16 v[118:121], v[106:109], v[30:33], v[94:97]
	v_mfma_f32_16x16x32_bf16 v[114:117], v[106:109], v[18:21], v[98:101]
	v_mfma_f32_16x16x32_bf16 v[110:113], v[106:109], v[6:9], v[102:105]
	v_mfma_f32_16x16x32_bf16 v[106:109], v[106:109], v[2:5], v[74:77]
	s_waitcnt lgkmcnt(1)
	v_cvt_pk_bf16_f32 v74, v78, v79
	v_cvt_pk_bf16_f32 v75, v80, v81
	s_waitcnt lgkmcnt(0)
	v_cvt_pk_bf16_f32 v76, v82, v83
	v_cvt_pk_bf16_f32 v77, v84, v85
	ds_read_b128 v[94:97], v239 offset:4480
	ds_read_b128 v[98:101], v239 offset:4496
	s_waitcnt lgkmcnt(1)
	v_cvt_pk_bf16_f32 v152, v94, v95
	v_cvt_pk_bf16_f32 v153, v96, v97
	s_waitcnt lgkmcnt(0)
	v_cvt_pk_bf16_f32 v154, v98, v99
	v_cvt_pk_bf16_f32 v155, v100, v101
	ds_read2_b32 v[168:169], v177 offset0:192 offset1:208
	v_mfma_f32_16x16x32_bf16 v[78:81], v[74:77], v[34:37], 0
	ds_read2_b32 v[164:165], v176 offset0:64 offset1:80
	ds_read2_b32 v[166:167], v176 offset1:16
	ds_read2_b32 v[156:157], v177 offset0:224 offset1:240
	v_mfma_f32_16x16x32_bf16 v[102:105], v[152:155], v[10:13], v[78:81]
	s_waitcnt lgkmcnt(3)
	v_add_f32_e32 v133, v133, v168
	v_mul_f32_e32 v133, 0xbfb8aa3b, v133
	v_exp_f32_e32 v133, v133
	v_add_f32_e32 v78, v132, v168
	v_mul_f32_e32 v78, 0xbfb8aa3b, v78
	v_exp_f32_e32 v130, v78
	v_mfma_f32_16x16x32_bf16 v[82:85], v[74:77], v[38:41], 0
	v_add_f32_e32 v133, 1.0, v133
	v_add_f32_e32 v134, v134, v168
	v_add_f32_e32 v130, 1.0, v130
	v_rcp_f32_e32 v130, v130
	v_mfma_f32_16x16x32_bf16 v[144:147], v[74:77], v[54:57], 0
	v_mul_f32_e32 v134, 0xbfb8aa3b, v134
	v_exp_f32_e32 v134, v134
	v_mul_f32_e32 v130, 0xc1000000, v130
	s_waitcnt lgkmcnt(2)
	v_mul_f32_e32 v130, v164, v130
	v_mul_f32_e32 v130, 0x3fb8aa3b, v130
	v_mfma_f32_16x16x32_bf16 v[98:101], v[152:155], v[14:17], v[82:85]
	v_add_f32_e32 v135, v135, v168
	v_mul_f32_e32 v135, 0xbfb8aa3b, v135
	v_exp_f32_e32 v135, v135
	v_mfma_f32_16x16x32_bf16 v[82:85], v[152:155], v[18:21], v[144:147]
	v_add_f32_e32 v126, v126, v169
	v_mul_f32_e32 v126, 0xbfb8aa3b, v126
	v_add_f32_e32 v135, 1.0, v135
	v_exp_f32_e32 v146, v130
	v_mfma_f32_16x16x32_bf16 v[86:89], v[74:77], v[42:45], 0
	s_waitcnt lgkmcnt(1)
; #define LAS __attribute__((address_space(3)))
; __device__ __forceinline__ unsigned cvt_pk_bf16(float lo, float hi) { unsigned r; asm volatile("v_cvt_pk_bf16_f32 %0, %1, %2" : "=v"(r) : "v"(lo), "v"(hi)); return r; }
; __device__ __forceinline__ float sigmoidf_(float x) { return __builtin_amdgcn_rcpf(1.0f + __expf(-x)); }
; template <int NT> ...
;     ...
;         for (int s = 0; s < 2; ++s) {
;             const f32x4 x0 = *(const LAS f32x4*)(XC + fr * 68 + 32 * s + 8 * fq), x1 = *(const LAS f32x4*)(XC + fr * 68 + 32 * s + 8 * fq + 4);
;             u32x4 aw; aw.x = cvt_pk_bf16(x0[0], x0[1]); aw.y = cvt_pk_bf16(x0[2], x0[3]); aw.z = cvt_pk_bf16(x1[0], x1[1]); aw.w = cvt_pk_bf16(x1[2], x1[3]);
;             const bf16x8 af = __builtin_bit_cast(bf16x8, aw);
; #pragma unroll
;             for (int n = 0; n < 4; ++n) { ar[u][n] = __builtin_amdgcn_mfma_f32_16x16x32_bf16(af, Wa[n][s], ar[u][n], 0, 0, 0); ai[u][n] = __builtin_amdgcn_mfma_f32_16x16x32_bf16(af, Wx[n][s], ai[u][n], 0, 0, 0); }
;         } }
;     float av[NT][4][4], bv[NT][4][4];
; #pragma unroll
;     for (int u = 0; u < NT; ++u) { const LAS float* XC = XCb + u * (16 * 68); const int t0 = m0 + 16 * u - b * TP;
; #pragma unroll
;         for (int n = 0; n < 4; ++n) { const int cc = 16 * n + fr;
;             const float ba = CST[5 * 64 + cc], bx = CST[6 * 64 + cc], sp = CST[7 * 64 + cc];
; #pragma unroll
;             for (int j = 0; j < 4; ++j) {
;                 const float xc = XC[(4 * fq + j) * 68 + cc];
;                 const float r = sigmoidf_(ar[u][n][j] + ba), ig = sigmoidf_(ai[u][n][j] + bx);
;                 const float a = __expf(-8.0f * r * sp);
;                 float mult = sqrtf(fmaxf(1.0f - a * a, 0.f));
;                 if (t0 + 4 * fq + j == 0) mult = 1.0f;
;                 av[u][n][j] = a; bv[u][n][j] = mult * ig * xc; } } }
	v_add_f32_e32 v130, v140, v166
	v_mul_f32_e32 v130, 0xbfb8aa3b, v130
	v_fma_f32 v131, -v146, v146, 1.0
	v_mfma_f32_16x16x32_bf16 v[136:139], v[74:77], v[50:53], 0
	v_max_f32_e32 v131, 0, v131
	s_nop 0
	s_nop 0
	v_exp_f32_e32 v130, v130
	v_mfma_f32_16x16x32_bf16 v[94:97], v[152:155], v[22:25], v[86:89]
	v_mov_b32_e32 v132, v131
	ds_read2_b32 v[144:145], v241 offset1:16
	v_add_f32_e32 v130, 1.0, v130
	v_mfma_f32_16x16x32_bf16 v[86:89], v[152:155], v[30:33], v[136:139]
	v_rcp_f32_e32 v131, v130
	v_rcp_f32_e32 v135, v135
	v_exp_f32_e32 v126, v126
	s_nop 0
	v_mfma_f32_16x16x32_bf16 v[148:151], v[74:77], v[62:65], 0
	v_add_f32_e32 v122, v122, v167
	v_add_f32_e32 v126, 1.0, v126
	s_nop 0
	s_nop 0
	s_nop 0
	v_rcp_f32_e32 v126, v126
	s_nop 0
	v_mul_f32_e32 v126, 0xc1000000, v126
	v_mul_f32_e32 v126, v165, v126
	v_rcp_f32_e32 v136, v133
	v_mul_f32_e32 v126, 0x3fb8aa3b, v126
	v_mfma_f32_16x16x32_bf16 v[78:81], v[152:155], v[6:9], v[148:151]
	v_sqrt_f32_e32 v130, v132
	s_nop 0
	v_cmp_eq_u32_e32 vcc, s19, v245
	v_mul_f32_e32 v122, 0xbfb8aa3b, v122
	v_exp_f32_e32 v148, v126
	v_cndmask_b32_e64 v133, v130, 1.0, vcc
	v_mul_f32_e32 v130, 0xc1000000, v136
	v_mul_f32_e32 v130, v164, v130
	v_mul_f32_e32 v130, 0x3fb8aa3b, v130
	v_exp_f32_e32 v138, v130
	v_add_f32_e32 v130, v141, v166
	v_mul_f32_e32 v130, 0xbfb8aa3b, v130
	v_exp_f32_e32 v130, v130
	v_fma_f32 v132, -v138, v138, 1.0
	v_max_f32_e32 v132, 0, v132
	v_add_f32_e32 v130, 1.0, v130
	v_rcp_f32_e32 v130, v130
	ds_read2_b32 v[136:137], v241 offset0:68 offset1:84
	v_fma_f32 v126, -v148, v148, 1.0
	v_max_f32_e32 v126, 0, v126
	v_exp_f32_e32 v122, v122
	v_add_f32_e32 v127, v127, v169
	v_mul_f32_e32 v127, 0xbfb8aa3b, v127
	v_add_f32_e32 v122, 1.0, v122
	v_exp_f32_e32 v127, v127
	v_sqrt_f32_e32 v132, v132
	s_nop 0
	v_pk_mul_f32 v[130:131], v[130:131], v[132:133]
	v_add_f32_e32 v132, 1.0, v134
	v_rcp_f32_e32 v134, v132
	s_waitcnt lgkmcnt(0)
	v_mov_b32_e32 v132, v136
	v_mov_b32_e32 v133, v144
	v_pk_mul_f32 v[132:133], v[132:133], v[130:131]
	v_mul_f32_e32 v130, 0xc1000000, v134
	v_mul_f32_e32 v130, v164, v130
	v_mul_f32_e32 v130, 0x3fb8aa3b, v130
	v_exp_f32_e32 v139, v130
	v_add_f32_e32 v130, v142, v166
	v_mul_f32_e32 v130, 0xbfb8aa3b, v130
	v_exp_f32_e32 v134, v130
	v_fma_f32 v130, -v139, v139, 1.0
	v_max_f32_e32 v130, 0, v130
	v_add_f32_e32 v134, 1.0, v134
	v_rcp_f32_e32 v134, v134
	v_mov_b32_e32 v136, v130
	v_rcp_f32_e32 v151, v122
	v_add_f32_e32 v127, 1.0, v127
	v_rcp_f32_e32 v127, v127
	v_add_f32_e32 v123, v123, v167
	v_mul_f32_e32 v123, 0xbfb8aa3b, v123
	v_add_f32_e32 v128, v128, v169
	v_mul_f32_e32 v128, 0xbfb8aa3b, v128
	v_exp_f32_e32 v128, v128
	v_sqrt_f32_e32 v136, v136
	s_nop 0
	v_mul_f32_e32 v136, v134, v136
	v_mul_f32_e32 v134, 0xc1000000, v135
	v_mul_f32_e32 v134, v164, v134
	v_mul_f32_e32 v134, 0x3fb8aa3b, v134
	v_exp_f32_e32 v141, v134
	v_add_f32_e32 v134, v143, v166
	v_mul_f32_e32 v134, 0xbfb8aa3b, v134
	v_exp_f32_e32 v140, v134
	v_fma_f32 v134, -v141, v141, 1.0
	v_max_f32_e32 v134, 0, v134
	v_add_f32_e32 v140, 1.0, v140
	v_rcp_f32_e32 v140, v140
	v_mov_b32_e32 v142, v134
	v_add_f32_e32 v129, v129, v169
	v_mul_f32_e32 v129, 0xbfb8aa3b, v129
	v_exp_f32_e32 v129, v129
	s_nop 0
	v_add_f32_e32 v129, 1.0, v129
	v_rcp_f32_e32 v129, v129
	v_add_f32_e32 v124, v124, v167
	v_mov_b32_e32 v144, v137
	v_mul_f32_e32 v129, 0xc1000000, v129
	v_sqrt_f32_e32 v142, v142
	s_nop 0
	v_mul_f32_e32 v142, v140, v142
	v_mul_f32_e32 v129, v165, v129
	v_mul_f32_e32 v129, 0x3fb8aa3b, v129
	v_exp_f32_e32 v129, v129
	v_add_f32_e32 v118, v118, v156
	v_mul_f32_e32 v124, 0xbfb8aa3b, v124
	v_mul_f32_e32 v118, 0xbfb8aa3b, v118
	v_exp_f32_e32 v124, v124
	v_exp_f32_e32 v118, v118
	v_mfma_f32_16x16x32_bf16 v[90:93], v[74:77], v[46:49], 0
	v_sqrt_f32_e32 v122, v126
	s_nop 0
	v_mul_f32_e32 v126, 0xc1000000, v127
	v_mul_f32_e32 v126, v165, v126
	v_mul_f32_e32 v126, 0x3fb8aa3b, v126
	v_exp_f32_e32 v126, v126
	v_exp_f32_e32 v127, v123
	v_mfma_f32_16x16x32_bf16 v[74:77], v[74:77], v[58:61], 0
	v_add_f32_e32 v124, 1.0, v124
	v_fma_f32 v123, -v126, v126, 1.0
	v_max_f32_e32 v123, 0, v123
	v_add_f32_e32 v118, 1.0, v118
	v_mfma_f32_16x16x32_bf16 v[90:93], v[152:155], v[26:29], v[90:93]
	v_mov_b32_e32 v140, v123
	v_cndmask_b32_e64 v123, v122, 1.0, vcc
	v_add_f32_e32 v122, 1.0, v127
	v_rcp_f32_e32 v150, v122
	v_mfma_f32_16x16x32_bf16 v[74:77], v[152:155], v[2:5], v[74:77]
	v_rcp_f32_e32 v124, v124
	ds_read2_b32 v[152:153], v176 offset0:96 offset1:112
	v_add_f32_e32 v127, 1.0, v128
	v_rcp_f32_e32 v127, v127
	v_rcp_f32_e32 v118, v118
	v_add_f32_e32 v125, v125, v167
	v_mul_f32_e32 v127, 0xc1000000, v127
	v_mul_f32_e32 v127, v165, v127
	v_mul_f32_e32 v127, 0x3fb8aa3b, v127
	v_exp_f32_e32 v127, v127
	v_sqrt_f32_e32 v122, v140
	s_nop 0
	v_mul_f32_e32 v125, 0xbfb8aa3b, v125
	v_exp_f32_e32 v125, v125
	v_fma_f32 v128, -v127, v127, 1.0
	v_max_f32_e32 v128, 0, v128
	v_mul_f32_e32 v118, 0xc1000000, v118
	s_waitcnt lgkmcnt(0)
	v_mul_f32_e32 v118, v152, v118
	v_mul_f32_e32 v118, 0x3fb8aa3b, v118
	ds_read2_b32 v[154:155], v176 offset0:32 offset1:48
	v_exp_f32_e32 v160, v118
	v_add_f32_e32 v125, 1.0, v125
	v_rcp_f32_e32 v125, v125
	v_fma_f32 v118, -v160, v160, 1.0
	v_pk_mul_f32 v[122:123], v[150:151], v[122:123]
	s_waitcnt lgkmcnt(0)
; #define LAS __attribute__((address_space(3)))
; __device__ __forceinline__ float sigmoidf_(float x) { return __builtin_amdgcn_rcpf(1.0f + __expf(-x)); }
; template <int NT> ...
;     ...
;     for (int u = 0; u < NT; ++u) { const LAS float* XC = XCb + u * (16 * 68); const int t0 = m0 + 16 * u - b * TP;
; #pragma unroll
;         for (int n = 0; n < 4; ++n) { const int cc = 16 * n + fr;
;             const float ba = CST[5 * 64 + cc], bx = CST[6 * 64 + cc], sp = CST[7 * 64 + cc];
; #pragma unroll
;             for (int j = 0; j < 4; ++j) {
;                 const float xc = XC[(4 * fq + j) * 68 + cc];
;                 const float r = sigmoidf_(ar[u][n][j] + ba), ig = sigmoidf_(ai[u][n][j] + bx);
;                 const float a = __expf(-8.0f * r * sp);
;                 float mult = sqrtf(fmaxf(1.0f - a * a, 0.f));
;                 if (t0 + 4 * fq + j == 0) mult = 1.0f;
;                 av[u][n][j] = a; bv[u][n][j] = mult * ig * xc; } } }
	v_add_f32_e32 v114, v114, v154
	v_sqrt_f32_e32 v128, v128
	s_nop 0
	v_fma_f32 v137, -v129, v129, 1.0
	v_max_f32_e32 v137, 0, v137
	v_mul_f32_e32 v124, v124, v128
	v_max_f32_e32 v118, 0, v118
	v_pk_mul_f32 v[122:123], v[144:145], v[122:123]
	v_mul_f32_e32 v114, 0xbfb8aa3b, v114
	v_exp_f32_e32 v114, v114
	s_nop 0
	v_add_f32_e32 v114, 1.0, v114
	v_rcp_f32_e32 v163, v114
	v_add_f32_e32 v119, v119, v156
	v_mul_f32_e32 v119, 0xbfb8aa3b, v119
	v_exp_f32_e32 v119, v119
	v_sqrt_f32_e32 v128, v137
	s_nop 0
	v_mul_f32_e32 v144, v125, v128
	v_add_f32_e32 v119, 1.0, v119
	ds_read2_b32 v[158:159], v241 offset0:32 offset1:48
	ds_read2_b32 v[170:171], v241 offset0:100 offset1:116
	v_add_f32_e32 v121, v121, v156
	v_mul_f32_e32 v121, 0xbfb8aa3b, v121
	v_exp_f32_e32 v121, v121
	s_nop 0
	v_add_f32_e32 v121, 1.0, v121
	v_rcp_f32_e32 v121, v121
	v_rcp_f32_e32 v125, v119
	v_add_f32_e32 v110, v110, v157
	v_mul_f32_e32 v110, 0xbfb8aa3b, v110
	v_sqrt_f32_e32 v114, v118
	s_nop 0
	v_cndmask_b32_e64 v119, v114, 1.0, vcc
	v_mul_f32_e32 v114, 0xc1000000, v125
	v_mul_f32_e32 v114, v152, v114
	v_mul_f32_e32 v114, 0x3fb8aa3b, v114
	v_exp_f32_e32 v151, v114
	v_add_f32_e32 v114, v115, v154
	v_mul_f32_e32 v114, 0xbfb8aa3b, v114
	v_exp_f32_e32 v114, v114
	v_fma_f32 v115, -v151, v151, 1.0
	v_max_f32_e32 v115, 0, v115
	v_add_f32_e32 v114, 1.0, v114
	v_rcp_f32_e32 v162, v114
	v_exp_f32_e32 v110, v110
	v_add_f32_e32 v106, v106, v155
	v_mul_f32_e32 v106, 0xbfb8aa3b, v106
	v_add_f32_e32 v110, 1.0, v110
	v_rcp_f32_e32 v110, v110
	v_exp_f32_e32 v106, v106
	v_add_f32_e32 v118, v120, v156
	v_mul_f32_e32 v118, 0xbfb8aa3b, v118
	v_exp_f32_e32 v120, v118
	v_mul_f32_e32 v110, 0xc1000000, v110
	v_mul_f32_e32 v110, v153, v110
	v_sqrt_f32_e32 v118, v115
	s_nop 0
	v_pk_mul_f32 v[114:115], v[162:163], v[118:119]
	v_add_f32_e32 v118, 1.0, v120
	v_rcp_f32_e32 v120, v118
	s_waitcnt lgkmcnt(0)
	v_mov_b32_e32 v118, v170
	v_mov_b32_e32 v119, v158
	v_pk_mul_f32 v[118:119], v[118:119], v[114:115]
	v_mul_f32_e32 v114, 0xc1000000, v120
	v_mul_f32_e32 v114, v152, v114
	v_mul_f32_e32 v114, 0x3fb8aa3b, v114
	v_exp_f32_e32 v147, v114
	v_add_f32_e32 v114, v116, v154
	v_mul_f32_e32 v114, 0xbfb8aa3b, v114
	v_exp_f32_e32 v116, v114
	v_fma_f32 v114, -v147, v147, 1.0
	v_max_f32_e32 v114, 0, v114
	v_add_f32_e32 v116, 1.0, v116
	v_rcp_f32_e32 v116, v116
	v_mov_b32_e32 v120, v114
	v_mul_f32_e32 v110, 0x3fb8aa3b, v110
	v_exp_f32_e32 v162, v110
	v_add_f32_e32 v111, v111, v157
	v_fma_f32 v110, -v162, v162, 1.0
	v_max_f32_e32 v110, 0, v110
	v_mul_f32_e32 v111, 0xbfb8aa3b, v111
	v_add_f32_e32 v106, 1.0, v106
	v_exp_f32_e32 v111, v111
	v_sqrt_f32_e32 v120, v120
	s_nop 0
	v_mul_f32_e32 v120, v116, v120
	v_mul_f32_e32 v116, 0xc1000000, v121
	v_mul_f32_e32 v116, v152, v116
	v_mul_f32_e32 v116, 0x3fb8aa3b, v116
	v_exp_f32_e32 v149, v116
	v_add_f32_e32 v116, v117, v154
	v_mul_f32_e32 v116, 0xbfb8aa3b, v116
	v_exp_f32_e32 v121, v116
	v_fma_f32 v116, -v149, v149, 1.0
	v_max_f32_e32 v116, 0, v116
	v_add_f32_e32 v121, 1.0, v121
	v_rcp_f32_e32 v121, v121
	v_mov_b32_e32 v125, v116
	v_rcp_f32_e32 v173, v106
	v_add_f32_e32 v111, 1.0, v111
	v_rcp_f32_e32 v111, v111
	v_add_f32_e32 v107, v107, v155
	v_mul_f32_e32 v107, 0xbfb8aa3b, v107
	v_add_f32_e32 v112, v112, v157
	v_mul_f32_e32 v112, 0xbfb8aa3b, v112
	v_exp_f32_e32 v112, v112
	v_sqrt_f32_e32 v125, v125
	s_nop 0
	v_mul_f32_e32 v150, v121, v125
	v_add_f32_e32 v113, v113, v157
	v_mul_f32_e32 v113, 0xbfb8aa3b, v113
	v_exp_f32_e32 v113, v113
	v_add_f32_e32 v108, v108, v155
	v_add_f32_e32 v113, 1.0, v113
	v_rcp_f32_e32 v113, v113
	s_nop 0
	v_mul_f32_e32 v113, 0xc1000000, v113
	v_mul_f32_e32 v113, v153, v113
	v_sqrt_f32_e32 v106, v110
	s_nop 0
	v_mul_f32_e32 v110, 0xc1000000, v111
	v_mul_f32_e32 v110, v153, v110
	v_mul_f32_e32 v110, 0x3fb8aa3b, v110
	v_exp_f32_e32 v110, v110
	v_exp_f32_e32 v111, v107
	v_mul_f32_e32 v113, 0x3fb8aa3b, v113
	v_exp_f32_e32 v113, v113
	v_fma_f32 v107, -v110, v110, 1.0
	v_max_f32_e32 v107, 0, v107
	v_add_f32_e32 v102, v102, v168
	v_mul_f32_e32 v108, 0xbfb8aa3b, v108
	v_mov_b32_e32 v121, v107
	v_cndmask_b32_e64 v107, v106, 1.0, vcc
	v_add_f32_e32 v106, 1.0, v111
	v_rcp_f32_e32 v172, v106
	v_mul_f32_e32 v102, 0xbfb8aa3b, v102
	v_exp_f32_e32 v108, v108
	v_exp_f32_e32 v102, v102
	v_add_f32_e32 v111, 1.0, v112
	v_rcp_f32_e32 v111, v111
	v_add_f32_e32 v108, 1.0, v108
	v_add_f32_e32 v102, 1.0, v102
	v_mul_f32_e32 v111, 0xc1000000, v111
	v_mul_f32_e32 v111, v153, v111
	v_mul_f32_e32 v111, 0x3fb8aa3b, v111
	v_exp_f32_e32 v111, v111
	v_sqrt_f32_e32 v106, v121
	s_nop 0
	v_rcp_f32_e32 v108, v108
	v_rcp_f32_e32 v102, v102
	v_fma_f32 v112, -v111, v111, 1.0
	v_max_f32_e32 v112, 0, v112
	v_add_f32_e32 v109, v109, v155
	v_mul_f32_e32 v109, 0xbfb8aa3b, v109
	v_exp_f32_e32 v109, v109
	v_mul_f32_e32 v102, 0xc1000000, v102
	v_mul_f32_e32 v102, v164, v102
	v_mul_f32_e32 v102, 0x3fb8aa3b, v102
	v_exp_f32_e32 v178, v102
	v_add_f32_e32 v103, v103, v168
	v_add_f32_e32 v109, 1.0, v109
	v_mul_f32_e32 v103, 0xbfb8aa3b, v103
	v_sqrt_f32_e32 v112, v112
	s_nop 0
	v_fma_f32 v121, -v113, v113, 1.0
	v_max_f32_e32 v121, 0, v121
	v_mul_f32_e32 v108, v108, v112
	v_rcp_f32_e32 v109, v109
	v_exp_f32_e32 v103, v103
	v_fma_f32 v102, -v178, v178, 1.0
	v_pk_mul_f32 v[106:107], v[172:173], v[106:107]
	v_mov_b32_e32 v158, v171
	v_max_f32_e32 v102, 0, v102
	v_pk_mul_f32 v[106:107], v[158:159], v[106:107]
	v_add_f32_e32 v103, 1.0, v103
	v_rcp_f32_e32 v103, v103
	v_sqrt_f32_e32 v112, v121
	s_nop 0
	v_mul_f32_e32 v158, v109, v112
	v_mul_f32_e32 v103, 0xc1000000, v103
	v_mul_f32_e32 v103, v164, v103
	v_mul_f32_e32 v103, 0x3fb8aa3b, v103
	v_exp_f32_e32 v179, v103
	v_add_f32_e32 v98, v98, v166
	v_fma_f32 v103, -v179, v179, 1.0
	v_max_f32_e32 v103, 0, v103
	v_add_f32_e32 v99, v99, v166
	v_mul_f32_e32 v98, 0xbfb8aa3b, v98
	v_mul_f32_e32 v99, 0xbfb8aa3b, v99
	v_sqrt_f32_e32 v102, v102
	s_nop 0
	v_exp_f32_e32 v98, v98
	v_exp_f32_e32 v99, v99
	v_add_f32_e32 v104, v104, v168
	v_add_f32_e32 v98, 1.0, v98
	v_add_f32_e32 v99, 1.0, v99
	v_mul_f32_e32 v104, 0xbfb8aa3b, v104
	v_rcp_f32_e32 v98, v98
	v_rcp_f32_e32 v99, v99
	v_exp_f32_e32 v104, v104
	v_add_u32_e32 v109, 0x1000, v241
	ds_read2_b32 v[170:171], v109 offset0:64 offset1:80
	ds_read2_b32 v[172:173], v109 offset0:132 offset1:148
	v_sqrt_f32_e32 v103, v103
	s_nop 0
	v_pk_mul_f32 v[98:99], v[98:99], v[102:103]
	v_add_f32_e32 v102, 1.0, v104
	v_rcp_f32_e32 v104, v102
	s_waitcnt lgkmcnt(1)
; #define LAS __attribute__((address_space(3)))
; __device__ __forceinline__ float sigmoidf_(float x) { return __builtin_amdgcn_rcpf(1.0f + __expf(-x)); }
; template <int NT> ...
;     ...
;     for (int u = 0; u < NT; ++u) { const LAS float* XC = XCb + u * (16 * 68); const int t0 = m0 + 16 * u - b * TP;
; #pragma unroll
;         for (int n = 0; n < 4; ++n) { const int cc = 16 * n + fr;
;             const float ba = CST[5 * 64 + cc], bx = CST[6 * 64 + cc], sp = CST[7 * 64 + cc];
; #pragma unroll
;             for (int j = 0; j < 4; ++j) {
;                 const float xc = XC[(4 * fq + j) * 68 + cc];
;                 const float r = sigmoidf_(ar[u][n][j] + ba), ig = sigmoidf_(ai[u][n][j] + bx);
;                 const float a = __expf(-8.0f * r * sp);
;                 float mult = sqrtf(fmaxf(1.0f - a * a, 0.f));
;                 if (t0 + 4 * fq + j == 0) mult = 1.0f;
;                 av[u][n][j] = a; bv[u][n][j] = mult * ig * xc; } } }
	v_mov_b32_e32 v102, v170
	s_waitcnt lgkmcnt(0)
	v_mov_b32_e32 v103, v172
	v_pk_mul_f32 v[102:103], v[98:99], v[102:103]
	v_mul_f32_e32 v98, 0xc1000000, v104
	v_mul_f32_e32 v98, v164, v98
	v_mul_f32_e32 v98, 0x3fb8aa3b, v98
	v_exp_f32_e32 v161, v98
	v_add_f32_e32 v98, v100, v166
	v_mul_f32_e32 v98, 0xbfb8aa3b, v98
	v_exp_f32_e32 v100, v98
	v_fma_f32 v98, -v161, v161, 1.0
	v_max_f32_e32 v98, 0, v98
	v_add_f32_e32 v105, v105, v168
	v_mul_f32_e32 v105, 0xbfb8aa3b, v105
	v_mov_b32_e32 v104, v98
	v_exp_f32_e32 v105, v105
	v_add_f32_e32 v100, 1.0, v100
	v_rcp_f32_e32 v100, v100
	v_add_f32_e32 v105, 1.0, v105
	v_rcp_f32_e32 v105, v105
	v_add_f32_e32 v94, v94, v169
	v_mul_f32_e32 v94, 0xbfb8aa3b, v94
	v_exp_f32_e32 v94, v94
	v_sqrt_f32_e32 v104, v104
	s_nop 0
	v_mul_f32_e32 v104, v100, v104
	v_mul_f32_e32 v100, 0xc1000000, v105
	v_mul_f32_e32 v100, v164, v100
	v_mul_f32_e32 v100, 0x3fb8aa3b, v100
	v_exp_f32_e32 v163, v100
	v_add_f32_e32 v100, v101, v166
	v_mul_f32_e32 v100, 0xbfb8aa3b, v100
	v_exp_f32_e32 v105, v100
	v_fma_f32 v100, -v163, v163, 1.0
	v_max_f32_e32 v100, 0, v100
	v_add_f32_e32 v94, 1.0, v94
	v_rcp_f32_e32 v94, v94
	v_mov_b32_e32 v121, v100
	v_add_f32_e32 v105, 1.0, v105
	v_mul_f32_e32 v94, 0xc1000000, v94
	v_mul_f32_e32 v94, v165, v94
	v_mul_f32_e32 v94, 0x3fb8aa3b, v94
	v_exp_f32_e32 v168, v94
	s_nop 0
	v_fma_f32 v94, -v168, v168, 1.0
	v_max_f32_e32 v94, 0, v94
	v_rcp_f32_e32 v105, v105
	v_add_f32_e32 v95, v95, v169
	v_sqrt_f32_e32 v121, v121
	s_nop 0
	v_mul_f32_e32 v125, 0x4f800000, v94
	v_cmp_gt_f32_e32 vcc, s47, v94
	v_mul_f32_e32 v95, 0xbfb8aa3b, v95
	v_exp_f32_e32 v95, v95
	v_cndmask_b32_e32 v125, v94, v125, vcc
	v_sqrt_f32_e32 v94, v125
	v_mul_f32_e32 v164, v105, v121
	v_add_f32_e32 v95, 1.0, v95
	v_rcp_f32_e32 v95, v95
	v_add_u32_e32 v105, -1, v94
	v_fma_f32 v121, -v105, v94, v125
	v_cmp_ge_f32_e64 s[10:11], 0, v121
	v_add_u32_e32 v121, 1, v94
	v_add_f32_e32 v96, v96, v169
	v_cndmask_b32_e64 v105, v94, v105, s[10:11]
	v_fma_f32 v94, -v121, v94, v125
	v_cmp_lt_f32_e64 s[10:11], 0, v94
	v_mul_f32_e32 v96, 0xbfb8aa3b, v96
	v_exp_f32_e32 v96, v96
	v_cndmask_b32_e64 v94, v105, v121, s[10:11]
	v_mul_f32_e32 v105, 0x37800000, v94
	v_cndmask_b32_e32 v105, v94, v105, vcc
	v_mul_f32_e32 v94, 0xc1000000, v95
	v_mul_f32_e32 v94, v165, v94
	v_mul_f32_e32 v94, 0x3fb8aa3b, v94
	v_exp_f32_e32 v94, v94
	v_cmp_class_f32_e64 s[10:11], v125, v219
	v_add_f32_e32 v96, 1.0, v96
	v_rcp_f32_e32 v96, v96
	v_fma_f32 v95, -v94, v94, 1.0
	v_max_f32_e32 v95, 0, v95
	v_cndmask_b32_e64 v174, v105, v125, s[10:11]
	v_add_f32_e32 v97, v97, v169
	v_mul_f32_e32 v97, 0xbfb8aa3b, v97
	v_exp_f32_e32 v97, v97
	v_add_f32_e32 v92, v92, v167
	v_add_f32_e32 v97, 1.0, v97
	v_rcp_f32_e32 v97, v97
	v_add_f32_e32 v86, v86, v156
	v_mul_f32_e32 v97, 0xc1000000, v97
	v_mul_f32_e32 v97, v165, v97
	v_sqrt_f32_e32 v175, v95
	s_nop 0
	v_mul_f32_e32 v95, 0xc1000000, v96
	v_mul_f32_e32 v95, v165, v95
	v_mul_f32_e32 v95, 0x3fb8aa3b, v95
	v_exp_f32_e32 v95, v95
	v_mul_f32_e32 v97, 0x3fb8aa3b, v97
	v_exp_f32_e32 v97, v97
	v_mul_f32_e32 v92, 0xbfb8aa3b, v92
	v_fma_f32 v96, -v95, v95, 1.0
	v_max_f32_e32 v96, 0, v96
	v_mul_f32_e32 v86, 0xbfb8aa3b, v86
	v_exp_f32_e32 v92, v92
	v_exp_f32_e32 v86, v86
	v_add_f32_e32 v92, 1.0, v92
	v_rcp_f32_e32 v92, v92
	v_add_f32_e32 v86, 1.0, v86
	v_rcp_f32_e32 v86, v86
	v_add_f32_e32 v93, v93, v167
	v_mul_f32_e32 v93, 0xbfb8aa3b, v93
	v_exp_f32_e32 v93, v93
	v_sqrt_f32_e32 v96, v96
	s_nop 0
	v_fma_f32 v105, -v97, v97, 1.0
	v_max_f32_e32 v105, 0, v105
	v_mul_f32_e32 v92, v92, v96
	v_mul_f32_e32 v86, 0xc1000000, v86
	v_mul_f32_e32 v86, v152, v86
	v_mul_f32_e32 v86, 0x3fb8aa3b, v86
	v_exp_f32_e32 v180, v86
	v_add_f32_e32 v87, v87, v156
	v_add_f32_e32 v93, 1.0, v93
	v_mul_f32_e32 v87, 0xbfb8aa3b, v87
	v_rcp_f32_e32 v93, v93
	v_exp_f32_e32 v87, v87
	v_fma_f32 v86, -v180, v180, 1.0
	v_max_f32_e32 v86, 0, v86
	v_sqrt_f32_e32 v96, v105
	s_nop 0
	v_mul_f32_e32 v166, v93, v96
	v_add_f32_e32 v87, 1.0, v87
	v_rcp_f32_e32 v87, v87
	v_add_f32_e32 v90, v90, v167
	v_mul_f32_e32 v87, 0xc1000000, v87
	v_mul_f32_e32 v87, v152, v87
	v_mul_f32_e32 v87, 0x3fb8aa3b, v87
	v_exp_f32_e32 v170, v87
	s_nop 0
	v_fma_f32 v87, -v170, v170, 1.0
	v_max_f32_e32 v87, 0, v87
	v_add_f32_e32 v91, v91, v167
	v_mul_f32_e32 v90, 0xbfb8aa3b, v90
	v_sqrt_f32_e32 v86, v86
	s_nop 0
	v_mul_f32_e32 v91, 0xbfb8aa3b, v91
	v_exp_f32_e32 v90, v90
	v_exp_f32_e32 v91, v91
	v_add_f32_e32 v82, v82, v154
	v_add_f32_e32 v83, v83, v154
	v_mul_f32_e32 v82, 0xbfb8aa3b, v82
	v_mul_f32_e32 v83, 0xbfb8aa3b, v83
	v_exp_f32_e32 v82, v82
	v_exp_f32_e32 v83, v83
	v_add_f32_e32 v90, 1.0, v90
	v_add_f32_e32 v91, 1.0, v91
	v_rcp_f32_e32 v90, v90
	v_rcp_f32_e32 v91, v91
	v_add_f32_e32 v88, v88, v156
	v_add_f32_e32 v82, 1.0, v82
	v_add_f32_e32 v83, 1.0, v83
	v_mul_f32_e32 v88, 0xbfb8aa3b, v88
	v_rcp_f32_e32 v82, v82
	v_rcp_f32_e32 v83, v83
	v_exp_f32_e32 v88, v88
	v_pk_mul_f32 v[90:91], v[90:91], v[174:175]
	v_mov_b32_e32 v172, v171
	v_pk_mul_f32 v[90:91], v[90:91], v[172:173]
	ds_read2_b32 v[172:173], v109 offset0:96 offset1:112
	ds_read2_b32 v[174:175], v109 offset0:164 offset1:180
	v_sqrt_f32_e32 v87, v87
	s_nop 0
	v_pk_mul_f32 v[82:83], v[82:83], v[86:87]
	v_add_f32_e32 v86, 1.0, v88
	v_rcp_f32_e32 v88, v86
	s_waitcnt lgkmcnt(1)
	v_mov_b32_e32 v86, v172
	s_waitcnt lgkmcnt(0)
; #define LAS __attribute__((address_space(3)))
; __device__ __forceinline__ float sigmoidf_(float x) { return __builtin_amdgcn_rcpf(1.0f + __expf(-x)); }
; template <int NT> ...
;     ...
;     for (int u = 0; u < NT; ++u) { const LAS float* XC = XCb + u * (16 * 68); const int t0 = m0 + 16 * u - b * TP;
; #pragma unroll
;         for (int n = 0; n < 4; ++n) { const int cc = 16 * n + fr;
;             const float ba = CST[5 * 64 + cc], bx = CST[6 * 64 + cc], sp = CST[7 * 64 + cc];
; #pragma unroll
;             for (int j = 0; j < 4; ++j) {
;                 const float xc = XC[(4 * fq + j) * 68 + cc];
;                 const float r = sigmoidf_(ar[u][n][j] + ba), ig = sigmoidf_(ai[u][n][j] + bx);
;                 const float a = __expf(-8.0f * r * sp);
;                 float mult = sqrtf(fmaxf(1.0f - a * a, 0.f));
;                 if (t0 + 4 * fq + j == 0) mult = 1.0f;
;                 av[u][n][j] = a; bv[u][n][j] = mult * ig * xc; } } }
; #pragma unroll
;     for (int u = 0; u < NT; ++u) {
; #pragma unroll
;         for (int n = 0; n < 4; ++n) { const int ch = hc0 + 16 * n + fr;
;             float hl[4], pl[4];
;             hl[0] = bv[u][n][0]; pl[0] = av[u][n][0];
; #pragma unroll
;             for (int j = 1; j < 4; ++j) { hl[j] = av[u][n][j] * hl[j - 1] + bv[u][n][j]; pl[j] = av[u][n][j] * pl[j - 1]; }
;             float He = 0.f, Pe = 1.f;
; #pragma unroll
;             for (int g = 0; g < 3; ++g) { const float Pg = __shfl(pl[3], fr + 16 * g), Hg = __shfl(hl[3], fr + 16 * g); if (g < fq) { He = Pg * He + Hg; Pe = Pg * Pe; } }
;             const float Hin = Pe * Hc[n] + He, Pin = Pe * Pc[n];
	v_mov_b32_e32 v87, v174
	v_pk_mul_f32 v[86:87], v[82:83], v[86:87]
	v_mul_f32_e32 v82, 0xc1000000, v88
	v_mul_f32_e32 v82, v152, v82
	v_mul_f32_e32 v82, 0x3fb8aa3b, v82
	v_exp_f32_e32 v169, v82
	v_add_f32_e32 v82, v84, v154
	v_mul_f32_e32 v82, 0xbfb8aa3b, v82
	v_exp_f32_e32 v84, v82
	v_fma_f32 v82, -v169, v169, 1.0
	v_max_f32_e32 v82, 0, v82
	v_add_f32_e32 v89, v89, v156
	v_mul_f32_e32 v89, 0xbfb8aa3b, v89
	v_mov_b32_e32 v88, v82
	v_exp_f32_e32 v89, v89
	v_add_f32_e32 v84, 1.0, v84
	v_rcp_f32_e32 v84, v84
	v_add_f32_e32 v89, 1.0, v89
	v_rcp_f32_e32 v89, v89
	v_add_f32_e32 v78, v78, v157
	v_mul_f32_e32 v78, 0xbfb8aa3b, v78
	v_exp_f32_e32 v78, v78
	v_sqrt_f32_e32 v88, v88
	s_nop 0
	v_mul_f32_e32 v88, v84, v88
	v_mul_f32_e32 v84, 0xc1000000, v89
	v_mul_f32_e32 v84, v152, v84
	v_mul_f32_e32 v84, 0x3fb8aa3b, v84
	v_exp_f32_e32 v171, v84
	v_add_f32_e32 v84, v85, v154
	v_mul_f32_e32 v84, 0xbfb8aa3b, v84
	v_exp_f32_e32 v89, v84
	v_fma_f32 v84, -v171, v171, 1.0
	v_max_f32_e32 v84, 0, v84
	v_add_f32_e32 v78, 1.0, v78
	v_rcp_f32_e32 v78, v78
	v_mov_b32_e32 v93, v84
	ds_read2_b32 v[98:99], v109 offset0:200 offset1:216
	v_mul_f32_e32 v78, 0xc1000000, v78
	v_mul_f32_e32 v78, v153, v78
	ds_read2_b32 v[82:83], v109 offset0:232 offset1:248
	v_mul_f32_e32 v78, 0x3fb8aa3b, v78
	v_add_f32_e32 v79, v79, v157
	v_exp_f32_e32 v152, v78
	v_mul_f32_e32 v79, 0xbfb8aa3b, v79
	v_exp_f32_e32 v79, v79
	v_add_f32_e32 v74, v74, v155
	v_mul_f32_e32 v74, 0xbfb8aa3b, v74
	v_exp_f32_e32 v78, v74
	v_fma_f32 v74, -v152, v152, 1.0
	v_max_f32_e32 v74, 0, v74
	v_add_f32_e32 v79, 1.0, v79
	v_sqrt_f32_e32 v93, v93
	s_nop 0
	v_mul_f32_e32 v96, 0x4f800000, v74
	v_cmp_gt_f32_e32 vcc, s47, v74
	v_rcp_f32_e32 v79, v79
	v_add_f32_e32 v89, 1.0, v89
	v_cndmask_b32_e32 v96, v74, v96, vcc
	v_rcp_f32_e32 v89, v89
	v_sqrt_f32_e32 v105, v96
	v_mul_f32_e32 v79, 0xc1000000, v79
	v_mul_f32_e32 v79, v153, v79
	v_mul_f32_e32 v74, v89, v93
	v_add_u32_e32 v89, -1, v105
	v_mul_f32_e32 v79, 0x3fb8aa3b, v79
	v_fma_f32 v93, -v89, v105, v96
	v_exp_f32_e32 v154, v79
	v_cmp_ge_f32_e64 s[10:11], 0, v93
	v_add_u32_e32 v93, 1, v105
	v_add_f32_e32 v75, v75, v155
	v_cndmask_b32_e64 v89, v105, v89, s[10:11]
	v_fma_f32 v105, -v93, v105, v96
	v_cmp_lt_f32_e64 s[10:11], 0, v105
	v_fma_f32 v79, -v154, v154, 1.0
	v_max_f32_e32 v79, 0, v79
	v_cndmask_b32_e64 v89, v89, v93, s[10:11]
	v_mul_f32_e32 v93, 0x37800000, v89
	v_cndmask_b32_e32 v89, v89, v93, vcc
	v_mul_f32_e32 v75, 0xbfb8aa3b, v75
	v_exp_f32_e32 v75, v75
	v_add_f32_e32 v80, v80, v157
	v_mov_b32_e32 v93, v79
	v_mul_f32_e32 v80, 0xbfb8aa3b, v80
	v_add_f32_e32 v75, 1.0, v75
	v_exp_f32_e32 v80, v80
	v_cmp_class_f32_e64 s[10:11], v96, v219
	v_rcp_f32_e32 v79, v75
	v_cndmask_b32_e64 v182, v89, v96, s[10:11]
	v_add_f32_e32 v80, 1.0, v80
	v_rcp_f32_e32 v80, v80
	v_mov_b32_e32 v174, v173
	v_add_f32_e32 v81, v81, v157
	v_mul_f32_e32 v81, 0xbfb8aa3b, v81
	v_sqrt_f32_e32 v183, v93
	s_nop 0
	v_mul_f32_e32 v75, 0xc1000000, v80
	v_mul_f32_e32 v75, v153, v75
	v_mul_f32_e32 v75, 0x3fb8aa3b, v75
	v_exp_f32_e32 v173, v75
	v_add_f32_e32 v75, v76, v155
	v_exp_f32_e32 v81, v81
	v_mul_f32_e32 v75, 0xbfb8aa3b, v75
	v_fma_f32 v76, -v173, v173, 1.0
	v_max_f32_e32 v76, 0, v76
	v_add_f32_e32 v81, 1.0, v81
	v_rcp_f32_e32 v81, v81
	v_exp_f32_e32 v75, v75
	v_add_f32_e32 v77, v77, v155
	v_mul_f32_e32 v77, 0xbfb8aa3b, v77
	v_add_f32_e32 v75, 1.0, v75
	v_rcp_f32_e32 v75, v75
	v_exp_f32_e32 v77, v77
	ds_read2_b32 v[130:131], v241 offset0:136 offset1:152
	ds_read2_b32 v[134:135], v241 offset0:204 offset1:220
	v_sqrt_f32_e32 v76, v76
	s_nop 0
	v_mul_f32_e32 v80, 0xc1000000, v81
	v_mul_f32_e32 v80, v153, v80
	v_mul_f32_e32 v80, 0x3fb8aa3b, v80
	v_exp_f32_e32 v81, v80
	v_mul_f32_e32 v76, v75, v76
	v_add_f32_e32 v75, 1.0, v77
	v_fma_f32 v137, v138, v133, v132
	v_fma_f32 v80, -v81, v81, 1.0
	v_max_f32_e32 v80, 0, v80
	s_waitcnt lgkmcnt(0)
	v_mov_b32_e32 v140, v134
	v_rcp_f32_e32 v75, v75
	v_add_u32_e32 v112, 0x1400, v241
	ds_read2_b32 v[100:101], v112 offset0:12 offset1:28
	ds_read2_b32 v[84:85], v112 offset0:44 offset1:60
	ds_read2_b32 v[114:115], v241 offset0:168 offset1:184
	ds_read2_b32 v[116:117], v241 offset0:236 offset1:252
	v_add_f32_e32 v78, 1.0, v78
	v_mul_f32_e32 v93, v138, v146
	v_mov_b32_e32 v138, v130
	v_sqrt_f32_e32 v77, v80
	s_nop 0
	v_mul_f32_e32 v80, v139, v137
	v_pk_fma_f32 v[156:157], v[138:139], v[136:137], v[80:81] op_sel_hi:[1,1,0]
	v_and_or_b32 v89, v207, 64, v223
	v_mov_b32_e32 v143, v156
	v_mul_f32_e32 v80, v139, v93
	v_pk_mul_f32 v[138:139], v[140:141], v[142:143]
	v_mul_f32_e32 v105, v141, v80
	v_add_f32_e32 v96, v138, v139
	v_lshlrev_b32_e32 v134, 2, v89
	ds_bpermute_b32 v89, v134, v105
	ds_bpermute_b32 v109, v134, v96
	v_mul_f32_e32 v130, v75, v77
	ds_bpermute_b32 v75, v134, v105 offset:64
	ds_bpermute_b32 v77, v134, v96 offset:64
	ds_bpermute_b32 v112, v134, v105 offset:128
	ds_bpermute_b32 v121, v134, v96 offset:128
	s_waitcnt lgkmcnt(4)
	v_fmac_f32_e32 v109, 0, v89
	v_cndmask_b32_e64 v109, v109, 0, s[8:9]
	v_cndmask_b32_e64 v89, v89, 1.0, s[8:9]
	s_waitcnt lgkmcnt(2)
	v_fmac_f32_e32 v77, v109, v75
	v_mul_f32_e32 v75, v89, v75
	v_cndmask_b32_e64 v77, v109, v77, s[4:5]
	v_cndmask_b32_e64 v75, v89, v75, s[4:5]
	v_add_u32_e32 v138, s19, v242
	s_waitcnt lgkmcnt(0)
; __device__ __forceinline__ unsigned cvt_pk_bf16(float lo, float hi) { unsigned r; asm volatile("v_cvt_pk_bf16_f32 %0, %1, %2" : "=v"(r) : "v"(lo), "v"(hi)); return r; }
; template <int NT> ...
;     ...
;             hl[0] = bv[u][n][0]; pl[0] = av[u][n][0];
; #pragma unroll
;             for (int j = 1; j < 4; ++j) { hl[j] = av[u][n][j] * hl[j - 1] + bv[u][n][j]; pl[j] = av[u][n][j] * pl[j - 1]; }
;             float He = 0.f, Pe = 1.f;
; #pragma unroll
;             for (int g = 0; g < 3; ++g) { const float Pg = __shfl(pl[3], fr + 16 * g), Hg = __shfl(hl[3], fr + 16 * g); if (g < fq) { He = Pg * He + Hg; Pe = Pg * Pe; } }
;             const float Hin = Pe * Hc[n] + He, Pin = Pe * Pc[n];
;             float hf[4], pf[4];
; #pragma unroll
;             for (int j = 0; j < 4; ++j) { hf[j] = hl[j] + pl[j] * Hin; pf[j] = pl[j] * Pin; }
; #pragma unroll
;             for (int j = 0; j < 4; ++j) { const size_t o = (size_t)(m0 + 16 * u + 4 * fq + j) * D + ch; HLOC[o] = (bf16_t)(cvt_pk_bf16(hf[j], 0.f) & 0xffffu); PCUM[o] = (bf16_t)(cvt_pk_bf16(pf[j], 0.f) & 0xffffu); }
;             Hc[n] = __shfl(hf[3], fr + 48); Pc[n] = __shfl(pf[3], fr + 48);
	v_fmac_f32_e32 v121, v77, v112
	v_mul_f32_e32 v89, v75, v112
	v_ashrrev_i32_e32 v139, 31, v138
	v_cndmask_b32_e64 v77, v77, v121, s[6:7]
	v_cndmask_b32_e64 v75, v75, v89, s[6:7]
	v_lshlrev_b64 v[140:141], 10, v[138:139]
	v_fmac_f32_e32 v77, v70, v75
	v_mul_f32_e32 v70, v72, v75
	v_fmac_f32_e32 v133, v146, v77
	v_or_b32_e32 v142, v140, v208
	v_mov_b32_e32 v143, v141
	v_mul_f32_e32 v72, v146, v70
	v_fmac_f32_e32 v137, v93, v77
	v_mul_f32_e32 v75, v93, v70
	v_fmac_f32_e32 v156, v80, v77
	v_mul_f32_e32 v80, v80, v70
	v_fmac_f32_e32 v96, v105, v77
	v_mul_f32_e32 v77, v105, v70
	v_cvt_pk_bf16_f32 v70, v133, v1
	v_lshlrev_b64 v[132:133], 1, v[142:143]
	v_lshl_add_u64 v[142:143], s[62:63], 0, v[132:133]
	v_lshl_add_u64 v[132:133], s[64:65], 0, v[132:133]
	global_store_short v[142:143], v70, off
	v_cvt_pk_bf16_f32 v70, v72, v1
	global_store_short v[132:133], v70, off
	v_add_u32_e32 v132, 1, v138
	v_ashrrev_i32_e32 v133, 31, v132
	v_lshlrev_b64 v[132:133], 10, v[132:133]
	v_or_b32_e32 v142, v132, v208
	v_mov_b32_e32 v143, v133
	v_cvt_pk_bf16_f32 v70, v137, v1
	v_lshlrev_b64 v[136:137], 1, v[142:143]
	v_lshl_add_u64 v[142:143], s[62:63], 0, v[136:137]
	v_lshl_add_u64 v[136:137], s[64:65], 0, v[136:137]
	global_store_short v[142:143], v70, off
	v_cvt_pk_bf16_f32 v70, v75, v1
	global_store_short v[136:137], v70, off
	v_add_u32_e32 v136, 2, v138
	v_ashrrev_i32_e32 v137, 31, v136
	v_lshlrev_b64 v[136:137], 10, v[136:137]
	v_or_b32_e32 v142, v136, v208
	v_mov_b32_e32 v143, v137
	v_lshlrev_b64 v[142:143], 1, v[142:143]
	v_cvt_pk_bf16_f32 v70, v156, v1
	v_lshl_add_u64 v[156:157], s[62:63], 0, v[142:143]
	v_lshl_add_u64 v[142:143], s[64:65], 0, v[142:143]
	v_rcp_f32_e32 v78, v78
	global_store_short v[156:157], v70, off
	v_cvt_pk_bf16_f32 v70, v80, v1
	global_store_short v[142:143], v70, off
	v_add_u32_e32 v142, 3, v138
	v_ashrrev_i32_e32 v143, 31, v142
	v_lshlrev_b64 v[142:143], 10, v[142:143]
	v_or_b32_e32 v156, v142, v208
	v_mov_b32_e32 v157, v143
	v_pk_mul_f32 v[78:79], v[78:79], v[182:183]
	v_lshlrev_b64 v[156:157], 1, v[156:157]
	v_pk_mul_f32 v[78:79], v[78:79], v[174:175]
	v_cvt_pk_bf16_f32 v70, v96, v1
	v_lshl_add_u64 v[174:175], s[62:63], 0, v[156:157]
	v_fma_f32 v125, v126, v123, v122
	global_store_short v[174:175], v70, off
	v_mul_f32_e32 v75, v126, v148
	v_mov_b32_e32 v126, v131
	v_mul_f32_e32 v70, v127, v125
	v_pk_fma_f32 v[174:175], v[126:127], v[124:125], v[70:71] op_sel_hi:[1,1,0]
	v_mov_b32_e32 v128, v135
	v_mov_b32_e32 v145, v174
	v_mul_f32_e32 v70, v127, v75
	v_pk_mul_f32 v[126:127], v[128:129], v[144:145]
	v_mul_f32_e32 v89, v129, v70
	v_add_f32_e32 v80, v126, v127
	ds_bpermute_b32 v93, v134, v89
	ds_bpermute_b32 v105, v134, v80
	v_cvt_pk_bf16_f32 v72, v77, v1
	v_lshl_add_u64 v[126:127], s[64:65], 0, v[156:157]
	global_store_short v[126:127], v72, off
	ds_bpermute_b32 v72, v134, v89 offset:64
	ds_bpermute_b32 v109, v134, v80 offset:64
	ds_bpermute_b32 v112, v134, v89 offset:128
	ds_bpermute_b32 v121, v134, v80 offset:128
	s_waitcnt lgkmcnt(4)
	v_fmac_f32_e32 v105, 0, v93
	v_cndmask_b32_e64 v105, v105, 0, s[8:9]
	v_cndmask_b32_e64 v93, v93, 1.0, s[8:9]
	s_waitcnt lgkmcnt(2)
	v_fmac_f32_e32 v109, v105, v72
	v_mul_f32_e32 v72, v93, v72
	v_cndmask_b32_e64 v105, v105, v109, s[4:5]
	v_cndmask_b32_e64 v72, v93, v72, s[4:5]
	s_waitcnt lgkmcnt(0)
	v_fmac_f32_e32 v121, v105, v112
	v_mul_f32_e32 v93, v72, v112
	v_cndmask_b32_e64 v105, v105, v121, s[6:7]
	v_cndmask_b32_e64 v72, v72, v93, s[6:7]
	v_fmac_f32_e32 v105, v71, v72
	v_mul_f32_e32 v71, v73, v72
	v_mul_f32_e32 v93, v148, v71
	v_fmac_f32_e32 v125, v75, v105
	v_mul_f32_e32 v75, v75, v71
	v_fmac_f32_e32 v174, v70, v105
	v_mul_f32_e32 v109, v70, v71
	v_fmac_f32_e32 v80, v89, v105
	v_mul_f32_e32 v89, v89, v71
	v_or_b32_e32 v70, v140, v214
	v_mov_b32_e32 v71, v141
	v_lshlrev_b64 v[70:71], 1, v[70:71]
	v_lshl_add_u64 v[72:73], s[62:63], 0, v[70:71]
	v_lshl_add_u64 v[70:71], s[64:65], 0, v[70:71]
	v_fmac_f32_e32 v123, v148, v105
	v_cvt_pk_bf16_f32 v105, v123, v1
	global_store_short v[72:73], v105, off
	v_cvt_pk_bf16_f32 v72, v93, v1
	global_store_short v[70:71], v72, off
	v_or_b32_e32 v70, v132, v214
	v_mov_b32_e32 v71, v133
	v_lshlrev_b64 v[70:71], 1, v[70:71]
	v_lshl_add_u64 v[72:73], s[62:63], 0, v[70:71]
	v_lshl_add_u64 v[70:71], s[64:65], 0, v[70:71]
	v_cvt_pk_bf16_f32 v93, v125, v1
	global_store_short v[72:73], v93, off
	v_cvt_pk_bf16_f32 v72, v75, v1
	global_store_short v[70:71], v72, off
	v_or_b32_e32 v70, v136, v214
	v_mov_b32_e32 v71, v137
	v_lshlrev_b64 v[70:71], 1, v[70:71]
	v_lshl_add_u64 v[72:73], s[62:63], 0, v[70:71]
	v_lshl_add_u64 v[70:71], s[64:65], 0, v[70:71]
	v_cvt_pk_bf16_f32 v75, v174, v1
	global_store_short v[72:73], v75, off
	v_cvt_pk_bf16_f32 v72, v109, v1
	global_store_short v[70:71], v72, off
	v_or_b32_e32 v70, v142, v214
	v_mov_b32_e32 v71, v143
	v_lshlrev_b64 v[70:71], 1, v[70:71]
	v_lshl_add_u64 v[72:73], s[62:63], 0, v[70:71]
	v_fma_f32 v121, v151, v119, v118
	v_cvt_pk_bf16_f32 v75, v80, v1
	global_store_short v[72:73], v75, off
	v_mov_b32_e32 v146, v114
	v_mul_f32_e32 v72, v147, v121
	v_pk_fma_f32 v[72:73], v[146:147], v[120:121], v[72:73] op_sel_hi:[1,1,0]
	v_mul_f32_e32 v93, v151, v160
	v_mov_b32_e32 v148, v116
	v_mov_b32_e32 v151, v72
	v_mul_f32_e32 v73, v147, v93
	v_pk_mul_f32 v[122:123], v[148:149], v[150:151]
	v_mul_f32_e32 v109, v149, v73
	v_add_f32_e32 v105, v122, v123
	ds_bpermute_b32 v112, v134, v109
	ds_bpermute_b32 v114, v134, v105
	v_lshl_add_u64 v[70:71], s[64:65], 0, v[70:71]
	v_cvt_pk_bf16_f32 v75, v89, v1
	global_store_short v[70:71], v75, off
	ds_bpermute_b32 v70, v134, v109 offset:64
	ds_bpermute_b32 v71, v134, v105 offset:64
	s_waitcnt lgkmcnt(2)
; __device__ __forceinline__ unsigned cvt_pk_bf16(float lo, float hi) { unsigned r; asm volatile("v_cvt_pk_bf16_f32 %0, %1, %2" : "=v"(r) : "v"(lo), "v"(hi)); return r; }
; template <int NT> ...
;     ...
;             hl[0] = bv[u][n][0]; pl[0] = av[u][n][0];
; #pragma unroll
;             for (int j = 1; j < 4; ++j) { hl[j] = av[u][n][j] * hl[j - 1] + bv[u][n][j]; pl[j] = av[u][n][j] * pl[j - 1]; }
;             float He = 0.f, Pe = 1.f;
; #pragma unroll
;             for (int g = 0; g < 3; ++g) { const float Pg = __shfl(pl[3], fr + 16 * g), Hg = __shfl(hl[3], fr + 16 * g); if (g < fq) { He = Pg * He + Hg; Pe = Pg * Pe; } }
;             const float Hin = Pe * Hc[n] + He, Pin = Pe * Pc[n];
;             float hf[4], pf[4];
; #pragma unroll
;             for (int j = 0; j < 4; ++j) { hf[j] = hl[j] + pl[j] * Hin; pf[j] = pl[j] * Pin; }
; #pragma unroll
;             for (int j = 0; j < 4; ++j) { const size_t o = (size_t)(m0 + 16 * u + 4 * fq + j) * D + ch; HLOC[o] = (bf16_t)(cvt_pk_bf16(hf[j], 0.f) & 0xffffu); PCUM[o] = (bf16_t)(cvt_pk_bf16(pf[j], 0.f) & 0xffffu); }
;             Hc[n] = __shfl(hf[3], fr + 48); Pc[n] = __shfl(pf[3], fr + 48);
	v_fmac_f32_e32 v114, 0, v112
	ds_bpermute_b32 v75, v134, v80 offset:192
	ds_bpermute_b32 v80, v134, v89 offset:192
	v_cndmask_b32_e64 v89, v114, 0, s[8:9]
	ds_bpermute_b32 v114, v134, v109 offset:128
	ds_bpermute_b32 v116, v134, v105 offset:128
	v_cndmask_b32_e64 v112, v112, 1.0, s[8:9]
	s_waitcnt lgkmcnt(4)
	v_fmac_f32_e32 v71, v89, v70
	v_mul_f32_e32 v70, v112, v70
	v_cndmask_b32_e64 v71, v89, v71, s[4:5]
	v_cndmask_b32_e64 v70, v112, v70, s[4:5]
	s_waitcnt lgkmcnt(0)
	v_fmac_f32_e32 v116, v71, v114
	v_mul_f32_e32 v89, v70, v114
	v_cndmask_b32_e64 v71, v71, v116, s[6:7]
	v_cndmask_b32_e64 v70, v70, v89, s[6:7]
	v_fmac_f32_e32 v71, v66, v70
	v_mul_f32_e32 v66, v68, v70
	v_fmac_f32_e32 v119, v160, v71
	v_fmac_f32_e32 v121, v93, v71
	v_fmac_f32_e32 v72, v73, v71
	v_fmac_f32_e32 v105, v109, v71
	v_or_b32_e32 v70, v140, v212
	v_mov_b32_e32 v71, v141
	v_lshlrev_b64 v[70:71], 1, v[70:71]
	v_mul_f32_e32 v68, v160, v66
	v_mul_f32_e32 v89, v93, v66
	v_mul_f32_e32 v93, v73, v66
	v_mul_f32_e32 v114, v109, v66
	v_cvt_pk_bf16_f32 v66, v119, v1
	v_lshl_add_u64 v[118:119], s[62:63], 0, v[70:71]
	v_lshl_add_u64 v[70:71], s[64:65], 0, v[70:71]
	global_store_short v[118:119], v66, off
	v_cvt_pk_bf16_f32 v66, v68, v1
	global_store_short v[70:71], v66, off
	v_or_b32_e32 v70, v132, v212
	v_mov_b32_e32 v71, v133
	v_lshlrev_b64 v[70:71], 1, v[70:71]
	v_cvt_pk_bf16_f32 v66, v121, v1
	v_lshl_add_u64 v[118:119], s[62:63], 0, v[70:71]
	v_lshl_add_u64 v[70:71], s[64:65], 0, v[70:71]
	global_store_short v[118:119], v66, off
	v_cvt_pk_bf16_f32 v66, v89, v1
	global_store_short v[70:71], v66, off
	v_or_b32_e32 v70, v136, v212
	v_mov_b32_e32 v71, v137
	v_lshlrev_b64 v[70:71], 1, v[70:71]
	v_cvt_pk_bf16_f32 v66, v72, v1
	v_lshl_add_u64 v[72:73], s[62:63], 0, v[70:71]
	v_lshl_add_u64 v[70:71], s[64:65], 0, v[70:71]
	global_store_short v[72:73], v66, off
	v_cvt_pk_bf16_f32 v66, v93, v1
	global_store_short v[70:71], v66, off
	v_or_b32_e32 v70, v142, v212
	v_mov_b32_e32 v71, v143
	v_lshlrev_b64 v[70:71], 1, v[70:71]
	v_cvt_pk_bf16_f32 v66, v105, v1
	v_lshl_add_u64 v[72:73], s[62:63], 0, v[70:71]
	v_fma_f32 v109, v110, v107, v106
	global_store_short v[72:73], v66, off
	v_mul_f32_e32 v89, v110, v162
	v_mov_b32_e32 v110, v115
	v_mul_f32_e32 v66, v111, v109
	v_pk_fma_f32 v[72:73], v[110:111], v[108:109], v[66:67] op_sel_hi:[1,1,0]
	v_mov_b32_e32 v112, v117
	v_mov_b32_e32 v159, v72
	v_mul_f32_e32 v66, v111, v89
	v_pk_mul_f32 v[110:111], v[112:113], v[158:159]
	v_mul_f32_e32 v93, v113, v66
	v_add_f32_e32 v73, v110, v111
	ds_bpermute_b32 v106, v134, v93
	ds_bpermute_b32 v108, v134, v73
	v_cvt_pk_bf16_f32 v68, v114, v1
	v_lshl_add_u64 v[70:71], s[64:65], 0, v[70:71]
	global_store_short v[70:71], v68, off
	ds_bpermute_b32 v68, v134, v93 offset:64
	ds_bpermute_b32 v70, v134, v73 offset:64
	s_waitcnt lgkmcnt(2)
	v_fmac_f32_e32 v108, 0, v106
	ds_bpermute_b32 v110, v134, v105 offset:192
	v_cndmask_b32_e64 v71, v108, 0, s[8:9]
	v_cndmask_b32_e64 v105, v106, 1.0, s[8:9]
	ds_bpermute_b32 v106, v134, v93 offset:128
	ds_bpermute_b32 v108, v134, v73 offset:128
	s_waitcnt lgkmcnt(3)
	v_fmac_f32_e32 v70, v71, v68
	v_mul_f32_e32 v68, v105, v68
	v_cndmask_b32_e64 v70, v71, v70, s[4:5]
	v_cndmask_b32_e64 v68, v105, v68, s[4:5]
	s_waitcnt lgkmcnt(0)
	v_fmac_f32_e32 v108, v70, v106
	v_mul_f32_e32 v71, v68, v106
	v_cndmask_b32_e64 v70, v70, v108, s[6:7]
	v_cndmask_b32_e64 v68, v68, v71, s[6:7]
	v_fmac_f32_e32 v70, v67, v68
	v_mul_f32_e32 v67, v69, v68
	v_or_b32_e32 v140, v140, v210
	v_fmac_f32_e32 v107, v162, v70
	v_mul_f32_e32 v71, v162, v67
	v_fmac_f32_e32 v109, v89, v70
	v_mul_f32_e32 v89, v89, v67
	v_fmac_f32_e32 v72, v66, v70
	v_mul_f32_e32 v105, v66, v67
	v_fmac_f32_e32 v73, v93, v70
	v_mul_f32_e32 v70, v93, v67
	v_lshlrev_b64 v[66:67], 1, v[140:141]
	v_lshl_add_u64 v[68:69], s[62:63], 0, v[66:67]
	v_lshl_add_u64 v[66:67], s[64:65], 0, v[66:67]
	v_or_b32_e32 v132, v132, v210
	v_cvt_pk_bf16_f32 v93, v107, v1
	global_store_short v[68:69], v93, off
	v_cvt_pk_bf16_f32 v68, v71, v1
	global_store_short v[66:67], v68, off
	v_lshlrev_b64 v[66:67], 1, v[132:133]
	v_lshl_add_u64 v[68:69], s[62:63], 0, v[66:67]
	v_lshl_add_u64 v[66:67], s[64:65], 0, v[66:67]
	v_or_b32_e32 v136, v136, v210
	v_cvt_pk_bf16_f32 v71, v109, v1
	global_store_short v[68:69], v71, off
	v_cvt_pk_bf16_f32 v68, v89, v1
	global_store_short v[66:67], v68, off
	v_lshlrev_b64 v[66:67], 1, v[136:137]
	v_lshl_add_u64 v[68:69], s[62:63], 0, v[66:67]
	v_lshl_add_u64 v[66:67], s[64:65], 0, v[66:67]
	v_or_b32_e32 v142, v142, v210
	v_cvt_pk_bf16_f32 v71, v72, v1
	global_store_short v[68:69], v71, off
	v_cvt_pk_bf16_f32 v68, v105, v1
	global_store_short v[66:67], v68, off
	v_lshlrev_b64 v[66:67], 1, v[142:143]
	v_lshl_add_u64 v[68:69], s[62:63], 0, v[66:67]
	v_lshl_add_u64 v[66:67], s[64:65], 0, v[66:67]
	v_fma_f32 v105, v179, v102, v103
	v_cvt_pk_bf16_f32 v71, v73, v1
	global_store_short v[68:69], v71, off
	v_cvt_pk_bf16_f32 v68, v70, v1
	global_store_short v[66:67], v68, off
	v_mov_b32_e32 v160, v98
	v_mul_f32_e32 v66, v105, v161
	v_pk_fma_f32 v[66:67], v[104:105], v[160:161], v[66:67] op_sel_hi:[1,1,0]
	v_mul_f32_e32 v71, v179, v178
	v_mov_b32_e32 v165, v66
	v_mov_b32_e32 v162, v100
	v_mul_f32_e32 v67, v161, v71
	v_pk_mul_f32 v[68:69], v[164:165], v[162:163]
	ds_bpermute_b32 v112, v134, v73 offset:192
	v_add_f32_e32 v72, v68, v69
	v_mul_f32_e32 v73, v163, v67
	ds_bpermute_b32 v89, v134, v73
	ds_bpermute_b32 v93, v134, v72
	v_add_u32_e32 v68, 16, v138
	v_ashrrev_i32_e32 v69, 31, v68
	v_lshlrev_b64 v[106:107], 10, v[68:69]
	ds_bpermute_b32 v68, v134, v73 offset:64
	ds_bpermute_b32 v69, v134, v72 offset:64
	s_waitcnt lgkmcnt(2)
; __device__ __forceinline__ unsigned cvt_pk_bf16(float lo, float hi) { unsigned r; asm volatile("v_cvt_pk_bf16_f32 %0, %1, %2" : "=v"(r) : "v"(lo), "v"(hi)); return r; }
; template <int NT> ...
;     ...
;             hl[0] = bv[u][n][0]; pl[0] = av[u][n][0];
; #pragma unroll
;             for (int j = 1; j < 4; ++j) { hl[j] = av[u][n][j] * hl[j - 1] + bv[u][n][j]; pl[j] = av[u][n][j] * pl[j - 1]; }
;             float He = 0.f, Pe = 1.f;
; #pragma unroll
;             for (int g = 0; g < 3; ++g) { const float Pg = __shfl(pl[3], fr + 16 * g), Hg = __shfl(hl[3], fr + 16 * g); if (g < fq) { He = Pg * He + Hg; Pe = Pg * Pe; } }
;             const float Hin = Pe * Hc[n] + He, Pin = Pe * Pc[n];
;             float hf[4], pf[4];
; #pragma unroll
;             for (int j = 0; j < 4; ++j) { hf[j] = hl[j] + pl[j] * Hin; pf[j] = pl[j] * Pin; }
; #pragma unroll
;             for (int j = 0; j < 4; ++j) { const size_t o = (size_t)(m0 + 16 * u + 4 * fq + j) * D + ch; HLOC[o] = (bf16_t)(cvt_pk_bf16(hf[j], 0.f) & 0xffffu); PCUM[o] = (bf16_t)(cvt_pk_bf16(pf[j], 0.f) & 0xffffu); }
;             Hc[n] = __shfl(hf[3], fr + 48); Pc[n] = __shfl(pf[3], fr + 48);
	v_fmac_f32_e32 v93, 0, v89
	ds_bpermute_b32 v98, v134, v70 offset:192
	v_cndmask_b32_e64 v70, v93, 0, s[8:9]
	ds_bpermute_b32 v93, v134, v73 offset:128
	ds_bpermute_b32 v100, v134, v72 offset:128
	ds_bpermute_b32 v96, v134, v96 offset:192
	ds_bpermute_b32 v77, v134, v77 offset:192
	v_cndmask_b32_e64 v89, v89, 1.0, s[8:9]
	s_waitcnt lgkmcnt(5)
	v_fmac_f32_e32 v69, v70, v68
	v_mul_f32_e32 v68, v89, v68
	v_cndmask_b32_e64 v69, v70, v69, s[4:5]
	v_cndmask_b32_e64 v68, v89, v68, s[4:5]
	s_waitcnt lgkmcnt(2)
	v_fmac_f32_e32 v100, v69, v93
	v_mul_f32_e32 v70, v68, v93
	v_cndmask_b32_e64 v69, v69, v100, s[6:7]
	v_cndmask_b32_e64 v68, v68, v70, s[6:7]
	s_waitcnt lgkmcnt(1)
	v_fmac_f32_e32 v69, v68, v96
	s_waitcnt lgkmcnt(0)
	v_mul_f32_e32 v68, v68, v77
	v_fmac_f32_e32 v102, v178, v69
	v_mul_f32_e32 v77, v178, v68
	v_fmac_f32_e32 v105, v71, v69
	v_mul_f32_e32 v89, v71, v68
	v_fmac_f32_e32 v66, v67, v69
	v_mul_f32_e32 v93, v67, v68
	v_fmac_f32_e32 v72, v73, v69
	v_mul_f32_e32 v73, v73, v68
	v_or_b32_e32 v68, v106, v208
	v_mov_b32_e32 v69, v107
	v_lshlrev_b64 v[68:69], 1, v[68:69]
	v_cvt_pk_bf16_f32 v67, v102, v1
	v_lshl_add_u64 v[70:71], s[62:63], 0, v[68:69]
	v_lshl_add_u64 v[68:69], s[64:65], 0, v[68:69]
	global_store_short v[70:71], v67, off
	v_cvt_pk_bf16_f32 v67, v77, v1
	global_store_short v[68:69], v67, off
	v_add_u32_e32 v68, 17, v138
	v_ashrrev_i32_e32 v69, 31, v68
	v_lshlrev_b64 v[102:103], 10, v[68:69]
	v_or_b32_e32 v68, v102, v208
	v_mov_b32_e32 v69, v103
	v_lshlrev_b64 v[68:69], 1, v[68:69]
	v_cvt_pk_bf16_f32 v67, v105, v1
	v_lshl_add_u64 v[70:71], s[62:63], 0, v[68:69]
	v_lshl_add_u64 v[68:69], s[64:65], 0, v[68:69]
	global_store_short v[70:71], v67, off
	v_cvt_pk_bf16_f32 v67, v89, v1
	global_store_short v[68:69], v67, off
	v_add_u32_e32 v68, 18, v138
	v_ashrrev_i32_e32 v69, 31, v68
	v_lshlrev_b64 v[104:105], 10, v[68:69]
	v_or_b32_e32 v68, v104, v208
	v_mov_b32_e32 v69, v105
	v_cvt_pk_bf16_f32 v70, v66, v1
	v_lshlrev_b64 v[66:67], 1, v[68:69]
	v_lshl_add_u64 v[68:69], s[62:63], 0, v[66:67]
	v_lshl_add_u64 v[66:67], s[64:65], 0, v[66:67]
	global_store_short v[68:69], v70, off
	v_cvt_pk_bf16_f32 v68, v93, v1
	global_store_short v[66:67], v68, off
	v_add_u32_e32 v66, 19, v138
	v_ashrrev_i32_e32 v67, 31, v66
	v_lshlrev_b64 v[108:109], 10, v[66:67]
	v_or_b32_e32 v66, v108, v208
	v_mov_b32_e32 v67, v109
	v_lshlrev_b64 v[66:67], 1, v[66:67]
	v_lshl_add_u64 v[68:69], s[62:63], 0, v[66:67]
	v_fma_f32 v93, v94, v90, v91
	v_cvt_pk_bf16_f32 v70, v72, v1
	global_store_short v[68:69], v70, off
	v_mul_f32_e32 v89, v94, v168
	v_mov_b32_e32 v94, v99
	v_mul_f32_e32 v68, v93, v95
	v_pk_fma_f32 v[68:69], v[92:93], v[94:95], v[68:69] op_sel_hi:[1,1,0]
	v_mov_b32_e32 v96, v101
	v_mov_b32_e32 v167, v68
	v_mul_f32_e32 v69, v95, v89
	v_pk_mul_f32 v[70:71], v[166:167], v[96:97]
	v_mul_f32_e32 v91, v97, v69
	v_add_f32_e32 v71, v70, v71
	ds_bpermute_b32 v92, v134, v91
	ds_bpermute_b32 v94, v134, v71
	v_lshl_add_u64 v[66:67], s[64:65], 0, v[66:67]
	v_cvt_pk_bf16_f32 v77, v73, v1
	global_store_short v[66:67], v77, off
	ds_bpermute_b32 v66, v134, v91 offset:64
	ds_bpermute_b32 v67, v134, v71 offset:64
	s_waitcnt lgkmcnt(2)
	v_fmac_f32_e32 v94, 0, v92
	ds_bpermute_b32 v70, v134, v72 offset:192
	ds_bpermute_b32 v72, v134, v73 offset:192
	v_cndmask_b32_e64 v73, v94, 0, s[8:9]
	v_cndmask_b32_e64 v77, v92, 1.0, s[8:9]
	ds_bpermute_b32 v92, v134, v91 offset:128
	ds_bpermute_b32 v94, v134, v71 offset:128
	s_waitcnt lgkmcnt(4)
	v_fmac_f32_e32 v67, v73, v66
	v_mul_f32_e32 v66, v77, v66
	v_cndmask_b32_e64 v67, v73, v67, s[4:5]
	v_cndmask_b32_e64 v66, v77, v66, s[4:5]
	s_waitcnt lgkmcnt(0)
	v_fmac_f32_e32 v94, v67, v92
	v_mul_f32_e32 v73, v66, v92
	v_cndmask_b32_e64 v67, v67, v94, s[6:7]
	v_cndmask_b32_e64 v66, v66, v73, s[6:7]
	v_fmac_f32_e32 v67, v66, v75
	v_mul_f32_e32 v66, v66, v80
	v_fmac_f32_e32 v90, v168, v67
	v_mul_f32_e32 v73, v168, v66
	v_fmac_f32_e32 v93, v89, v67
	v_mul_f32_e32 v75, v89, v66
	v_fmac_f32_e32 v68, v69, v67
	v_mul_f32_e32 v77, v69, v66
	v_fmac_f32_e32 v71, v91, v67
	v_mul_f32_e32 v80, v91, v66
	v_or_b32_e32 v66, v106, v214
	v_mov_b32_e32 v67, v107
	v_lshlrev_b64 v[66:67], 1, v[66:67]
	v_cvt_pk_bf16_f32 v69, v90, v1
	v_lshl_add_u64 v[90:91], s[62:63], 0, v[66:67]
	v_lshl_add_u64 v[66:67], s[64:65], 0, v[66:67]
	global_store_short v[90:91], v69, off
	v_cvt_pk_bf16_f32 v69, v73, v1
	global_store_short v[66:67], v69, off
	v_or_b32_e32 v66, v102, v214
	v_mov_b32_e32 v67, v103
	v_lshlrev_b64 v[66:67], 1, v[66:67]
	v_cvt_pk_bf16_f32 v69, v93, v1
	v_lshl_add_u64 v[90:91], s[62:63], 0, v[66:67]
	v_lshl_add_u64 v[66:67], s[64:65], 0, v[66:67]
	global_store_short v[90:91], v69, off
	v_cvt_pk_bf16_f32 v69, v75, v1
	global_store_short v[66:67], v69, off
	v_or_b32_e32 v66, v104, v214
	v_mov_b32_e32 v67, v105
	v_lshlrev_b64 v[66:67], 1, v[66:67]
	v_cvt_pk_bf16_f32 v73, v68, v1
	v_lshl_add_u64 v[68:69], s[62:63], 0, v[66:67]
	v_lshl_add_u64 v[66:67], s[64:65], 0, v[66:67]
	global_store_short v[68:69], v73, off
	v_cvt_pk_bf16_f32 v68, v77, v1
	global_store_short v[66:67], v68, off
	v_or_b32_e32 v66, v108, v214
	v_mov_b32_e32 v67, v109
	v_lshlrev_b64 v[66:67], 1, v[66:67]
	v_lshl_add_u64 v[68:69], s[62:63], 0, v[66:67]
	v_fma_f32 v89, v170, v86, v87
	v_cvt_pk_bf16_f32 v73, v71, v1
	global_store_short v[68:69], v73, off
	v_mov_b32_e32 v168, v82
	v_mul_f32_e32 v68, v89, v169
	v_pk_fma_f32 v[68:69], v[88:89], v[168:169], v[68:69] op_sel_hi:[1,1,0]
	v_mul_f32_e32 v77, v170, v180
	v_mov_b32_e32 v75, v68
	v_mov_b32_e32 v170, v84
	v_mul_f32_e32 v69, v169, v77
	v_pk_mul_f32 v[74:75], v[74:75], v[170:171]
	v_lshl_add_u64 v[66:67], s[64:65], 0, v[66:67]
	v_add_f32_e32 v82, v74, v75
	v_mul_f32_e32 v74, v171, v69
	ds_bpermute_b32 v75, v134, v74
	ds_bpermute_b32 v84, v134, v82
	v_cvt_pk_bf16_f32 v73, v80, v1
	global_store_short v[66:67], v73, off
	ds_bpermute_b32 v66, v134, v74 offset:64
	ds_bpermute_b32 v67, v134, v82 offset:64
	s_waitcnt lgkmcnt(2)
; __device__ __forceinline__ unsigned cvt_pk_bf16(float lo, float hi) { unsigned r; asm volatile("v_cvt_pk_bf16_f32 %0, %1, %2" : "=v"(r) : "v"(lo), "v"(hi)); return r; }
; template <int NT> ...
;     ...
;             hl[0] = bv[u][n][0]; pl[0] = av[u][n][0];
; #pragma unroll
;             for (int j = 1; j < 4; ++j) { hl[j] = av[u][n][j] * hl[j - 1] + bv[u][n][j]; pl[j] = av[u][n][j] * pl[j - 1]; }
;             float He = 0.f, Pe = 1.f;
; #pragma unroll
;             for (int g = 0; g < 3; ++g) { const float Pg = __shfl(pl[3], fr + 16 * g), Hg = __shfl(hl[3], fr + 16 * g); if (g < fq) { He = Pg * He + Hg; Pe = Pg * Pe; } }
;             const float Hin = Pe * Hc[n] + He, Pin = Pe * Pc[n];
;             float hf[4], pf[4];
; #pragma unroll
;             for (int j = 0; j < 4; ++j) { hf[j] = hl[j] + pl[j] * Hin; pf[j] = pl[j] * Pin; }
; #pragma unroll
;             for (int j = 0; j < 4; ++j) { const size_t o = (size_t)(m0 + 16 * u + 4 * fq + j) * D + ch; HLOC[o] = (bf16_t)(cvt_pk_bf16(hf[j], 0.f) & 0xffffu); PCUM[o] = (bf16_t)(cvt_pk_bf16(pf[j], 0.f) & 0xffffu); }
;             Hc[n] = __shfl(hf[3], fr + 48); Pc[n] = __shfl(pf[3], fr + 48);
	v_fmac_f32_e32 v84, 0, v75
	ds_bpermute_b32 v73, v134, v80 offset:192
	v_cndmask_b32_e64 v80, v84, 0, s[8:9]
	ds_bpermute_b32 v84, v134, v74 offset:128
	ds_bpermute_b32 v87, v134, v82 offset:128
	ds_bpermute_b32 v111, v134, v114 offset:192
	v_cndmask_b32_e64 v75, v75, 1.0, s[8:9]
	s_waitcnt lgkmcnt(4)
	v_fmac_f32_e32 v67, v80, v66
	v_mul_f32_e32 v66, v75, v66
	v_cndmask_b32_e64 v67, v80, v67, s[4:5]
	v_cndmask_b32_e64 v66, v75, v66, s[4:5]
	s_waitcnt lgkmcnt(1)
	v_fmac_f32_e32 v87, v67, v84
	v_mul_f32_e32 v75, v66, v84
	v_cndmask_b32_e64 v67, v67, v87, s[6:7]
	v_cndmask_b32_e64 v66, v66, v75, s[6:7]
	v_fmac_f32_e32 v67, v66, v110
	s_waitcnt lgkmcnt(0)
	v_mul_f32_e32 v66, v66, v111
	v_fmac_f32_e32 v86, v180, v67
	v_mul_f32_e32 v80, v180, v66
	v_fmac_f32_e32 v89, v77, v67
	v_mul_f32_e32 v77, v77, v66
	v_fmac_f32_e32 v68, v69, v67
	v_mul_f32_e32 v84, v69, v66
	v_fmac_f32_e32 v82, v74, v67
	v_mul_f32_e32 v87, v74, v66
	v_or_b32_e32 v66, v106, v212
	v_mov_b32_e32 v67, v107
	v_lshlrev_b64 v[66:67], 1, v[66:67]
	v_cvt_pk_bf16_f32 v69, v86, v1
	v_lshl_add_u64 v[74:75], s[62:63], 0, v[66:67]
	v_lshl_add_u64 v[66:67], s[64:65], 0, v[66:67]
	global_store_short v[74:75], v69, off
	v_cvt_pk_bf16_f32 v69, v80, v1
	global_store_short v[66:67], v69, off
	v_or_b32_e32 v66, v102, v212
	v_mov_b32_e32 v67, v103
	v_lshlrev_b64 v[66:67], 1, v[66:67]
	v_cvt_pk_bf16_f32 v69, v89, v1
	v_lshl_add_u64 v[74:75], s[62:63], 0, v[66:67]
	v_lshl_add_u64 v[66:67], s[64:65], 0, v[66:67]
	global_store_short v[74:75], v69, off
	v_cvt_pk_bf16_f32 v69, v77, v1
	global_store_short v[66:67], v69, off
	v_or_b32_e32 v66, v104, v212
	v_mov_b32_e32 v67, v105
	v_lshlrev_b64 v[66:67], 1, v[66:67]
	v_cvt_pk_bf16_f32 v74, v68, v1
	v_lshl_add_u64 v[68:69], s[62:63], 0, v[66:67]
	v_lshl_add_u64 v[66:67], s[64:65], 0, v[66:67]
	global_store_short v[68:69], v74, off
	v_cvt_pk_bf16_f32 v68, v84, v1
	global_store_short v[66:67], v68, off
	v_or_b32_e32 v66, v108, v212
	v_mov_b32_e32 v67, v109
	v_lshlrev_b64 v[66:67], 1, v[66:67]
	v_lshl_add_u64 v[68:69], s[62:63], 0, v[66:67]
	v_fma_f32 v77, v154, v78, v79
	v_cvt_pk_bf16_f32 v74, v82, v1
	global_store_short v[68:69], v74, off
	v_mov_b32_e32 v172, v83
	v_mul_f32_e32 v68, v77, v173
	v_pk_fma_f32 v[74:75], v[76:77], v[172:173], v[68:69] op_sel_hi:[1,1,0]
	v_mul_f32_e32 v79, v154, v152
	v_mov_b32_e32 v131, v74
	v_mov_b32_e32 v80, v85
	v_mul_f32_e32 v75, v173, v79
	v_pk_mul_f32 v[68:69], v[130:131], v[80:81]
	v_mul_f32_e32 v76, v81, v75
	v_add_f32_e32 v69, v68, v69
	ds_bpermute_b32 v80, v134, v76
	ds_bpermute_b32 v81, v134, v69
	v_lshl_add_u64 v[66:67], s[64:65], 0, v[66:67]
	v_cvt_pk_bf16_f32 v84, v87, v1
	global_store_short v[66:67], v84, off
	ds_bpermute_b32 v66, v134, v82 offset:192
	ds_bpermute_b32 v67, v134, v76 offset:64
	ds_bpermute_b32 v82, v134, v69 offset:64
	ds_bpermute_b32 v83, v134, v76 offset:128
	ds_bpermute_b32 v84, v134, v69 offset:128
	s_waitcnt lgkmcnt(5)
	v_fmac_f32_e32 v81, 0, v80
	v_cndmask_b32_e64 v81, v81, 0, s[8:9]
	v_cndmask_b32_e64 v80, v80, 1.0, s[8:9]
	s_waitcnt lgkmcnt(2)
	v_fmac_f32_e32 v82, v81, v67
	v_mul_f32_e32 v67, v80, v67
	v_cndmask_b32_e64 v81, v81, v82, s[4:5]
	v_cndmask_b32_e64 v67, v80, v67, s[4:5]
	s_waitcnt lgkmcnt(0)
	v_fmac_f32_e32 v84, v81, v83
	v_mul_f32_e32 v80, v67, v83
	v_cndmask_b32_e64 v81, v81, v84, s[6:7]
	v_cndmask_b32_e64 v67, v67, v80, s[6:7]
	v_fmac_f32_e32 v81, v67, v112
	v_mul_f32_e32 v67, v67, v98
	v_fmac_f32_e32 v78, v152, v81
	v_or_b32_e32 v106, v106, v210
	v_mul_f32_e32 v82, v152, v67
	v_fmac_f32_e32 v77, v79, v81
	v_mul_f32_e32 v83, v79, v67
	v_mul_f32_e32 v84, v75, v67
	v_mul_f32_e32 v85, v76, v67
	v_cvt_pk_bf16_f32 v67, v78, v1
	v_lshlrev_b64 v[78:79], 1, v[106:107]
	v_fmac_f32_e32 v74, v75, v81
	v_fmac_f32_e32 v69, v76, v81
	v_lshl_add_u64 v[80:81], s[62:63], 0, v[78:79]
	global_store_short v[80:81], v67, off
	v_cvt_pk_bf16_f32 v67, v82, v1
	v_lshl_add_u64 v[78:79], s[64:65], 0, v[78:79]
	v_or_b32_e32 v102, v102, v210
	global_store_short v[78:79], v67, off
	v_cvt_pk_bf16_f32 v67, v77, v1
	v_lshlrev_b64 v[76:77], 1, v[102:103]
	v_lshl_add_u64 v[78:79], s[62:63], 0, v[76:77]
	global_store_short v[78:79], v67, off
	v_cvt_pk_bf16_f32 v67, v83, v1
	v_lshl_add_u64 v[76:77], s[64:65], 0, v[76:77]
	v_or_b32_e32 v104, v104, v210
	global_store_short v[76:77], v67, off
	v_cvt_pk_bf16_f32 v67, v74, v1
	v_lshlrev_b64 v[74:75], 1, v[104:105]
	v_lshl_add_u64 v[76:77], s[62:63], 0, v[74:75]
	v_lshl_add_u64 v[74:75], s[64:65], 0, v[74:75]
	v_or_b32_e32 v108, v108, v210
	global_store_short v[76:77], v67, off
	v_cvt_pk_bf16_f32 v67, v84, v1
	global_store_short v[74:75], v67, off
	v_lshlrev_b64 v[74:75], 1, v[108:109]
	v_cvt_pk_bf16_f32 v67, v69, v1
	v_lshl_add_u64 v[76:77], s[62:63], 0, v[74:75]
	global_store_short v[76:77], v67, off
	v_cvt_pk_bf16_f32 v67, v85, v1
	v_lshl_add_u64 v[74:75], s[64:65], 0, v[74:75]
	ds_bpermute_b32 v71, v134, v71 offset:192
	ds_bpermute_b32 v68, v134, v87 offset:192
	global_store_short v[74:75], v67, off
	ds_bpermute_b32 v67, v134, v69 offset:192
	ds_bpermute_b32 v69, v134, v85 offset:192
	v_add_u32_e32 v242, 32, v242
	v_subrev_u32_e32 v245, 32, v245
	s_cbranch_scc1 .LBB0_342

; #define LAS __attribute__((address_space(3)))
; __device__ __forceinline__ unsigned cvt_pk_bf16(float lo, float hi) { unsigned r; asm volatile("v_cvt_pk_bf16_f32 %0, %1, %2" : "=v"(r) : "v"(lo), "v"(hi)); return r; }
; #define LDS_WAIT() asm volatile("s_waitcnt lgkmcnt(0)" ::: "memory")
; template <int NT> ...
;     ...
;     for (int u = 0; u < NT; ++u) { const int m = m0 + 16 * u + rr, t = m - b * TP; LAS float* XC = XCb + u * (16 * 68);
;         float xv[4][16];
; #pragma unroll
;         for (int k = 0; k < 4; ++k) { float f0[8], f1[8]; unpack8(raw[u][k][0], f0); unpack8(raw[u][k][1], f1);
; #pragma unroll
;             for (int e = 0; e < 8; ++e) { xv[k][e] = f0[e]; xv[k][8 + e] = f1[e]; } }
;         if (t >= TP - 3) { float* o = p->out + O_PCB + ((size_t)(l * NB + b) * 3 + (t - (TP - 3))) * D + hc0 + cl;
; #pragma unroll
;             for (int e = 0; e < 16; e += 4) *(f32x4*)(o + e) = (f32x4){xv[3][e], xv[3][e + 1], xv[3][e + 2], xv[3][e + 3]}; }
; #pragma unroll
;         for (int e = 0; e < 16; e += 4) {
;             const f32x4 w0 = *(const LAS f32x4*)(CST + 0 * 64 + cl + e), w1 = *(const LAS f32x4*)(CST + 1 * 64 + cl + e), w2 = *(const LAS f32x4*)(CST + 2 * 64 + cl + e),
;                         w3 = *(const LAS f32x4*)(CST + 3 * 64 + cl + e), bb = *(const LAS f32x4*)(CST + 4 * 64 + cl + e);
;             f32x4 r;
; #pragma unroll
;             for (int q = 0; q < 4; ++q) r[q] = w0[q] * xv[0][e + q] + w1[q] * xv[1][e + q] + w2[q] * xv[2][e + q] + w3[q] * xv[3][e + q] + bb[q];
;             *(LAS f32x4*)(XC + rr * 68 + cl + e) = r;
;         } }
;     LDS_WAIT();
;     f32x4 ar[NT][4], ai[NT][4];
; #pragma unroll
;     for (int u = 0; u < NT; ++u) { const LAS float* XC = XCb + u * (16 * 68);
; #pragma unroll
;         for (int n = 0; n < 4; ++n) { ar[u][n] = (f32x4){0.f, 0.f, 0.f, 0.f}; ai[u][n] = (f32x4){0.f, 0.f, 0.f, 0.f}; }
; #pragma unroll
;         for (int s = 0; s < 2; ++s) {
;             const f32x4 x0 = *(const LAS f32x4*)(XC + fr * 68 + 32 * s + 8 * fq), x1 = *(const LAS f32x4*)(XC + fr * 68 + 32 * s + 8 * fq + 4);
;             u32x4 aw; aw.x = cvt_pk_bf16(x0[0], x0[1]); aw.y = cvt_pk_bf16(x0[2], x0[3]); aw.z = cvt_pk_bf16(x1[0], x1[1]); aw.w = cvt_pk_bf16(x1[2], x1[3]);
;             const bf16x8 af = __builtin_bit_cast(bf16x8, aw);
.LBB0_353:
	s_or_b64 exec, exec, s[10:11]
	ds_read_b128 v[114:117], v227 offset:8704
	ds_read_b128 v[118:121], v227 offset:8960
	ds_read_b128 v[122:125], v227 offset:9216
	ds_read_b128 v[126:129], v227 offset:9472
	ds_read_b128 v[130:133], v227 offset:9728
	v_lshlrev_b32_e32 v138, 16, v86
	v_and_b32_e32 v139, 0xffff0000, v86
	v_lshlrev_b32_e32 v86, 16, v87
	v_and_b32_e32 v87, 0xffff0000, v87
	v_lshlrev_b32_e32 v140, 16, v82
	v_and_b32_e32 v141, 0xffff0000, v82
	s_waitcnt lgkmcnt(3)
	v_pk_mul_f32 v[118:119], v[118:119], v[138:139]
	v_lshlrev_b32_e32 v82, 16, v83
	v_and_b32_e32 v83, 0xffff0000, v83
	v_pk_mul_f32 v[86:87], v[120:121], v[86:87]
	v_lshlrev_b32_e32 v136, 16, v98
	v_and_b32_e32 v137, 0xffff0000, v98
	v_pk_fma_f32 v[114:115], v[114:115], v[140:141], v[118:119]
	v_lshlrev_b32_e32 v98, 16, v99
	v_and_b32_e32 v99, 0xffff0000, v99
	v_pk_fma_f32 v[82:83], v[116:117], v[82:83], v[86:87]
	s_waitcnt lgkmcnt(2)
	v_pk_fma_f32 v[114:115], v[122:123], v[136:137], v[114:115]
	v_pk_fma_f32 v[82:83], v[124:125], v[98:99], v[82:83]
	s_waitcnt lgkmcnt(1)
	v_pk_fma_f32 v[110:111], v[126:127], v[110:111], v[114:115]
	v_pk_fma_f32 v[82:83], v[128:129], v[112:113], v[82:83]
	s_waitcnt lgkmcnt(0)
	v_pk_add_f32 v[110:111], v[130:131], v[110:111]
	v_pk_add_f32 v[112:113], v[132:133], v[82:83]
	ds_write_b128 v240, v[110:113]
	ds_read_b128 v[110:113], v227 offset:8720
	ds_read_b128 v[114:117], v227 offset:8976
	ds_read_b128 v[118:121], v227 offset:9232
	ds_read_b128 v[122:125], v227 offset:9488
	ds_read_b128 v[126:129], v227 offset:9744
	v_lshlrev_b32_e32 v86, 16, v88
	v_and_b32_e32 v87, 0xffff0000, v88
	v_lshlrev_b32_e32 v98, 16, v84
	v_and_b32_e32 v99, 0xffff0000, v84
	s_waitcnt lgkmcnt(3)
	v_pk_mul_f32 v[86:87], v[114:115], v[86:87]
	v_lshlrev_b32_e32 v88, 16, v89
	v_and_b32_e32 v89, 0xffff0000, v89
	v_lshlrev_b32_e32 v82, 16, v100
	v_and_b32_e32 v83, 0xffff0000, v100
	v_pk_fma_f32 v[86:87], v[110:111], v[98:99], v[86:87]
	v_lshlrev_b32_e32 v84, 16, v85
	v_and_b32_e32 v85, 0xffff0000, v85
	v_pk_mul_f32 v[88:89], v[116:117], v[88:89]
	s_waitcnt lgkmcnt(2)
	v_pk_fma_f32 v[82:83], v[118:119], v[82:83], v[86:87]
	v_lshlrev_b32_e32 v86, 16, v101
	v_and_b32_e32 v87, 0xffff0000, v101
	v_pk_fma_f32 v[84:85], v[112:113], v[84:85], v[88:89]
	s_waitcnt lgkmcnt(1)
	v_pk_fma_f32 v[82:83], v[122:123], v[106:107], v[82:83]
	v_pk_fma_f32 v[84:85], v[120:121], v[86:87], v[84:85]
	s_waitcnt lgkmcnt(0)
	v_pk_add_f32 v[82:83], v[126:127], v[82:83]
	v_pk_fma_f32 v[84:85], v[124:125], v[108:109], v[84:85]
	v_lshlrev_b32_e32 v116, 16, v78
	v_pk_add_f32 v[84:85], v[128:129], v[84:85]
	ds_write_b128 v240, v[82:85] offset:16
	ds_read_b128 v[82:85], v227 offset:8736
	ds_read_b128 v[86:89], v227 offset:8992
	ds_read_b128 v[98:101], v227 offset:9248
	ds_read_b128 v[106:109], v227 offset:9504
	ds_read_b128 v[110:113], v227 offset:9760
	v_and_b32_e32 v117, 0xffff0000, v78
	v_lshlrev_b32_e32 v78, 16, v79
	v_and_b32_e32 v79, 0xffff0000, v79
	v_lshlrev_b32_e32 v118, 16, v74
	v_and_b32_e32 v119, 0xffff0000, v74
	s_waitcnt lgkmcnt(3)
	v_pk_mul_f32 v[86:87], v[86:87], v[116:117]
	v_lshlrev_b32_e32 v74, 16, v75
	v_and_b32_e32 v75, 0xffff0000, v75
	v_pk_mul_f32 v[78:79], v[88:89], v[78:79]
	v_lshlrev_b32_e32 v114, 16, v90
	v_and_b32_e32 v115, 0xffff0000, v90
	v_pk_fma_f32 v[82:83], v[82:83], v[118:119], v[86:87]
	v_lshlrev_b32_e32 v86, 16, v91
	v_and_b32_e32 v87, 0xffff0000, v91
	v_pk_fma_f32 v[74:75], v[84:85], v[74:75], v[78:79]
	s_waitcnt lgkmcnt(2)
	v_pk_fma_f32 v[82:83], v[98:99], v[114:115], v[82:83]
	v_pk_fma_f32 v[74:75], v[100:101], v[86:87], v[74:75]
	s_waitcnt lgkmcnt(1)
	v_pk_fma_f32 v[82:83], v[106:107], v[102:103], v[82:83]
	v_pk_fma_f32 v[74:75], v[108:109], v[104:105], v[74:75]
	s_waitcnt lgkmcnt(0)
	v_pk_add_f32 v[82:83], v[110:111], v[82:83]
	v_pk_add_f32 v[84:85], v[112:113], v[74:75]
	ds_write_b128 v240, v[82:85] offset:32
	ds_read_b128 v[82:85], v227 offset:8752
	ds_read_b128 v[86:89], v227 offset:9008
	ds_read_b128 v[98:101], v227 offset:9264
	ds_read_b128 v[102:105], v227 offset:9520
	ds_read_b128 v[106:109], v227 offset:9776
	v_lshlrev_b32_e32 v78, 16, v80
	v_and_b32_e32 v79, 0xffff0000, v80
	v_lshlrev_b32_e32 v90, 16, v76
	v_and_b32_e32 v91, 0xffff0000, v76
	s_waitcnt lgkmcnt(3)
	v_pk_mul_f32 v[78:79], v[86:87], v[78:79]
	v_lshlrev_b32_e32 v80, 16, v81
	v_and_b32_e32 v81, 0xffff0000, v81
	v_lshlrev_b32_e32 v74, 16, v92
	v_and_b32_e32 v75, 0xffff0000, v92
	v_pk_fma_f32 v[78:79], v[82:83], v[90:91], v[78:79]
	v_lshlrev_b32_e32 v76, 16, v77
	v_and_b32_e32 v77, 0xffff0000, v77
	v_pk_mul_f32 v[80:81], v[88:89], v[80:81]
	s_waitcnt lgkmcnt(2)
	v_pk_fma_f32 v[74:75], v[98:99], v[74:75], v[78:79]
	v_lshlrev_b32_e32 v78, 16, v93
	v_and_b32_e32 v79, 0xffff0000, v93
	v_pk_fma_f32 v[76:77], v[84:85], v[76:77], v[80:81]
	s_waitcnt lgkmcnt(1)
	v_pk_fma_f32 v[74:75], v[102:103], v[94:95], v[74:75]
	v_pk_fma_f32 v[76:77], v[100:101], v[78:79], v[76:77]
	s_waitcnt lgkmcnt(0)
	v_pk_add_f32 v[74:75], v[106:107], v[74:75]
	v_pk_fma_f32 v[76:77], v[104:105], v[96:97], v[76:77]
	s_add_i32 s12, s18, s12
	v_pk_add_f32 v[76:77], v[108:109], v[76:77]
	ds_write_b128 v240, v[74:77] offset:48
	s_waitcnt lgkmcnt(0)
	ds_read_b128 v[74:77], v239
	ds_read_b128 v[78:81], v239 offset:16
	s_waitcnt lgkmcnt(1)
	v_cvt_pk_bf16_f32 v74, v74, v75
	v_cvt_pk_bf16_f32 v75, v76, v77
	s_waitcnt lgkmcnt(0)
; #define LAS __attribute__((address_space(3)))
; __device__ __forceinline__ unsigned cvt_pk_bf16(float lo, float hi) { unsigned r; asm volatile("v_cvt_pk_bf16_f32 %0, %1, %2" : "=v"(r) : "v"(lo), "v"(hi)); return r; }
; __device__ __forceinline__ float sigmoidf_(float x) { return __builtin_amdgcn_rcpf(1.0f + __expf(-x)); }
; template <int NT> ...
;     ...
;     for (int u = 0; u < NT; ++u) { const LAS float* XC = XCb + u * (16 * 68);
; #pragma unroll
;         for (int n = 0; n < 4; ++n) { ar[u][n] = (f32x4){0.f, 0.f, 0.f, 0.f}; ai[u][n] = (f32x4){0.f, 0.f, 0.f, 0.f}; }
; #pragma unroll
;         for (int s = 0; s < 2; ++s) {
;             const f32x4 x0 = *(const LAS f32x4*)(XC + fr * 68 + 32 * s + 8 * fq), x1 = *(const LAS f32x4*)(XC + fr * 68 + 32 * s + 8 * fq + 4);
;             u32x4 aw; aw.x = cvt_pk_bf16(x0[0], x0[1]); aw.y = cvt_pk_bf16(x0[2], x0[3]); aw.z = cvt_pk_bf16(x1[0], x1[1]); aw.w = cvt_pk_bf16(x1[2], x1[3]);
;             const bf16x8 af = __builtin_bit_cast(bf16x8, aw);
; #pragma unroll
;             for (int n = 0; n < 4; ++n) { ar[u][n] = __builtin_amdgcn_mfma_f32_16x16x32_bf16(af, Wa[n][s], ar[u][n], 0, 0, 0); ai[u][n] = __builtin_amdgcn_mfma_f32_16x16x32_bf16(af, Wx[n][s], ai[u][n], 0, 0, 0); }
;         } }
;     float av[NT][4][4], bv[NT][4][4];
; #pragma unroll
;     for (int u = 0; u < NT; ++u) { const LAS float* XC = XCb + u * (16 * 68); const int t0 = m0 + 16 * u - b * TP;
; #pragma unroll
;         for (int n = 0; n < 4; ++n) { const int cc = 16 * n + fr;
;             const float ba = CST[5 * 64 + cc], bx = CST[6 * 64 + cc], sp = CST[7 * 64 + cc];
; #pragma unroll
;             for (int j = 0; j < 4; ++j) {
;                 const float xc = XC[(4 * fq + j) * 68 + cc];
;                 const float r = sigmoidf_(ar[u][n][j] + ba), ig = sigmoidf_(ai[u][n][j] + bx);
;                 const float a = __expf(-8.0f * r * sp);
;                 float mult = sqrtf(fmaxf(1.0f - a * a, 0.f));
;                 if (t0 + 4 * fq + j == 0) mult = 1.0f;
;                 av[u][n][j] = a; bv[u][n][j] = mult * ig * xc; } } }
	v_cvt_pk_bf16_f32 v76, v78, v79
	v_cvt_pk_bf16_f32 v77, v80, v81
	s_nop 0
	v_mfma_f32_16x16x32_bf16 v[78:81], v[74:77], v[54:57], 0
	ds_read_b128 v[54:57], v239 offset:128
	ds_read_b128 v[82:85], v239 offset:144
	v_mfma_f32_16x16x32_bf16 v[34:37], v[74:77], v[34:37], 0
	v_mfma_f32_16x16x32_bf16 v[42:45], v[74:77], v[42:45], 0
	v_mfma_f32_16x16x32_bf16 v[46:49], v[74:77], v[46:49], 0
	v_mfma_f32_16x16x32_bf16 v[38:41], v[74:77], v[38:41], 0
	v_mfma_f32_16x16x32_bf16 v[50:53], v[74:77], v[50:53], 0
	v_mfma_f32_16x16x32_bf16 v[62:65], v[74:77], v[62:65], 0
	v_mfma_f32_16x16x32_bf16 v[58:61], v[74:77], v[58:61], 0
	s_waitcnt lgkmcnt(1)
	v_cvt_pk_bf16_f32 v74, v54, v55
	v_cvt_pk_bf16_f32 v75, v56, v57
	s_waitcnt lgkmcnt(0)
	v_cvt_pk_bf16_f32 v76, v82, v83
	v_cvt_pk_bf16_f32 v77, v84, v85
	v_or_b32_e32 v55, 64, v134
	v_mfma_f32_16x16x32_bf16 v[82:85], v[74:77], v[10:13], v[34:37]
	v_or_b32_e32 v54, 0x80, v134
	v_mfma_f32_16x16x32_bf16 v[34:37], v[74:77], v[22:25], v[42:45]
	v_mfma_f32_16x16x32_bf16 v[22:25], v[74:77], v[26:29], v[46:49]
	ds_read2_b32 v[28:29], v177 offset0:192 offset1:208
	s_nop 0
	ds_read2_b32 v[42:43], v241 offset1:16
	s_waitcnt lgkmcnt(1)
	s_nop 0
	v_add_f32_e32 v0, v82, v28
	v_mul_f32_e32 v0, 0xbfb8aa3b, v0
	v_mfma_f32_16x16x32_bf16 v[10:13], v[74:77], v[18:21], v[78:81]
	v_exp_f32_e32 v18, v0
	ds_read2_b32 v[46:47], v241 offset0:68 offset1:84
	v_add_f32_e32 v34, v34, v29
	v_mfma_f32_16x16x32_bf16 v[86:89], v[74:77], v[14:17], v[38:41]
	v_add_f32_e32 v18, 1.0, v18
	v_rcp_f32_e32 v18, v18
	v_mul_f32_e32 v34, 0xbfb8aa3b, v34
	ds_read2_b32 v[38:39], v176 offset0:64 offset1:80
	ds_read2_b32 v[40:41], v176 offset1:16
	v_mul_f32_e32 v18, 0xc1000000, v18
	v_mfma_f32_16x16x32_bf16 v[14:17], v[74:77], v[30:33], v[50:53]
	v_exp_f32_e32 v34, v34
	s_waitcnt lgkmcnt(1)
	v_mul_f32_e32 v18, v38, v18
	v_mul_f32_e32 v18, 0x3fb8aa3b, v18
	v_exp_f32_e32 v44, v18
	s_waitcnt lgkmcnt(0)
	v_add_f32_e32 v18, v86, v40
	v_mul_f32_e32 v18, 0xbfb8aa3b, v18
	v_exp_f32_e32 v18, v18
	v_fma_f32 v19, -v44, v44, 1.0
	v_max_f32_e32 v19, 0, v19
	v_add_f32_e32 v18, 1.0, v18
	v_add_f32_e32 v34, 1.0, v34
	v_mov_b32_e32 v20, v19
	v_rcp_f32_e32 v19, v18
	v_rcp_f32_e32 v34, v34
	v_add_f32_e32 v22, v22, v41
	v_mul_f32_e32 v34, 0xc1000000, v34
	v_mul_f32_e32 v34, v39, v34
	v_mul_f32_e32 v34, 0x3fb8aa3b, v34
	v_add_f32_e32 v26, v83, v28
	v_mul_f32_e32 v26, 0xbfb8aa3b, v26
	v_exp_f32_e32 v26, v26
	v_or_b32_e32 v21, s12, v224
	v_exp_f32_e32 v56, v34
	v_sqrt_f32_e32 v18, v20
	s_nop 0
	v_add_f32_e32 v20, 1.0, v26
	v_rcp_f32_e32 v20, v20
	v_cmp_eq_u32_e32 vcc, 0, v21
	v_fma_f32 v34, -v56, v56, 1.0
	v_max_f32_e32 v34, 0, v34
	v_cndmask_b32_e64 v21, v18, 1.0, vcc
	v_mul_f32_e32 v18, 0xc1000000, v20
	v_mul_f32_e32 v18, v38, v18
	v_mul_f32_e32 v18, 0x3fb8aa3b, v18
	v_exp_f32_e32 v30, v18
	v_add_f32_e32 v18, v87, v40
	v_mul_f32_e32 v18, 0xbfb8aa3b, v18
	v_exp_f32_e32 v18, v18
	v_fma_f32 v20, -v30, v30, 1.0
	v_max_f32_e32 v20, 0, v20
	v_add_f32_e32 v18, 1.0, v18
	v_rcp_f32_e32 v18, v18
	v_mul_f32_e32 v22, 0xbfb8aa3b, v22
	v_exp_f32_e32 v22, v22
	v_add_f32_e32 v35, v35, v29
	v_mul_f32_e32 v35, 0xbfb8aa3b, v35
	v_exp_f32_e32 v35, v35
	v_add_f32_e32 v22, 1.0, v22
	v_add_f32_e32 v27, v84, v28
	v_mul_f32_e32 v27, 0xbfb8aa3b, v27
	v_exp_f32_e32 v27, v27
	v_add_f32_e32 v28, v85, v28
	v_mul_f32_e32 v28, 0xbfb8aa3b, v28
	v_sqrt_f32_e32 v20, v20
	s_nop 0
	v_pk_mul_f32 v[18:19], v[18:19], v[20:21]
	v_add_f32_e32 v20, 1.0, v27
	v_rcp_f32_e32 v26, v20
	v_mov_b32_e32 v20, v46
	v_mov_b32_e32 v21, v42
	v_pk_mul_f32 v[20:21], v[20:21], v[18:19]
	v_mul_f32_e32 v18, 0xc1000000, v26
	v_mul_f32_e32 v18, v38, v18
	v_mul_f32_e32 v18, 0x3fb8aa3b, v18
	v_exp_f32_e32 v31, v18
	v_add_f32_e32 v18, v88, v40
	v_mul_f32_e32 v18, 0xbfb8aa3b, v18
	v_exp_f32_e32 v26, v18
	v_fma_f32 v18, -v31, v31, 1.0
	v_max_f32_e32 v18, 0, v18
	v_exp_f32_e32 v28, v28
	v_add_f32_e32 v26, 1.0, v26
	v_mov_b32_e32 v27, v18
	v_add_f32_e32 v28, 1.0, v28
	v_rcp_f32_e32 v26, v26
	v_rcp_f32_e32 v49, v22
	v_add_f32_e32 v35, 1.0, v35
	v_rcp_f32_e32 v35, v35
	v_add_f32_e32 v23, v23, v41
	v_rcp_f32_e32 v33, v28
	v_mul_f32_e32 v23, 0xbfb8aa3b, v23
	v_add_f32_e32 v36, v36, v29
	v_sqrt_f32_e32 v27, v27
	s_nop 0
	v_mul_f32_e32 v28, v26, v27
	v_mul_f32_e32 v26, 0xc1000000, v33
	v_mul_f32_e32 v26, v38, v26
	v_mul_f32_e32 v26, 0x3fb8aa3b, v26
	v_exp_f32_e32 v33, v26
	v_add_f32_e32 v26, v89, v40
	v_mul_f32_e32 v26, 0xbfb8aa3b, v26
	v_exp_f32_e32 v32, v26
	v_fma_f32 v26, -v33, v33, 1.0
	v_max_f32_e32 v26, 0, v26
	v_add_f32_e32 v32, 1.0, v32
	v_rcp_f32_e32 v32, v32
	v_mov_b32_e32 v38, v26
	v_mul_f32_e32 v36, 0xbfb8aa3b, v36
	v_exp_f32_e32 v36, v36
	v_add_f32_e32 v29, v37, v29
	v_mul_f32_e32 v29, 0xbfb8aa3b, v29
	v_exp_f32_e32 v29, v29
	v_add_f32_e32 v24, v24, v41
	v_add_f32_e32 v29, 1.0, v29
	v_mov_b32_e32 v42, v47
	v_sqrt_f32_e32 v38, v38
	s_nop 0
	v_mul_f32_e32 v38, v32, v38
	v_rcp_f32_e32 v29, v29
	v_mul_f32_e32 v24, 0xbfb8aa3b, v24
	v_mul_f32_e32 v29, 0xc1000000, v29
	v_mul_f32_e32 v29, v39, v29
	v_mul_f32_e32 v29, 0x3fb8aa3b, v29
	v_exp_f32_e32 v24, v24
	ds_read2_b32 v[46:47], v176 offset0:96 offset1:112
	v_mul_f32_e32 v32, 0xc1000000, v35
	v_mul_f32_e32 v32, v39, v32
	v_mul_f32_e32 v32, 0x3fb8aa3b, v32
	v_add_f32_e32 v24, 1.0, v24
	v_sqrt_f32_e32 v22, v34
	s_nop 0
	v_exp_f32_e32 v34, v32
	v_exp_f32_e32 v32, v23
	v_rcp_f32_e32 v24, v24
	v_add_f32_e32 v25, v25, v41
	v_fma_f32 v23, -v34, v34, 1.0
	v_max_f32_e32 v23, 0, v23
	v_mul_f32_e32 v25, 0xbfb8aa3b, v25
	v_exp_f32_e32 v25, v25
	v_mov_b32_e32 v35, v23
	v_cndmask_b32_e64 v23, v22, 1.0, vcc
	v_add_f32_e32 v22, 1.0, v32
	v_rcp_f32_e32 v48, v22
	ds_read2_b32 v[50:51], v176 offset0:32 offset1:48
	v_add_f32_e32 v25, 1.0, v25
	v_rcp_f32_e32 v25, v25
	v_add_f32_e32 v32, 1.0, v36
	v_rcp_f32_e32 v32, v32
	s_waitcnt lgkmcnt(0)
; #define LAS __attribute__((address_space(3)))
; __device__ __forceinline__ float sigmoidf_(float x) { return __builtin_amdgcn_rcpf(1.0f + __expf(-x)); }
; template <int NT> ...
;     ...
;     for (int u = 0; u < NT; ++u) { const LAS float* XC = XCb + u * (16 * 68); const int t0 = m0 + 16 * u - b * TP;
; #pragma unroll
;         for (int n = 0; n < 4; ++n) { const int cc = 16 * n + fr;
;             const float ba = CST[5 * 64 + cc], bx = CST[6 * 64 + cc], sp = CST[7 * 64 + cc];
; #pragma unroll
;             for (int j = 0; j < 4; ++j) {
;                 const float xc = XC[(4 * fq + j) * 68 + cc];
;                 const float r = sigmoidf_(ar[u][n][j] + ba), ig = sigmoidf_(ai[u][n][j] + bx);
;                 const float a = __expf(-8.0f * r * sp);
;                 float mult = sqrtf(fmaxf(1.0f - a * a, 0.f));
;                 if (t0 + 4 * fq + j == 0) mult = 1.0f;
;                 av[u][n][j] = a; bv[u][n][j] = mult * ig * xc; } } }
; #pragma unroll
;     for (int u = 0; u < NT; ++u) {
; #pragma unroll
;         for (int n = 0; n < 4; ++n) { const int ch = hc0 + 16 * n + fr;
;             float hl[4], pl[4];
;             hl[0] = bv[u][n][0]; pl[0] = av[u][n][0];
; #pragma unroll
;             for (int j = 1; j < 4; ++j) { hl[j] = av[u][n][j] * hl[j - 1] + bv[u][n][j]; pl[j] = av[u][n][j] * pl[j - 1]; }
;             float He = 0.f, Pe = 1.f;
; #pragma unroll
;             for (int g = 0; g < 3; ++g) { const float Pg = __shfl(pl[3], fr + 16 * g), Hg = __shfl(hl[3], fr + 16 * g); if (g < fq) { He = Pg * He + Hg; Pe = Pg * Pe; } }
;             const float Hin = Pe * Hc[n] + He, Pin = Pe * Pc[n];
	v_add_f32_e32 v10, v10, v50
	v_mul_f32_e32 v10, 0xbfb8aa3b, v10
	v_mul_f32_e32 v32, 0xc1000000, v32
	v_mul_f32_e32 v32, v39, v32
	v_mul_f32_e32 v32, 0x3fb8aa3b, v32
	v_sqrt_f32_e32 v22, v35
	s_nop 0
	v_exp_f32_e32 v35, v32
	v_pk_mul_f32 v[22:23], v[48:49], v[22:23]
	ds_read2_b32 v[48:49], v177 offset0:224 offset1:240
	v_pk_mul_f32 v[22:23], v[42:43], v[22:23]
	v_fma_f32 v32, -v35, v35, 1.0
	v_max_f32_e32 v32, 0, v32
	s_waitcnt lgkmcnt(0)
	v_add_f32_e32 v14, v14, v48
	v_mul_f32_e32 v14, 0xbfb8aa3b, v14
	v_exp_f32_e32 v14, v14
	v_exp_f32_e32 v10, v10
	v_mfma_f32_16x16x32_bf16 v[2:5], v[74:77], v[2:5], v[58:61]
	v_add_f32_e32 v14, 1.0, v14
	v_rcp_f32_e32 v14, v14
	v_add_f32_e32 v10, 1.0, v10
	v_exp_f32_e32 v37, v29
	v_mul_f32_e32 v14, 0xc1000000, v14
	v_mul_f32_e32 v14, v46, v14
	v_fma_f32 v29, -v37, v37, 1.0
	v_max_f32_e32 v29, 0, v29
	v_sqrt_f32_e32 v32, v32
	s_nop 0
	v_mul_f32_e32 v24, v24, v32
	v_mul_f32_e32 v14, 0x3fb8aa3b, v14
	v_exp_f32_e32 v57, v14
	v_rcp_f32_e32 v59, v10
	v_add_f32_e32 v15, v15, v48
	v_fma_f32 v14, -v57, v57, 1.0
	v_max_f32_e32 v14, 0, v14
	v_mul_f32_e32 v15, 0xbfb8aa3b, v15
	v_exp_f32_e32 v15, v15
	ds_read2_b32 v[52:53], v241 offset0:32 offset1:48
	v_sqrt_f32_e32 v29, v29
	s_nop 0
	v_mul_f32_e32 v40, v25, v29
	v_add_f32_e32 v15, 1.0, v15
	ds_read2_b32 v[60:61], v241 offset0:100 offset1:116
	v_add_f32_e32 v17, v17, v48
	v_mul_f32_e32 v17, 0xbfb8aa3b, v17
	v_exp_f32_e32 v17, v17
	s_nop 0
	v_add_f32_e32 v17, 1.0, v17
	v_rcp_f32_e32 v17, v17
	v_mfma_f32_16x16x32_bf16 v[6:9], v[74:77], v[6:9], v[62:65]
	s_nop 0
	s_nop 0
	s_nop 0
	v_rcp_f32_e32 v25, v15
	s_nop 0
	s_nop 2
	v_add_f32_e32 v6, v6, v49
	v_mul_f32_e32 v6, 0xbfb8aa3b, v6
	v_sqrt_f32_e32 v10, v14
	s_nop 0
	v_cndmask_b32_e64 v15, v10, 1.0, vcc
	v_mul_f32_e32 v10, 0xc1000000, v25
	v_mul_f32_e32 v10, v46, v10
	v_mul_f32_e32 v10, 0x3fb8aa3b, v10
	v_exp_f32_e32 v42, v10
	v_add_f32_e32 v10, v11, v50
	v_mul_f32_e32 v10, 0xbfb8aa3b, v10
	v_exp_f32_e32 v10, v10
	v_fma_f32 v11, -v42, v42, 1.0
	v_max_f32_e32 v11, 0, v11
	v_add_f32_e32 v10, 1.0, v10
	v_rcp_f32_e32 v58, v10
	v_exp_f32_e32 v6, v6
	v_add_f32_e32 v2, v2, v51
	v_mul_f32_e32 v2, 0xbfb8aa3b, v2
	v_add_f32_e32 v6, 1.0, v6
	v_rcp_f32_e32 v6, v6
	v_exp_f32_e32 v2, v2
	v_add_f32_e32 v14, v16, v48
	v_mul_f32_e32 v14, 0xbfb8aa3b, v14
	v_exp_f32_e32 v16, v14
	v_mul_f32_e32 v6, 0xc1000000, v6
	v_mul_f32_e32 v6, v47, v6
	v_sqrt_f32_e32 v14, v11
	s_nop 0
	v_pk_mul_f32 v[10:11], v[58:59], v[14:15]
	v_add_f32_e32 v14, 1.0, v16
	v_rcp_f32_e32 v16, v14
	s_waitcnt lgkmcnt(0)
	v_mov_b32_e32 v14, v60
	v_mov_b32_e32 v15, v52
	v_pk_mul_f32 v[14:15], v[14:15], v[10:11]
	v_mul_f32_e32 v10, 0xc1000000, v16
	v_mul_f32_e32 v10, v46, v10
	v_mul_f32_e32 v10, 0x3fb8aa3b, v10
	v_exp_f32_e32 v43, v10
	v_add_f32_e32 v10, v12, v50
	v_mul_f32_e32 v10, 0xbfb8aa3b, v10
	v_exp_f32_e32 v12, v10
	v_fma_f32 v10, -v43, v43, 1.0
	v_max_f32_e32 v10, 0, v10
	v_add_f32_e32 v12, 1.0, v12
	v_rcp_f32_e32 v12, v12
	v_mov_b32_e32 v16, v10
	v_mul_f32_e32 v6, 0x3fb8aa3b, v6
	v_exp_f32_e32 v48, v6
	v_add_f32_e32 v7, v7, v49
	v_fma_f32 v6, -v48, v48, 1.0
	v_max_f32_e32 v6, 0, v6
	v_mul_f32_e32 v7, 0xbfb8aa3b, v7
	v_add_f32_e32 v2, 1.0, v2
	v_exp_f32_e32 v7, v7
	v_sqrt_f32_e32 v16, v16
	s_nop 0
	v_mul_f32_e32 v16, v12, v16
	v_mul_f32_e32 v12, 0xc1000000, v17
	v_mul_f32_e32 v12, v46, v12
	v_mul_f32_e32 v12, 0x3fb8aa3b, v12
	v_exp_f32_e32 v45, v12
	v_add_f32_e32 v12, v13, v50
	v_mul_f32_e32 v12, 0xbfb8aa3b, v12
	v_exp_f32_e32 v17, v12
	v_fma_f32 v12, -v45, v45, 1.0
	v_max_f32_e32 v12, 0, v12
	v_add_f32_e32 v17, 1.0, v17
	v_rcp_f32_e32 v17, v17
	v_mov_b32_e32 v25, v12
	v_rcp_f32_e32 v59, v2
	v_add_f32_e32 v7, 1.0, v7
	v_rcp_f32_e32 v7, v7
	v_add_f32_e32 v3, v3, v51
	v_mul_f32_e32 v3, 0xbfb8aa3b, v3
	v_add_f32_e32 v8, v8, v49
	v_mul_f32_e32 v8, 0xbfb8aa3b, v8
	v_exp_f32_e32 v8, v8
	v_sqrt_f32_e32 v25, v25
	s_nop 0
	v_mul_f32_e32 v46, v17, v25
	v_add_f32_e32 v9, v9, v49
	v_mul_f32_e32 v9, 0xbfb8aa3b, v9
	v_exp_f32_e32 v9, v9
	v_add_f32_e32 v4, v4, v51
	v_add_f32_e32 v9, 1.0, v9
	v_rcp_f32_e32 v9, v9
	v_mul_f32_e32 v4, 0xbfb8aa3b, v4
	v_exp_f32_e32 v4, v4
	v_sqrt_f32_e32 v2, v6
	s_nop 0
	v_mul_f32_e32 v6, 0xc1000000, v7
	v_mul_f32_e32 v6, v47, v6
	v_mul_f32_e32 v6, 0x3fb8aa3b, v6
	v_exp_f32_e32 v60, v6
	v_exp_f32_e32 v6, v3
	v_add_f32_e32 v4, 1.0, v4
	v_rcp_f32_e32 v4, v4
	v_fma_f32 v3, -v60, v60, 1.0
	v_max_f32_e32 v3, 0, v3
	ds_read2_b32 v[18:19], v241 offset0:136 offset1:152
	v_add_f32_e32 v5, v5, v51
	v_mov_b32_e32 v7, v3
	v_cndmask_b32_e64 v3, v2, 1.0, vcc
	v_add_f32_e32 v2, 1.0, v6
	v_rcp_f32_e32 v58, v2
	ds_read2_b32 v[26:27], v241 offset0:204 offset1:220
	v_mul_f32_e32 v5, 0xbfb8aa3b, v5
	v_exp_f32_e32 v5, v5
	v_add_f32_e32 v6, 1.0, v8
	v_rcp_f32_e32 v6, v6
	v_fma_f32 v29, v30, v21, v20
	v_add_f32_e32 v5, 1.0, v5
	v_mul_f32_e32 v6, 0xc1000000, v6
	v_mul_f32_e32 v6, v47, v6
	v_mul_f32_e32 v6, 0x3fb8aa3b, v6
	v_sqrt_f32_e32 v2, v7
	s_nop 0
	v_exp_f32_e32 v7, v6
	s_waitcnt lgkmcnt(0)
	v_mov_b32_e32 v32, v26
	v_rcp_f32_e32 v5, v5
	ds_read2_b32 v[10:11], v241 offset0:168 offset1:184
	v_fma_f32 v6, -v7, v7, 1.0
	v_max_f32_e32 v6, 0, v6
	ds_read2_b32 v[12:13], v241 offset0:236 offset1:252
	v_mov_b32_e32 v36, v27
	v_or_b32_e32 v0, 0xc0, v134
	v_pk_mul_f32 v[2:3], v[58:59], v[2:3]
	v_mov_b32_e32 v52, v61
	v_pk_mul_f32 v[2:3], v[52:53], v[2:3]
	s_nop 1
	s_nop 1
	v_sqrt_f32_e32 v6, v6
	s_nop 0
	v_mul_f32_e32 v8, 0xc1000000, v9
	v_mul_f32_e32 v8, v47, v8
	v_mul_f32_e32 v8, 0x3fb8aa3b, v8
	v_exp_f32_e32 v9, v8
	v_mul_f32_e32 v4, v4, v6
	v_fma_f32 v8, -v9, v9, 1.0
	v_max_f32_e32 v8, 0, v8
	s_nop 1
	s_nop 0
	s_nop 0
	s_nop 1
	v_mul_f32_e32 v17, v30, v44
	v_mov_b32_e32 v30, v18
	v_sqrt_f32_e32 v8, v8
	s_nop 0
	v_mul_f32_e32 v6, v31, v29
	v_pk_fma_f32 v[50:51], v[30:31], v[28:29], v[6:7] op_sel_hi:[1,1,0]
	v_mul_f32_e32 v6, v31, v17
	v_mov_b32_e32 v39, v50
	v_pk_mul_f32 v[30:31], v[32:33], v[38:39]
	v_mul_f32_e32 v20, v33, v6
	v_add_f32_e32 v47, v30, v31
	ds_bpermute_b32 v25, v134, v20
	ds_bpermute_b32 v26, v134, v47
	v_mul_f32_e32 v18, v5, v8
	v_or_b32_e32 v32, s18, v229
	ds_bpermute_b32 v5, v55, v20
	ds_bpermute_b32 v8, v55, v47
	v_ashrrev_i32_e32 v33, 31, v32
	v_lshlrev_b64 v[30:31], 10, v[32:33]
	ds_bpermute_b32 v28, v54, v20
	ds_bpermute_b32 v33, v54, v47
	s_waitcnt lgkmcnt(4)
; __device__ __forceinline__ unsigned cvt_pk_bf16(float lo, float hi) { unsigned r; asm volatile("v_cvt_pk_bf16_f32 %0, %1, %2" : "=v"(r) : "v"(lo), "v"(hi)); return r; }
; template <int NT> ...
;     ...
;             hl[0] = bv[u][n][0]; pl[0] = av[u][n][0];
; #pragma unroll
;             for (int j = 1; j < 4; ++j) { hl[j] = av[u][n][j] * hl[j - 1] + bv[u][n][j]; pl[j] = av[u][n][j] * pl[j - 1]; }
;             float He = 0.f, Pe = 1.f;
; #pragma unroll
;             for (int g = 0; g < 3; ++g) { const float Pg = __shfl(pl[3], fr + 16 * g), Hg = __shfl(hl[3], fr + 16 * g); if (g < fq) { He = Pg * He + Hg; Pe = Pg * Pe; } }
;             const float Hin = Pe * Hc[n] + He, Pin = Pe * Pc[n];
;             float hf[4], pf[4];
; #pragma unroll
;             for (int j = 0; j < 4; ++j) { hf[j] = hl[j] + pl[j] * Hin; pf[j] = pl[j] * Pin; }
; #pragma unroll
;             for (int j = 0; j < 4; ++j) { const size_t o = (size_t)(m0 + 16 * u + 4 * fq + j) * D + ch; HLOC[o] = (bf16_t)(cvt_pk_bf16(hf[j], 0.f) & 0xffffu); PCUM[o] = (bf16_t)(cvt_pk_bf16(pf[j], 0.f) & 0xffffu); }
;             Hc[n] = __shfl(hf[3], fr + 48); Pc[n] = __shfl(pf[3], fr + 48);
	v_fmac_f32_e32 v26, 0, v25
	v_cndmask_b32_e64 v26, v26, 0, s[8:9]
	v_cndmask_b32_e64 v25, v25, 1.0, s[8:9]
	s_waitcnt lgkmcnt(2)
	v_fmac_f32_e32 v8, v26, v5
	v_mul_f32_e32 v5, v25, v5
	v_cndmask_b32_e64 v8, v26, v8, s[4:5]
	v_cndmask_b32_e64 v5, v25, v5, s[4:5]
	s_waitcnt lgkmcnt(0)
	v_fmac_f32_e32 v33, v8, v28
	v_mul_f32_e32 v25, v5, v28
	v_cndmask_b32_e64 v8, v8, v33, s[6:7]
	v_cndmask_b32_e64 v5, v5, v25, s[6:7]
	v_fmac_f32_e32 v8, v5, v70
	v_mul_f32_e32 v5, v5, v72
	v_fmac_f32_e32 v21, v44, v8
	v_or_b32_e32 v38, v30, v208
	v_mov_b32_e32 v39, v31
	v_mul_f32_e32 v25, v44, v5
	v_fmac_f32_e32 v29, v17, v8
	v_mul_f32_e32 v17, v17, v5
	v_fmac_f32_e32 v50, v6, v8
	v_mul_f32_e32 v6, v6, v5
	v_fmac_f32_e32 v47, v20, v8
	v_mul_f32_e32 v5, v20, v5
	v_cvt_pk_bf16_f32 v8, v21, v1
	v_lshlrev_b64 v[20:21], 1, v[38:39]
	v_lshl_add_u64 v[38:39], s[62:63], 0, v[20:21]
	v_lshl_add_u64 v[20:21], s[64:65], 0, v[20:21]
	global_store_short v[38:39], v8, off
	v_cvt_pk_bf16_f32 v8, v25, v1
	global_store_short v[20:21], v8, off
	v_or_b32_e32 v20, 1, v32
	v_ashrrev_i32_e32 v21, 31, v20
	v_lshlrev_b64 v[20:21], 10, v[20:21]
	v_or_b32_e32 v38, v20, v208
	v_mov_b32_e32 v39, v21
	v_cvt_pk_bf16_f32 v8, v29, v1
	v_lshlrev_b64 v[28:29], 1, v[38:39]
	v_lshl_add_u64 v[38:39], s[62:63], 0, v[28:29]
	v_lshl_add_u64 v[28:29], s[64:65], 0, v[28:29]
	global_store_short v[38:39], v8, off
	v_cvt_pk_bf16_f32 v8, v17, v1
	global_store_short v[28:29], v8, off
	v_or_b32_e32 v28, 2, v32
	v_ashrrev_i32_e32 v29, 31, v28
	v_lshlrev_b64 v[28:29], 10, v[28:29]
	v_or_b32_e32 v38, v28, v208
	v_mov_b32_e32 v39, v29
	v_or_b32_e32 v32, 3, v32
	v_lshlrev_b64 v[38:39], 1, v[38:39]
	v_ashrrev_i32_e32 v33, 31, v32
	v_cvt_pk_bf16_f32 v8, v50, v1
	v_lshl_add_u64 v[50:51], s[62:63], 0, v[38:39]
	v_lshl_add_u64 v[38:39], s[64:65], 0, v[38:39]
	v_lshlrev_b64 v[32:33], 10, v[32:33]
	global_store_short v[50:51], v8, off
	v_cvt_pk_bf16_f32 v6, v6, v1
	global_store_short v[38:39], v6, off
	v_or_b32_e32 v38, v32, v208
	v_mov_b32_e32 v39, v33
	v_lshlrev_b64 v[38:39], 1, v[38:39]
	v_cvt_pk_bf16_f32 v6, v47, v1
	v_lshl_add_u64 v[50:51], s[62:63], 0, v[38:39]
	v_fma_f32 v25, v34, v23, v22
	global_store_short v[50:51], v6, off
	v_mul_f32_e32 v17, v34, v56
	v_mov_b32_e32 v34, v19
	v_mul_f32_e32 v6, v35, v25
	v_pk_fma_f32 v[50:51], v[34:35], v[24:25], v[6:7] op_sel_hi:[1,1,0]
	v_mul_f32_e32 v6, v35, v17
	v_mov_b32_e32 v41, v50
	v_pk_mul_f32 v[26:27], v[36:37], v[40:41]
	v_mul_f32_e32 v22, v37, v6
	v_add_f32_e32 v19, v26, v27
	ds_bpermute_b32 v24, v134, v22
	ds_bpermute_b32 v34, v134, v19
	v_cvt_pk_bf16_f32 v8, v5, v1
	v_lshl_add_u64 v[26:27], s[64:65], 0, v[38:39]
	global_store_short v[26:27], v8, off
	ds_bpermute_b32 v72, v0, v5
	ds_bpermute_b32 v5, v55, v22
	ds_bpermute_b32 v8, v55, v19
	s_waitcnt lgkmcnt(3)
	v_fmac_f32_e32 v34, 0, v24
	v_cndmask_b32_e64 v26, v34, 0, s[8:9]
	ds_bpermute_b32 v27, v54, v22
	ds_bpermute_b32 v34, v54, v19
	v_cndmask_b32_e64 v24, v24, 1.0, s[8:9]
	s_waitcnt lgkmcnt(2)
	v_fmac_f32_e32 v8, v26, v5
	v_mul_f32_e32 v5, v24, v5
	v_cndmask_b32_e64 v8, v26, v8, s[4:5]
	v_cndmask_b32_e64 v5, v24, v5, s[4:5]
	s_waitcnt lgkmcnt(0)
	v_fmac_f32_e32 v34, v8, v27
	v_mul_f32_e32 v24, v5, v27
	v_cndmask_b32_e64 v8, v8, v34, s[6:7]
	v_cndmask_b32_e64 v5, v5, v24, s[6:7]
	v_fmac_f32_e32 v8, v5, v71
	v_mul_f32_e32 v5, v5, v73
	v_fmac_f32_e32 v23, v56, v8
	v_or_b32_e32 v26, v30, v214
	v_mov_b32_e32 v27, v31
	v_mul_f32_e32 v24, v56, v5
	v_fmac_f32_e32 v25, v17, v8
	v_mul_f32_e32 v17, v17, v5
	v_fmac_f32_e32 v50, v6, v8
	v_mul_f32_e32 v6, v6, v5
	v_fmac_f32_e32 v19, v22, v8
	v_mul_f32_e32 v5, v22, v5
	v_cvt_pk_bf16_f32 v8, v23, v1
	v_lshlrev_b64 v[22:23], 1, v[26:27]
	v_lshl_add_u64 v[26:27], s[62:63], 0, v[22:23]
	v_lshl_add_u64 v[22:23], s[64:65], 0, v[22:23]
	global_store_short v[26:27], v8, off
	v_cvt_pk_bf16_f32 v8, v24, v1
	global_store_short v[22:23], v8, off
	v_or_b32_e32 v22, v20, v214
	v_mov_b32_e32 v23, v21
	v_lshlrev_b64 v[22:23], 1, v[22:23]
	v_cvt_pk_bf16_f32 v8, v25, v1
	v_lshl_add_u64 v[24:25], s[62:63], 0, v[22:23]
	v_lshl_add_u64 v[22:23], s[64:65], 0, v[22:23]
	global_store_short v[24:25], v8, off
	v_cvt_pk_bf16_f32 v8, v17, v1
	global_store_short v[22:23], v8, off
	v_or_b32_e32 v22, v28, v214
	v_mov_b32_e32 v23, v29
	v_lshlrev_b64 v[22:23], 1, v[22:23]
	v_lshl_add_u64 v[24:25], s[62:63], 0, v[22:23]
	v_lshl_add_u64 v[22:23], s[64:65], 0, v[22:23]
	v_cvt_pk_bf16_f32 v8, v50, v1
	global_store_short v[24:25], v8, off
	v_cvt_pk_bf16_f32 v6, v6, v1
	global_store_short v[22:23], v6, off
	v_or_b32_e32 v22, v32, v214
	v_mov_b32_e32 v23, v33
	v_lshlrev_b64 v[22:23], 1, v[22:23]
	v_cvt_pk_bf16_f32 v6, v19, v1
	v_lshl_add_u64 v[24:25], s[62:63], 0, v[22:23]
	v_fma_f32 v17, v42, v15, v14
	global_store_short v[24:25], v6, off
	v_mul_f32_e32 v14, v42, v57
	v_mov_b32_e32 v42, v10
	v_mul_f32_e32 v6, v43, v17
	v_pk_fma_f32 v[24:25], v[42:43], v[16:17], v[6:7] op_sel_hi:[1,1,0]
	ds_bpermute_b32 v70, v0, v47
	v_mov_b32_e32 v44, v12
	v_mov_b32_e32 v47, v24
	v_mul_f32_e32 v6, v43, v14
	v_pk_mul_f32 v[26:27], v[44:45], v[46:47]
	v_mul_f32_e32 v10, v45, v6
	v_add_f32_e32 v12, v26, v27
	ds_bpermute_b32 v16, v134, v10
	ds_bpermute_b32 v25, v134, v12
	v_cvt_pk_bf16_f32 v8, v5, v1
	v_lshl_add_u64 v[22:23], s[64:65], 0, v[22:23]
	global_store_short v[22:23], v8, off
	ds_bpermute_b32 v73, v0, v5
	ds_bpermute_b32 v5, v55, v10
	ds_bpermute_b32 v8, v55, v12
	ds_bpermute_b32 v22, v54, v10
	ds_bpermute_b32 v23, v54, v12
	s_waitcnt lgkmcnt(5)
; __device__ __forceinline__ unsigned cvt_pk_bf16(float lo, float hi) { unsigned r; asm volatile("v_cvt_pk_bf16_f32 %0, %1, %2" : "=v"(r) : "v"(lo), "v"(hi)); return r; }
; template <int NT> ...
;     ...
;             hl[0] = bv[u][n][0]; pl[0] = av[u][n][0];
; #pragma unroll
;             for (int j = 1; j < 4; ++j) { hl[j] = av[u][n][j] * hl[j - 1] + bv[u][n][j]; pl[j] = av[u][n][j] * pl[j - 1]; }
;             float He = 0.f, Pe = 1.f;
; #pragma unroll
;             for (int g = 0; g < 3; ++g) { const float Pg = __shfl(pl[3], fr + 16 * g), Hg = __shfl(hl[3], fr + 16 * g); if (g < fq) { He = Pg * He + Hg; Pe = Pg * Pe; } }
;             const float Hin = Pe * Hc[n] + He, Pin = Pe * Pc[n];
;             float hf[4], pf[4];
; #pragma unroll
;             for (int j = 0; j < 4; ++j) { hf[j] = hl[j] + pl[j] * Hin; pf[j] = pl[j] * Pin; }
; #pragma unroll
;             for (int j = 0; j < 4; ++j) { const size_t o = (size_t)(m0 + 16 * u + 4 * fq + j) * D + ch; HLOC[o] = (bf16_t)(cvt_pk_bf16(hf[j], 0.f) & 0xffffu); PCUM[o] = (bf16_t)(cvt_pk_bf16(pf[j], 0.f) & 0xffffu); }
;             Hc[n] = __shfl(hf[3], fr + 48); Pc[n] = __shfl(pf[3], fr + 48);
	v_fmac_f32_e32 v25, 0, v16
	ds_bpermute_b32 v71, v0, v19
	v_cndmask_b32_e64 v19, v25, 0, s[8:9]
	v_cndmask_b32_e64 v16, v16, 1.0, s[8:9]
	s_waitcnt lgkmcnt(3)
	v_fmac_f32_e32 v8, v19, v5
	v_mul_f32_e32 v5, v16, v5
	v_cndmask_b32_e64 v8, v19, v8, s[4:5]
	v_cndmask_b32_e64 v5, v16, v5, s[4:5]
	s_waitcnt lgkmcnt(1)
	v_fmac_f32_e32 v23, v8, v22
	v_mul_f32_e32 v16, v5, v22
	v_cndmask_b32_e64 v8, v8, v23, s[6:7]
	v_cndmask_b32_e64 v5, v5, v16, s[6:7]
	v_fmac_f32_e32 v8, v5, v66
	v_mul_f32_e32 v5, v5, v68
	v_fmac_f32_e32 v15, v57, v8
	v_or_b32_e32 v22, v30, v212
	v_mov_b32_e32 v23, v31
	v_mul_f32_e32 v16, v57, v5
	v_fmac_f32_e32 v17, v14, v8
	v_mul_f32_e32 v19, v14, v5
	v_fmac_f32_e32 v24, v6, v8
	v_mul_f32_e32 v6, v6, v5
	v_mul_f32_e32 v25, v10, v5
	v_cvt_pk_bf16_f32 v5, v15, v1
	v_lshlrev_b64 v[14:15], 1, v[22:23]
	v_lshl_add_u64 v[22:23], s[62:63], 0, v[14:15]
	v_lshl_add_u64 v[14:15], s[64:65], 0, v[14:15]
	global_store_short v[22:23], v5, off
	v_cvt_pk_bf16_f32 v5, v16, v1
	global_store_short v[14:15], v5, off
	v_or_b32_e32 v14, v20, v212
	v_mov_b32_e32 v15, v21
	v_lshlrev_b64 v[14:15], 1, v[14:15]
	v_cvt_pk_bf16_f32 v5, v17, v1
	v_lshl_add_u64 v[16:17], s[62:63], 0, v[14:15]
	v_lshl_add_u64 v[14:15], s[64:65], 0, v[14:15]
	global_store_short v[16:17], v5, off
	v_cvt_pk_bf16_f32 v5, v19, v1
	global_store_short v[14:15], v5, off
	v_or_b32_e32 v14, v28, v212
	v_mov_b32_e32 v15, v29
	v_lshlrev_b64 v[14:15], 1, v[14:15]
	v_cvt_pk_bf16_f32 v5, v24, v1
	v_lshl_add_u64 v[16:17], s[62:63], 0, v[14:15]
	v_lshl_add_u64 v[14:15], s[64:65], 0, v[14:15]
	global_store_short v[16:17], v5, off
	v_cvt_pk_bf16_f32 v5, v6, v1
	global_store_short v[14:15], v5, off
	v_or_b32_e32 v14, v32, v212
	v_mov_b32_e32 v15, v33
	v_lshlrev_b64 v[14:15], 1, v[14:15]
	v_fmac_f32_e32 v12, v10, v8
	v_cvt_pk_bf16_f32 v5, v12, v1
	v_lshl_add_u64 v[16:17], s[62:63], 0, v[14:15]
	global_store_short v[16:17], v5, off
	v_fma_f32 v5, v60, v3, v2
	v_mov_b32_e32 v6, v11
	v_mul_f32_e32 v2, v7, v5
	v_pk_fma_f32 v[10:11], v[6:7], v[4:5], v[2:3] op_sel_hi:[1,1,0]
	v_mul_f32_e32 v17, v60, v48
	v_mov_b32_e32 v8, v13
	v_mov_b32_e32 v19, v10
	v_mul_f32_e32 v2, v7, v17
	v_pk_mul_f32 v[6:7], v[8:9], v[18:19]
	v_mul_f32_e32 v4, v9, v2
	v_add_f32_e32 v8, v6, v7
	ds_bpermute_b32 v9, v134, v4
	ds_bpermute_b32 v11, v134, v8
	v_lshl_add_u64 v[6:7], s[64:65], 0, v[14:15]
	v_cvt_pk_bf16_f32 v16, v25, v1
	global_store_short v[6:7], v16, off
	ds_bpermute_b32 v6, v55, v4
	ds_bpermute_b32 v7, v55, v8
	ds_bpermute_b32 v66, v0, v12
	ds_bpermute_b32 v12, v54, v4
	ds_bpermute_b32 v13, v54, v8
	s_waitcnt lgkmcnt(5)
	v_fmac_f32_e32 v11, 0, v9
	v_cndmask_b32_e64 v11, v11, 0, s[8:9]
	v_cndmask_b32_e64 v9, v9, 1.0, s[8:9]
	s_waitcnt lgkmcnt(3)
	v_fmac_f32_e32 v7, v11, v6
	v_mul_f32_e32 v6, v9, v6
	v_cndmask_b32_e64 v7, v11, v7, s[4:5]
	v_cndmask_b32_e64 v6, v9, v6, s[4:5]
	s_waitcnt lgkmcnt(0)
	v_fmac_f32_e32 v13, v7, v12
	v_mul_f32_e32 v9, v6, v12
	v_cndmask_b32_e64 v7, v7, v13, s[6:7]
	v_cndmask_b32_e64 v6, v6, v9, s[6:7]
	v_fmac_f32_e32 v7, v6, v67
	v_mul_f32_e32 v6, v6, v69
	v_fmac_f32_e32 v3, v48, v7
	v_or_b32_e32 v30, v30, v210
	v_fmac_f32_e32 v10, v2, v7
	v_mul_f32_e32 v12, v2, v6
	v_fmac_f32_e32 v8, v4, v7
	v_mul_f32_e32 v13, v4, v6
	v_cvt_pk_bf16_f32 v4, v3, v1
	v_lshlrev_b64 v[2:3], 1, v[30:31]
	v_mul_f32_e32 v9, v48, v6
	v_fmac_f32_e32 v5, v17, v7
	v_mul_f32_e32 v11, v17, v6
	v_lshl_add_u64 v[6:7], s[62:63], 0, v[2:3]
	v_lshl_add_u64 v[2:3], s[64:65], 0, v[2:3]
	v_or_b32_e32 v20, v20, v210
	global_store_short v[6:7], v4, off
	v_cvt_pk_bf16_f32 v4, v9, v1
	global_store_short v[2:3], v4, off
	v_lshlrev_b64 v[2:3], 1, v[20:21]
	ds_bpermute_b32 v68, v0, v25
	v_cvt_pk_bf16_f32 v6, v5, v1
	v_lshl_add_u64 v[4:5], s[62:63], 0, v[2:3]
	v_lshl_add_u64 v[2:3], s[64:65], 0, v[2:3]
	v_or_b32_e32 v28, v28, v210
	ds_bpermute_b32 v67, v0, v8
	ds_bpermute_b32 v69, v0, v13
	global_store_short v[4:5], v6, off
	v_cvt_pk_bf16_f32 v4, v11, v1
	global_store_short v[2:3], v4, off
	v_lshlrev_b64 v[2:3], 1, v[28:29]
	v_lshl_add_u64 v[4:5], s[62:63], 0, v[2:3]
	v_lshl_add_u64 v[2:3], s[64:65], 0, v[2:3]
	v_or_b32_e32 v32, v32, v210
	v_cvt_pk_bf16_f32 v6, v10, v1
	global_store_short v[4:5], v6, off
	v_cvt_pk_bf16_f32 v4, v12, v1
	global_store_short v[2:3], v4, off
	v_lshlrev_b64 v[2:3], 1, v[32:33]
	v_lshl_add_u64 v[4:5], s[62:63], 0, v[2:3]
	v_lshl_add_u64 v[2:3], s[64:65], 0, v[2:3]
	v_cvt_pk_bf16_f32 v6, v8, v1
	global_store_short v[4:5], v6, off
	v_cvt_pk_bf16_f32 v0, v13, v1
	global_store_short v[2:3], v0, off
